# GEMM tile start: first fragment reads issued right after the stage-0 barrier; first unrolled K iteration peeled with a zero C operand on its first 8 MFMAs so the 128 accumulator-zeroing moves per tile
# speedup vs baseline: 1.0351x; 1.0025x over previous
;     ...
;   const char* Abase = (const char*)(A + (size_t)m0 * lda) + (size_t)(wid * 2) * 32 * lda;
;   const char* Bbase = (const char*)(Bt + (size_t)n0 * K) + (size_t)(wid * 4) * 32 * K;
;   const size_t ablk = (size_t)32 * lda, bblk = (size_t)32 * K;
;   LAS char* lds = (LAS char*)smem;
;   LAS char* ldsA = lds + (wid * 2) * 1024;
;   LAS char* ldsB = lds + 8192 + (wid * 4) * 1024;
;     ...
;   const int x0 = ((0 + h) ^ key) * 16, x1 = ((2 + h) ^ key) * 16;
;   const int a_rd = (wr * 64 + r) * 64, b_rd = 8192 + (wc * 128 + r) * 64;
;   f32x16 acc[2][4];
; #pragma unroll
;   for (int i = 0; i < 2; ++i)
; #pragma unroll
;     for (int j = 0; j < 4; ++j)
; #pragma unroll
;       for (int e = 0; e < 16; ++e) acc[i][j][e] = 0.f;
;   const int nk = K >> 5;
;   DMA_STEP_(0, 0);
;   DMA_STEP_(1, STG);
;   asm volatile("s_waitcnt vmcnt(6)" ::: "memory");
;   __builtin_amdgcn_s_barrier();
;   asm volatile("" ::: "memory");
;   int s0 = 0, s2 = 2 * STG;
;   for (int kt = 0; kt < nk; ++kt) {
;     const int kn = (kt + 2 < nk) ? (kt + 2) : (nk - 1);
;     const LAS char* cur = lds + s0;
;     bf16x8 af[2][2], bfr[2][4];
; #pragma unroll
;     for (int kk = 0; kk < 2; ++kk) {
;       const int xo = kk ? x1 : x0;
;       af[kk][0] = *(const LAS bf16x8*)(cur + a_rd + xo);
;       bfr[kk][0] = *(const LAS bf16x8*)(cur + b_rd + xo);
;       bfr[kk][1] = *(const LAS bf16x8*)(cur + b_rd + 2048 + xo);
;       af[kk][1] = *(const LAS bf16x8*)(cur + a_rd + 2048 + xo);
;       bfr[kk][2] = *(const LAS bf16x8*)(cur + b_rd + 4096 + xo);
;       bfr[kk][3] = *(const LAS bf16x8*)(cur + b_rd + 6144 + xo);
;     }
;     DMA_STEP_(kn, s2);
; #pragma unroll
;     for (int kk = 0; kk < 2; ++kk) {
;       acc[0][0] = mfma32(bfr[kk][0], af[kk][0], acc[0][0]); acc[0][1] = mfma32(bfr[kk][1], af[kk][0], acc[0][1]);
;       acc[1][0] = mfma32(bfr[kk][0], af[kk][1], acc[1][0]); acc[1][1] = mfma32(bfr[kk][1], af[kk][1], acc[1][1]);
;       acc[0][2] = mfma32(bfr[kk][2], af[kk][0], acc[0][2]); acc[0][3] = mfma32(bfr[kk][3], af[kk][0], acc[0][3]);
;       acc[1][2] = mfma32(bfr[kk][2], af[kk][1], acc[1][2]); acc[1][3] = mfma32(bfr[kk][3], af[kk][1], acc[1][3]);
;     }
;     __builtin_amdgcn_sched_group_barrier(0x100, 12, 0);
;     __builtin_amdgcn_sched_group_barrier(0x010, 6, 0);
;     __builtin_amdgcn_sched_group_barrier(0x008, 16, 0);
;     asm volatile("s_waitcnt vmcnt(6) lgkmcnt(0)" ::: "memory");
.LBB0_20:
	s_ashr_i32 s10, s23, 31
	s_lshr_b32 s10, s10, 27
	s_add_i32 s10, s23, s10
	s_ashr_i32 s10, s10, 5
	v_readlane_b32 s11, v252, 18
	v_mov_b32_e32 v189, v188
	s_lshl_b32 s11, s10, s11
	v_readlane_b32 s12, v252, 41
	s_add_i32 s11, s11, s12
	v_readfirstlane_b32 s44, v189
	s_ashr_i32 s46, s44, 6
	s_lshl_b32 s12, s23, 7
	s_lshl_b32 s11, s11, 10
	s_and_b32 s12, s12, 0x380
	s_lshl_b32 s28, s46, 1
	s_or_b32 s12, s11, s12
	s_lshl_b32 s10, s10, 10
	s_lshl_b32 s11, s23, 5
	s_ashr_i32 s29, s28, 31
	s_sub_i32 s10, s11, s10
	s_lshl_b64 s[40:41], s[28:29], 15
	s_lshl_b32 s28, s46, 2
	s_ashr_i32 s11, s44, 1
	s_and_b32 s14, s10, 0xffffff00
	v_and_b32_e32 v0, 31, v189
	s_ashr_i32 s29, s28, 31
	s_lshl_b32 s10, s46, 12
	s_andn2_b32 s11, s11, 63
	v_lshlrev_b32_e32 v2, 4, v189
	s_ashr_i32 s13, s12, 31
	s_lshl_b64 s[42:43], s[28:29], 10
	s_add_i32 s29, s10, 16
	v_or_b32_e32 v197, s11, v0
	s_lshl_b32 s11, s46, 7
	v_bitop3_b32 v2, v2, 48, v189 bitop3:0x48
	v_lshlrev_b32_e32 v3, 9, v189
	s_ashr_i32 s15, s14, 31
	s_add_i32 s10, s29, 0x2000
	s_and_b32 s28, s11, 0x80
	s_movk_i32 s11, 0x7800
	s_lshl_b64 s[44:45], s[12:13], 11
	v_or_b32_e32 v4, s28, v0
	v_and_or_b32 v0, v3, s11, v2
	v_lshlrev_b32_e32 v10, 4, v189
	v_and_b32_e32 v10, 0x3c0, v10
	v_or_b32_e32 v10, v10, v2
	v_mov_b32_e32 v11, 0
	s_add_u32 s11, s21, s44
	s_addc_u32 s13, s22, s45
	s_add_u32 s40, s11, s40
	s_addc_u32 s41, s13, s41
	s_lshl_b64 s[44:45], s[14:15], 6
	s_add_u32 s11, s17, s44
	s_addc_u32 s13, s18, s45
	s_add_u32 s42, s11, s42
	s_addc_u32 s43, s13, s43
	s_lshl_b32 s11, s46, 11
	s_sub_i32 s13, s29, s11
	v_lshl_add_u64 v[192:193], s[40:41], 0, v[0:1]
	s_mov_b32 m0, s13
	v_lshl_add_u64 v[2:3], v[192:193], 0, s[72:73]
	global_load_lds_dwordx4 v0, s[40:41]
	s_add_i32 m0, s13, 0x400
	v_lshl_add_u64 v[194:195], s[42:43], 0, v[10:11]
	global_load_lds_dwordx4 v[2:3], off
	s_mov_b32 m0, s10
	s_nop 0
	global_load_lds_dwordx4 v[194:195], off
	global_load_lds_dwordx4 v[194:195], off offset:1024
	global_load_lds_dwordx4 v[194:195], off offset:2048
	global_load_lds_dwordx4 v[194:195], off offset:3072
	s_mov_b64 s[10:11], 0x10000
	s_mov_b64 s[10:11], 0x18000
	s_mov_b64 s[10:11], 0x8040
	s_add_i32 m0, s13, 0x6000
	v_lshl_add_u64 v[2:3], v[192:193], 0, 64
	global_load_lds_dwordx4 v[2:3], off
	v_lshl_add_u64 v[2:3], v[192:193], 0, s[10:11]
	s_add_i32 m0, s13, 0x6400
	v_bfe_u32 v196, v189, 5, 1
	global_load_lds_dwordx4 v[2:3], off
	s_add_i32 m0, s29, 0x8000
	s_mov_b32 s100, 0x10000
	v_lshl_add_u64 v[2:3], v[194:195], 0, s[100:101]
	global_load_lds_dwordx4 v[2:3], off
	global_load_lds_dwordx4 v[2:3], off offset:1024
	global_load_lds_dwordx4 v[2:3], off offset:2048
	global_load_lds_dwordx4 v[2:3], off offset:3072
	s_mov_b64 s[10:11], 0x10040
	s_mov_b64 s[10:11], 0x18040
	v_lshlrev_b32_e32 v218, 6, v4
	v_bfe_u32 v4, v189, 2, 2
	v_lshrrev_b32_e32 v5, 5, v189
	s_lshl_b32 s100, s100, 1
	v_lshl_add_u64 v[194:195], v[194:195], 0, s[100:101]
	s_waitcnt vmcnt(6)
	s_barrier
	v_bitop3_b32 v2, v196, v4, 2 bitop3:0x36
	v_bitop3_b32 v0, v5, v4, 1 bitop3:0x6c
	v_lshlrev_b32_e32 v220, 4, v2
	v_mov_b32_e32 v2, 0
	v_lshlrev_b32_e32 v219, 6, v197
	v_lshlrev_b32_e32 v0, 4, v0
	s_mov_b32 s41, 0xc000
	s_mov_b32 s40, 0
	s_mov_b32 s42, 0
	v_readfirstlane_b32 s10, v192
	v_readfirstlane_b32 s11, v193
	v_readfirstlane_b32 s100, v194
	v_readfirstlane_b32 s101, v195
	s_sub_u32 s10, s10, 0x100000
	s_subb_u32 s11, s11, 0
	s_sub_u32 s100, s100, 0x100000
	s_subb_u32 s101, s101, 0
	v_subrev_u32_e32 v238, s10, v192
	v_subrev_u32_e32 v239, s100, v194
	s_add_u32 vcc_lo, s10, s24
	s_addc_u32 vcc_hi, s11, s25
	s_add_u32 s70, s10, s38
	s_addc_u32 s71, s11, s39
	v_add3_u32 v226, v219, v0, 16
	v_add3_u32 v227, v218, v0, 16
	v_add3_u32 v228, v219, v220, 16
	v_add3_u32 v229, v218, v220, 16
	ds_read_b128 v[154:157], v226 offset:0
	ds_read_b128 v[182:185], v227 offset:8192
	ds_read_b128 v[178:181], v227 offset:10240
	ds_read_b128 v[158:161], v226 offset:2048
	ds_read_b128 v[174:177], v227 offset:12288
	ds_read_b128 v[170:173], v227 offset:14336
	s_setprio 1
	ds_read_b128 v[138:141], v228 offset:0
	ds_read_b128 v[162:165], v229 offset:8192
	ds_read_b128 v[166:169], v229 offset:10240
	ds_read_b128 v[142:145], v228 offset:2048
	ds_read_b128 v[146:149], v229 offset:12288
	ds_read_b128 v[150:153], v229 offset:14336
	s_add_i32 m0, s13, 0xc000
	s_waitcnt lgkmcnt(6)
	v_mfma_f32_32x32x16_bf16 v[114:129], v[182:185], v[154:157], 0
	global_load_lds_dwordx4 v238, vcc
	s_add_i32 m0, s13, 0xc400
	s_add_u32 vcc_lo, vcc_lo, 64
	s_addc_u32 vcc_hi, vcc_hi, 0
	v_mfma_f32_32x32x16_bf16 v[98:113], v[178:181], v[154:157], 0
	global_load_lds_dwordx4 v238, s[70:71]
	s_add_i32 m0, s29, 0xe000
	s_add_u32 s70, s70, 64
	s_addc_u32 s71, s71, 0
	v_mfma_f32_32x32x16_bf16 v[66:81], v[182:185], v[158:161], 0
	global_load_lds_dwordx4 v239, s[100:101]
	v_mfma_f32_32x32x16_bf16 v[34:49], v[178:181], v[158:161], 0
	global_load_lds_dwordx4 v239, s[100:101] offset:1024
	v_mfma_f32_32x32x16_bf16 v[82:97], v[174:177], v[154:157], 0
	global_load_lds_dwordx4 v239, s[100:101] offset:2048
	v_mfma_f32_32x32x16_bf16 v[50:65], v[170:173], v[154:157], 0
	global_load_lds_dwordx4 v239, s[100:101] offset:3072
	s_add_u32 s100, s100, 0x10000
	s_addc_u32 s101, s101, 0
	v_mfma_f32_32x32x16_bf16 v[18:33], v[174:177], v[158:161], 0
	v_mfma_f32_32x32x16_bf16 v[2:17], v[170:173], v[158:161], 0
	s_waitcnt vmcnt(6) lgkmcnt(0)
	s_barrier
; #define LAS __attribute__((address_space(3)))
; DI f32x16 mfma32(bf16x8 a, bf16x8 b, f32x16 c) { return __builtin_amdgcn_mfma_f32_32x32x16_bf16(a, b, c, 0, 0, 0); }
;     ...
;   for (int kt = 0; kt < nk; ++kt) {
;     const int kn = (kt + 2 < nk) ? (kt + 2) : (nk - 1);
;     const LAS char* cur = lds + s0;
;     bf16x8 af[2][2], bfr[2][4];
; #pragma unroll
;     for (int kk = 0; kk < 2; ++kk) {
;       const int xo = kk ? x1 : x0;
;       af[kk][0] = *(const LAS bf16x8*)(cur + a_rd + xo);
;       bfr[kk][0] = *(const LAS bf16x8*)(cur + b_rd + xo);
;       bfr[kk][1] = *(const LAS bf16x8*)(cur + b_rd + 2048 + xo);
;       af[kk][1] = *(const LAS bf16x8*)(cur + a_rd + 2048 + xo);
;       bfr[kk][2] = *(const LAS bf16x8*)(cur + b_rd + 4096 + xo);
;       bfr[kk][3] = *(const LAS bf16x8*)(cur + b_rd + 6144 + xo);
;     }
;     DMA_STEP_(kn, s2);
; #pragma unroll
;     for (int kk = 0; kk < 2; ++kk) {
;       acc[0][0] = mfma32(bfr[kk][0], af[kk][0], acc[0][0]); acc[0][1] = mfma32(bfr[kk][1], af[kk][0], acc[0][1]);
;       acc[1][0] = mfma32(bfr[kk][0], af[kk][1], acc[1][0]); acc[1][1] = mfma32(bfr[kk][1], af[kk][1], acc[1][1]);
;       acc[0][2] = mfma32(bfr[kk][2], af[kk][0], acc[0][2]); acc[0][3] = mfma32(bfr[kk][3], af[kk][0], acc[0][3]);
;       acc[1][2] = mfma32(bfr[kk][2], af[kk][1], acc[1][2]); acc[1][3] = mfma32(bfr[kk][3], af[kk][1], acc[1][3]);
;     }
;     __builtin_amdgcn_sched_group_barrier(0x100, 12, 0);
;     __builtin_amdgcn_sched_group_barrier(0x010, 6, 0);
;     __builtin_amdgcn_sched_group_barrier(0x008, 16, 0);
;     asm volatile("s_waitcnt vmcnt(6) lgkmcnt(0)" ::: "memory");
;     __builtin_amdgcn_s_barrier();
;     asm volatile("" ::: "memory");
;     s0 = (s0 == 2 * STG) ? 0 : s0 + STG;
;     s2 = (s2 == 2 * STG) ? 0 : s2 + STG;
	ds_read_b128 v[154:157], v226 offset:24576
	ds_read_b128 v[182:185], v227 offset:32768
	ds_read_b128 v[178:181], v227 offset:34816
	ds_read_b128 v[158:161], v226 offset:26624
	ds_read_b128 v[174:177], v227 offset:36864
	ds_read_b128 v[170:173], v227 offset:38912
	v_mfma_f32_32x32x16_bf16 v[114:129], v[162:165], v[138:141], v[114:129]
	v_mfma_f32_32x32x16_bf16 v[98:113], v[166:169], v[138:141], v[98:113]
	v_mfma_f32_32x32x16_bf16 v[66:81], v[162:165], v[142:145], v[66:81]
	v_mfma_f32_32x32x16_bf16 v[34:49], v[166:169], v[142:145], v[34:49]
	v_mfma_f32_32x32x16_bf16 v[82:97], v[146:149], v[138:141], v[82:97]
	v_mfma_f32_32x32x16_bf16 v[50:65], v[150:153], v[138:141], v[50:65]
	v_mfma_f32_32x32x16_bf16 v[18:33], v[146:149], v[142:145], v[18:33]
	v_mfma_f32_32x32x16_bf16 v[2:17], v[150:153], v[142:145], v[2:17]
	ds_read_b128 v[138:141], v228 offset:24576
	ds_read_b128 v[162:165], v229 offset:32768
	ds_read_b128 v[166:169], v229 offset:34816
	ds_read_b128 v[142:145], v228 offset:26624
	ds_read_b128 v[146:149], v229 offset:36864
	ds_read_b128 v[150:153], v229 offset:38912
	s_add_i32 m0, s13, 0x0
	s_waitcnt lgkmcnt(6)
	v_mfma_f32_32x32x16_bf16 v[114:129], v[182:185], v[154:157], v[114:129]
	global_load_lds_dwordx4 v238, vcc
	s_add_i32 m0, s13, 0x400
	s_add_u32 vcc_lo, vcc_lo, 64
	s_addc_u32 vcc_hi, vcc_hi, 0
	v_mfma_f32_32x32x16_bf16 v[98:113], v[178:181], v[154:157], v[98:113]
	global_load_lds_dwordx4 v238, s[70:71]
	s_add_i32 m0, s29, 0x2000
	s_add_u32 s70, s70, 64
	s_addc_u32 s71, s71, 0
	v_mfma_f32_32x32x16_bf16 v[66:81], v[182:185], v[158:161], v[66:81]
	global_load_lds_dwordx4 v239, s[100:101]
	v_mfma_f32_32x32x16_bf16 v[34:49], v[178:181], v[158:161], v[34:49]
	global_load_lds_dwordx4 v239, s[100:101] offset:1024
	v_mfma_f32_32x32x16_bf16 v[82:97], v[174:177], v[154:157], v[82:97]
	global_load_lds_dwordx4 v239, s[100:101] offset:2048
	v_mfma_f32_32x32x16_bf16 v[50:65], v[170:173], v[154:157], v[50:65]
	global_load_lds_dwordx4 v239, s[100:101] offset:3072
	s_add_u32 s100, s100, 0x10000
	s_addc_u32 s101, s101, 0
	v_mfma_f32_32x32x16_bf16 v[18:33], v[174:177], v[158:161], v[18:33]
	v_mfma_f32_32x32x16_bf16 v[2:17], v[170:173], v[158:161], v[2:17]
	s_waitcnt vmcnt(6) lgkmcnt(0)
	s_barrier
	ds_read_b128 v[154:157], v226 offset:49152
	ds_read_b128 v[182:185], v227 offset:57344
	ds_read_b128 v[178:181], v227 offset:59392
	ds_read_b128 v[158:161], v226 offset:51200
	ds_read_b128 v[174:177], v227 offset:61440
	ds_read_b128 v[170:173], v227 offset:63488
	v_mfma_f32_32x32x16_bf16 v[114:129], v[162:165], v[138:141], v[114:129]
	v_mfma_f32_32x32x16_bf16 v[98:113], v[166:169], v[138:141], v[98:113]
	v_mfma_f32_32x32x16_bf16 v[66:81], v[162:165], v[142:145], v[66:81]
	v_mfma_f32_32x32x16_bf16 v[34:49], v[166:169], v[142:145], v[34:49]
	v_mfma_f32_32x32x16_bf16 v[82:97], v[146:149], v[138:141], v[82:97]
	v_mfma_f32_32x32x16_bf16 v[50:65], v[150:153], v[138:141], v[50:65]
	v_mfma_f32_32x32x16_bf16 v[18:33], v[146:149], v[142:145], v[18:33]
	v_mfma_f32_32x32x16_bf16 v[2:17], v[150:153], v[142:145], v[2:17]
	ds_read_b128 v[138:141], v228 offset:49152
	ds_read_b128 v[162:165], v229 offset:57344
	ds_read_b128 v[166:169], v229 offset:59392
	ds_read_b128 v[142:145], v228 offset:51200
	ds_read_b128 v[146:149], v229 offset:61440
	ds_read_b128 v[150:153], v229 offset:63488
	s_add_i32 m0, s13, 0x6000
	s_waitcnt lgkmcnt(6)
	v_mfma_f32_32x32x16_bf16 v[114:129], v[182:185], v[154:157], v[114:129]
	global_load_lds_dwordx4 v238, vcc
	s_add_i32 m0, s13, 0x6400
	s_add_u32 vcc_lo, vcc_lo, 64
	s_addc_u32 vcc_hi, vcc_hi, 0
	v_mfma_f32_32x32x16_bf16 v[98:113], v[178:181], v[154:157], v[98:113]
	global_load_lds_dwordx4 v238, s[70:71]
	s_add_i32 m0, s29, 0x8000
	s_add_u32 s70, s70, 64
	s_addc_u32 s71, s71, 0
	v_mfma_f32_32x32x16_bf16 v[66:81], v[182:185], v[158:161], v[66:81]
	global_load_lds_dwordx4 v239, s[100:101]
	v_mfma_f32_32x32x16_bf16 v[34:49], v[178:181], v[158:161], v[34:49]
	global_load_lds_dwordx4 v239, s[100:101] offset:1024
	v_mfma_f32_32x32x16_bf16 v[82:97], v[174:177], v[154:157], v[82:97]
	global_load_lds_dwordx4 v239, s[100:101] offset:2048
	v_mfma_f32_32x32x16_bf16 v[50:65], v[170:173], v[154:157], v[50:65]
	global_load_lds_dwordx4 v239, s[100:101] offset:3072
	s_add_u32 s100, s100, 0x10000
	s_addc_u32 s101, s101, 0
	v_mfma_f32_32x32x16_bf16 v[18:33], v[174:177], v[158:161], v[18:33]
	v_mfma_f32_32x32x16_bf16 v[2:17], v[170:173], v[158:161], v[2:17]
	s_waitcnt vmcnt(6) lgkmcnt(0)
	s_barrier
	ds_read_b128 v[154:157], v226 offset:0
	ds_read_b128 v[182:185], v227 offset:8192
	ds_read_b128 v[178:181], v227 offset:10240
	ds_read_b128 v[158:161], v226 offset:2048
	ds_read_b128 v[174:177], v227 offset:12288
	ds_read_b128 v[170:173], v227 offset:14336
	v_mfma_f32_32x32x16_bf16 v[114:129], v[162:165], v[138:141], v[114:129]
	v_mfma_f32_32x32x16_bf16 v[98:113], v[166:169], v[138:141], v[98:113]
	v_mfma_f32_32x32x16_bf16 v[66:81], v[162:165], v[142:145], v[66:81]
	v_mfma_f32_32x32x16_bf16 v[34:49], v[166:169], v[142:145], v[34:49]
	v_mfma_f32_32x32x16_bf16 v[82:97], v[146:149], v[138:141], v[82:97]
	v_mfma_f32_32x32x16_bf16 v[50:65], v[150:153], v[138:141], v[50:65]
	v_mfma_f32_32x32x16_bf16 v[18:33], v[146:149], v[142:145], v[18:33]
	v_mfma_f32_32x32x16_bf16 v[2:17], v[150:153], v[142:145], v[2:17]
	ds_read_b128 v[138:141], v228 offset:0
	ds_read_b128 v[162:165], v229 offset:8192
	ds_read_b128 v[166:169], v229 offset:10240
	ds_read_b128 v[142:145], v228 offset:2048
	ds_read_b128 v[146:149], v229 offset:12288
	ds_read_b128 v[150:153], v229 offset:14336
	s_add_i32 m0, s13, 0xc000
	s_waitcnt lgkmcnt(6)
	v_mfma_f32_32x32x16_bf16 v[114:129], v[182:185], v[154:157], v[114:129]
	global_load_lds_dwordx4 v238, vcc
	s_add_i32 m0, s13, 0xc400
	s_add_u32 vcc_lo, vcc_lo, 64
	s_addc_u32 vcc_hi, vcc_hi, 0
	v_mfma_f32_32x32x16_bf16 v[98:113], v[178:181], v[154:157], v[98:113]
	global_load_lds_dwordx4 v238, s[70:71]
	s_add_i32 m0, s29, 0xe000
	s_add_u32 s70, s70, 64
	s_addc_u32 s71, s71, 0
	v_mfma_f32_32x32x16_bf16 v[66:81], v[182:185], v[158:161], v[66:81]
	global_load_lds_dwordx4 v239, s[100:101]
	v_mfma_f32_32x32x16_bf16 v[34:49], v[178:181], v[158:161], v[34:49]
	global_load_lds_dwordx4 v239, s[100:101] offset:1024
	v_mfma_f32_32x32x16_bf16 v[82:97], v[174:177], v[154:157], v[82:97]
	global_load_lds_dwordx4 v239, s[100:101] offset:2048
	v_mfma_f32_32x32x16_bf16 v[50:65], v[170:173], v[154:157], v[50:65]
	global_load_lds_dwordx4 v239, s[100:101] offset:3072
	s_add_u32 s100, s100, 0x10000
	s_addc_u32 s101, s101, 0
	v_mfma_f32_32x32x16_bf16 v[18:33], v[174:177], v[158:161], v[18:33]
	v_mfma_f32_32x32x16_bf16 v[2:17], v[170:173], v[158:161], v[2:17]
	s_waitcnt vmcnt(6) lgkmcnt(0)
	s_barrier
; #define LAS __attribute__((address_space(3)))
; DI f32x16 mfma32(bf16x8 a, bf16x8 b, f32x16 c) { return __builtin_amdgcn_mfma_f32_32x32x16_bf16(a, b, c, 0, 0, 0); }
;     ...
;   for (int kt = 0; kt < nk; ++kt) {
;     const int kn = (kt + 2 < nk) ? (kt + 2) : (nk - 1);
;     const LAS char* cur = lds + s0;
;     bf16x8 af[2][2], bfr[2][4];
; #pragma unroll
;     for (int kk = 0; kk < 2; ++kk) {
;       const int xo = kk ? x1 : x0;
;       af[kk][0] = *(const LAS bf16x8*)(cur + a_rd + xo);
;       bfr[kk][0] = *(const LAS bf16x8*)(cur + b_rd + xo);
;       bfr[kk][1] = *(const LAS bf16x8*)(cur + b_rd + 2048 + xo);
;       af[kk][1] = *(const LAS bf16x8*)(cur + a_rd + 2048 + xo);
;       bfr[kk][2] = *(const LAS bf16x8*)(cur + b_rd + 4096 + xo);
;       bfr[kk][3] = *(const LAS bf16x8*)(cur + b_rd + 6144 + xo);
;     }
;     DMA_STEP_(kn, s2);
; #pragma unroll
;     for (int kk = 0; kk < 2; ++kk) {
;       acc[0][0] = mfma32(bfr[kk][0], af[kk][0], acc[0][0]); acc[0][1] = mfma32(bfr[kk][1], af[kk][0], acc[0][1]);
;       acc[1][0] = mfma32(bfr[kk][0], af[kk][1], acc[1][0]); acc[1][1] = mfma32(bfr[kk][1], af[kk][1], acc[1][1]);
;       acc[0][2] = mfma32(bfr[kk][2], af[kk][0], acc[0][2]); acc[0][3] = mfma32(bfr[kk][3], af[kk][0], acc[0][3]);
;       acc[1][2] = mfma32(bfr[kk][2], af[kk][1], acc[1][2]); acc[1][3] = mfma32(bfr[kk][3], af[kk][1], acc[1][3]);
;     }
;     __builtin_amdgcn_sched_group_barrier(0x100, 12, 0);
;     __builtin_amdgcn_sched_group_barrier(0x010, 6, 0);
;     __builtin_amdgcn_sched_group_barrier(0x008, 16, 0);
;     asm volatile("s_waitcnt vmcnt(6) lgkmcnt(0)" ::: "memory");
;     __builtin_amdgcn_s_barrier();
;     asm volatile("" ::: "memory");
;     s0 = (s0 == 2 * STG) ? 0 : s0 + STG;
;     s2 = (s2 == 2 * STG) ? 0 : s2 + STG;
	ds_read_b128 v[154:157], v226 offset:24576
	ds_read_b128 v[182:185], v227 offset:32768
	ds_read_b128 v[178:181], v227 offset:34816
	ds_read_b128 v[158:161], v226 offset:26624
	ds_read_b128 v[174:177], v227 offset:36864
	ds_read_b128 v[170:173], v227 offset:38912
	v_mfma_f32_32x32x16_bf16 v[114:129], v[162:165], v[138:141], v[114:129]
	v_mfma_f32_32x32x16_bf16 v[98:113], v[166:169], v[138:141], v[98:113]
	v_mfma_f32_32x32x16_bf16 v[66:81], v[162:165], v[142:145], v[66:81]
	v_mfma_f32_32x32x16_bf16 v[34:49], v[166:169], v[142:145], v[34:49]
	v_mfma_f32_32x32x16_bf16 v[82:97], v[146:149], v[138:141], v[82:97]
	v_mfma_f32_32x32x16_bf16 v[50:65], v[150:153], v[138:141], v[50:65]
	v_mfma_f32_32x32x16_bf16 v[18:33], v[146:149], v[142:145], v[18:33]
	v_mfma_f32_32x32x16_bf16 v[2:17], v[150:153], v[142:145], v[2:17]
	ds_read_b128 v[138:141], v228 offset:24576
	ds_read_b128 v[162:165], v229 offset:32768
	ds_read_b128 v[166:169], v229 offset:34816
	ds_read_b128 v[142:145], v228 offset:26624
	ds_read_b128 v[146:149], v229 offset:36864
	ds_read_b128 v[150:153], v229 offset:38912
	s_add_i32 m0, s13, 0x0
	s_waitcnt lgkmcnt(6)
	v_mfma_f32_32x32x16_bf16 v[114:129], v[182:185], v[154:157], v[114:129]
	global_load_lds_dwordx4 v238, vcc
	s_add_i32 m0, s13, 0x400
	s_add_u32 vcc_lo, vcc_lo, 64
	s_addc_u32 vcc_hi, vcc_hi, 0
	v_mfma_f32_32x32x16_bf16 v[98:113], v[178:181], v[154:157], v[98:113]
	global_load_lds_dwordx4 v238, s[70:71]
	s_add_i32 m0, s29, 0x2000
	s_add_u32 s70, s70, 64
	s_addc_u32 s71, s71, 0
	v_mfma_f32_32x32x16_bf16 v[66:81], v[182:185], v[158:161], v[66:81]
	global_load_lds_dwordx4 v239, s[100:101]
	v_mfma_f32_32x32x16_bf16 v[34:49], v[178:181], v[158:161], v[34:49]
	global_load_lds_dwordx4 v239, s[100:101] offset:1024
	v_mfma_f32_32x32x16_bf16 v[82:97], v[174:177], v[154:157], v[82:97]
	global_load_lds_dwordx4 v239, s[100:101] offset:2048
	v_mfma_f32_32x32x16_bf16 v[50:65], v[170:173], v[154:157], v[50:65]
	global_load_lds_dwordx4 v239, s[100:101] offset:3072
	s_add_u32 s100, s100, 0x10000
	s_addc_u32 s101, s101, 0
	v_mfma_f32_32x32x16_bf16 v[18:33], v[174:177], v[158:161], v[18:33]
	v_mfma_f32_32x32x16_bf16 v[2:17], v[170:173], v[158:161], v[2:17]
	s_waitcnt vmcnt(6) lgkmcnt(0)
	s_barrier
	ds_read_b128 v[154:157], v226 offset:49152
	ds_read_b128 v[182:185], v227 offset:57344
	ds_read_b128 v[178:181], v227 offset:59392
	ds_read_b128 v[158:161], v226 offset:51200
	ds_read_b128 v[174:177], v227 offset:61440
	ds_read_b128 v[170:173], v227 offset:63488
	v_mfma_f32_32x32x16_bf16 v[114:129], v[162:165], v[138:141], v[114:129]
	v_mfma_f32_32x32x16_bf16 v[98:113], v[166:169], v[138:141], v[98:113]
	v_mfma_f32_32x32x16_bf16 v[66:81], v[162:165], v[142:145], v[66:81]
	v_mfma_f32_32x32x16_bf16 v[34:49], v[166:169], v[142:145], v[34:49]
	v_mfma_f32_32x32x16_bf16 v[82:97], v[146:149], v[138:141], v[82:97]
	v_mfma_f32_32x32x16_bf16 v[50:65], v[150:153], v[138:141], v[50:65]
	v_mfma_f32_32x32x16_bf16 v[18:33], v[146:149], v[142:145], v[18:33]
	v_mfma_f32_32x32x16_bf16 v[2:17], v[150:153], v[142:145], v[2:17]
	ds_read_b128 v[138:141], v228 offset:49152
	ds_read_b128 v[162:165], v229 offset:57344
	ds_read_b128 v[166:169], v229 offset:59392
	ds_read_b128 v[142:145], v228 offset:51200
	ds_read_b128 v[146:149], v229 offset:61440
	ds_read_b128 v[150:153], v229 offset:63488
	s_add_i32 m0, s13, 0x6000
	s_waitcnt lgkmcnt(6)
	v_mfma_f32_32x32x16_bf16 v[114:129], v[182:185], v[154:157], v[114:129]
	global_load_lds_dwordx4 v238, vcc
	s_add_i32 m0, s13, 0x6400
	s_add_u32 vcc_lo, vcc_lo, 64
	s_addc_u32 vcc_hi, vcc_hi, 0
	v_mfma_f32_32x32x16_bf16 v[98:113], v[178:181], v[154:157], v[98:113]
	global_load_lds_dwordx4 v238, s[70:71]
	s_add_i32 m0, s29, 0x8000
	s_add_u32 s70, s70, 64
	s_addc_u32 s71, s71, 0
	v_mfma_f32_32x32x16_bf16 v[66:81], v[182:185], v[158:161], v[66:81]
	global_load_lds_dwordx4 v239, s[100:101]
	v_mfma_f32_32x32x16_bf16 v[34:49], v[178:181], v[158:161], v[34:49]
	global_load_lds_dwordx4 v239, s[100:101] offset:1024
	v_mfma_f32_32x32x16_bf16 v[82:97], v[174:177], v[154:157], v[82:97]
	global_load_lds_dwordx4 v239, s[100:101] offset:2048
	v_mfma_f32_32x32x16_bf16 v[50:65], v[170:173], v[154:157], v[50:65]
	global_load_lds_dwordx4 v239, s[100:101] offset:3072
	s_add_u32 s100, s100, 0x10000
	s_addc_u32 s101, s101, 0
	v_mfma_f32_32x32x16_bf16 v[18:33], v[174:177], v[158:161], v[18:33]
	v_mfma_f32_32x32x16_bf16 v[2:17], v[170:173], v[158:161], v[2:17]
	s_waitcnt vmcnt(6) lgkmcnt(0)
	s_barrier
	ds_read_b128 v[154:157], v226 offset:0
	ds_read_b128 v[182:185], v227 offset:8192
	ds_read_b128 v[178:181], v227 offset:10240
	ds_read_b128 v[158:161], v226 offset:2048
	ds_read_b128 v[174:177], v227 offset:12288
	ds_read_b128 v[170:173], v227 offset:14336
	v_mfma_f32_32x32x16_bf16 v[114:129], v[162:165], v[138:141], v[114:129]
	v_mfma_f32_32x32x16_bf16 v[98:113], v[166:169], v[138:141], v[98:113]
	v_mfma_f32_32x32x16_bf16 v[66:81], v[162:165], v[142:145], v[66:81]
	v_mfma_f32_32x32x16_bf16 v[34:49], v[166:169], v[142:145], v[34:49]
	v_mfma_f32_32x32x16_bf16 v[82:97], v[146:149], v[138:141], v[82:97]
	v_mfma_f32_32x32x16_bf16 v[50:65], v[150:153], v[138:141], v[50:65]
	v_mfma_f32_32x32x16_bf16 v[18:33], v[146:149], v[142:145], v[18:33]
	v_mfma_f32_32x32x16_bf16 v[2:17], v[150:153], v[142:145], v[2:17]
	s_add_i32 s40, s40, 6

;     ...
;   const char* Abase = (const char*)(A + (size_t)m0 * lda) + (size_t)(wid * 2) * 32 * lda;
;   const char* Bbase = (const char*)(Bt + (size_t)n0 * K) + (size_t)(wid * 4) * 32 * K;
;   const size_t ablk = (size_t)32 * lda, bblk = (size_t)32 * K;
;   LAS char* lds = (LAS char*)smem;
;   LAS char* ldsA = lds + (wid * 2) * 1024;
;   LAS char* ldsB = lds + 8192 + (wid * 4) * 1024;
;     ...
;   const int x0 = ((0 + h) ^ key) * 16, x1 = ((2 + h) ^ key) * 16;
;   const int a_rd = (wr * 64 + r) * 64, b_rd = 8192 + (wc * 128 + r) * 64;
;   f32x16 acc[2][4];
; #pragma unroll
;   for (int i = 0; i < 2; ++i)
; #pragma unroll
;     for (int j = 0; j < 4; ++j)
; #pragma unroll
;       for (int e = 0; e < 16; ++e) acc[i][j][e] = 0.f;
;   const int nk = K >> 5;
;   DMA_STEP_(0, 0);
;   DMA_STEP_(1, STG);
;   asm volatile("s_waitcnt vmcnt(6)" ::: "memory");
;   __builtin_amdgcn_s_barrier();
;   asm volatile("" ::: "memory");
;   int s0 = 0, s2 = 2 * STG;
;   for (int kt = 0; kt < nk; ++kt) {
;     const int kn = (kt + 2 < nk) ? (kt + 2) : (nk - 1);
;     const LAS char* cur = lds + s0;
;     bf16x8 af[2][2], bfr[2][4];
; #pragma unroll
;     for (int kk = 0; kk < 2; ++kk) {
;       const int xo = kk ? x1 : x0;
;       af[kk][0] = *(const LAS bf16x8*)(cur + a_rd + xo);
;       bfr[kk][0] = *(const LAS bf16x8*)(cur + b_rd + xo);
;       bfr[kk][1] = *(const LAS bf16x8*)(cur + b_rd + 2048 + xo);
;       af[kk][1] = *(const LAS bf16x8*)(cur + a_rd + 2048 + xo);
;       bfr[kk][2] = *(const LAS bf16x8*)(cur + b_rd + 4096 + xo);
;       bfr[kk][3] = *(const LAS bf16x8*)(cur + b_rd + 6144 + xo);
;     }
;     DMA_STEP_(kn, s2);
; #pragma unroll
;     for (int kk = 0; kk < 2; ++kk) {
;       acc[0][0] = mfma32(bfr[kk][0], af[kk][0], acc[0][0]); acc[0][1] = mfma32(bfr[kk][1], af[kk][0], acc[0][1]);
;       acc[1][0] = mfma32(bfr[kk][0], af[kk][1], acc[1][0]); acc[1][1] = mfma32(bfr[kk][1], af[kk][1], acc[1][1]);
;       acc[0][2] = mfma32(bfr[kk][2], af[kk][0], acc[0][2]); acc[0][3] = mfma32(bfr[kk][3], af[kk][0], acc[0][3]);
;       acc[1][2] = mfma32(bfr[kk][2], af[kk][1], acc[1][2]); acc[1][3] = mfma32(bfr[kk][3], af[kk][1], acc[1][3]);
;     }
;     __builtin_amdgcn_sched_group_barrier(0x100, 12, 0);
;     __builtin_amdgcn_sched_group_barrier(0x010, 6, 0);
;     __builtin_amdgcn_sched_group_barrier(0x008, 16, 0);
;     asm volatile("s_waitcnt vmcnt(6) lgkmcnt(0)" ::: "memory");
.LBB0_146:
	v_readlane_b32 s10, v252, 29
	s_cmp_ge_i32 s40, s10
	s_mov_b64 s[12:13], -1
	s_cbranch_scc0 .LBB0_150
	v_readlane_b32 s10, v252, 29
	s_sub_i32 s10, s40, s10
	v_mov_b32_e32 v189, v188
	s_bfe_u32 s11, s10, 0x5001a
	s_add_i32 s11, s10, s11
	v_readfirstlane_b32 s46, v189
	s_ashr_i32 s58, s46, 6
	s_sext_i32_i16 s11, s11
	s_lshl_b32 s42, s58, 2
	s_ashr_i32 s11, s11, 5
	v_readlane_b32 s12, v252, 18
	s_ashr_i32 s43, s42, 31
	s_lshl_b32 s12, s11, s12
	v_readlane_b32 s13, v252, 41
	s_lshl_b64 s[44:45], s[42:43], 10
	s_lshl_b32 s42, s58, 12
	s_add_i32 s12, s12, s13
	s_lshl_b32 s13, s40, 7
	s_lshl_b32 s11, s11, 10
	s_lshl_b32 s10, s10, 5
	s_add_i32 s43, s42, 16
	s_ashr_i32 s42, s46, 1
	s_lshl_b32 s12, s12, 10
	s_and_b32 s13, s13, 0x380
	s_sub_i32 s10, s10, s11
	v_and_b32_e32 v0, 31, v189
	s_andn2_b32 s42, s42, 63
	s_or_b32 s41, s12, s13
	s_and_b32 s12, s10, 0xffffff00
	v_or_b32_e32 v197, s42, v0
	s_lshl_b32 s42, s58, 7
	s_lshl_b32 s10, s58, 1
	s_ashr_i32 s13, s12, 31
	s_add_i32 s59, s43, 0x2000
	s_and_b32 s42, s42, 0x80
	s_mul_i32 s47, s41, 0x1200
	s_mul_hi_i32 s46, s41, 0x1200
	s_add_u32 s47, s18, s47
	s_mul_i32 s11, s58, 0x24000
	s_addc_u32 s56, s19, s46
	s_mul_hi_i32 s10, s10, 0x12000
	s_add_u32 s46, s47, s11
	s_addc_u32 s47, s56, s10
	s_lshl_b64 s[56:57], s[12:13], 6
	s_add_u32 s10, s20, s56
	s_addc_u32 s11, s21, s57
	v_bfe_u32 v5, v189, 2, 4
	v_lshlrev_b32_e32 v2, 4, v189
	s_add_u32 s56, s10, s44
	v_bitop3_b32 v6, v2, 48, v189 bitop3:0x48
	v_or_b32_e32 v2, s42, v0
	v_mul_u32_u24_e32 v0, 0x1200, v5
	s_addc_u32 s57, s11, s45
	s_lshl_b32 s10, s58, 11
	v_or_b32_e32 v0, v0, v6
	s_sub_i32 s44, s43, s10
	v_lshl_add_u64 v[192:193], s[46:47], 0, v[0:1]
	s_mov_b32 m0, s44
	s_mov_b64 s[10:11], 0x12000
	v_lshlrev_b32_e32 v218, 6, v2
	global_load_lds_dwordx4 v0, s[46:47]
	v_lshl_add_u64 v[2:3], v[192:193], 0, s[10:11]
	s_add_i32 m0, s44, 0x400
	v_lshl_or_b32 v0, v5, 9, v6
	v_lshl_or_b32 v10, v5, 6, v6
	v_mov_b32_e32 v11, 0
	global_load_lds_dwordx4 v[2:3], off
	v_lshl_add_u64 v[194:195], s[56:57], 0, v[10:11]
	s_mov_b32 m0, s59
	s_mov_b64 s[46:47], 0x2000
	global_load_lds_dwordx4 v[194:195], off
	global_load_lds_dwordx4 v[194:195], off offset:1024
	global_load_lds_dwordx4 v[194:195], off offset:2048
	global_load_lds_dwordx4 v[194:195], off offset:3072
	s_mov_b64 s[46:47], 0x4000
	s_mov_b64 s[10:11], 0x6000
	s_mov_b64 s[10:11], 0x12040
	s_add_i32 m0, s44, 0x6000
	v_lshl_add_u64 v[2:3], v[192:193], 0, 64
	global_load_lds_dwordx4 v[2:3], off
	v_lshl_add_u64 v[2:3], v[192:193], 0, s[10:11]
	s_add_i32 m0, s44, 0x6400
	s_mov_b64 s[46:47], 0x2040
	global_load_lds_dwordx4 v[2:3], off
	s_add_i32 m0, s43, 0x8000
	s_mov_b32 s100, 0x10000
	v_lshl_add_u64 v[2:3], v[194:195], 0, s[100:101]
	global_load_lds_dwordx4 v[2:3], off
	global_load_lds_dwordx4 v[2:3], off offset:1024
	global_load_lds_dwordx4 v[2:3], off offset:2048
	global_load_lds_dwordx4 v[2:3], off offset:3072
	s_mov_b64 s[46:47], 0x4040
	s_mov_b64 s[10:11], 0x6040
	v_bfe_u32 v196, v189, 5, 1
	v_bfe_u32 v5, v189, 2, 2
	v_lshrrev_b32_e32 v4, 2, v189
	s_lshl_b32 s100, s100, 1
	v_lshl_add_u64 v[194:195], v[194:195], 0, s[100:101]
	s_waitcnt vmcnt(6)
	s_barrier
	v_bitop3_b32 v2, v196, v5, 2 bitop3:0x36
	v_bitop3_b32 v0, v196, v4, 3 bitop3:0x78
	v_lshlrev_b32_e32 v220, 4, v2
	v_mov_b32_e32 v2, 0
	v_lshlrev_b32_e32 v219, 6, v197
	v_lshlrev_b32_e32 v0, 4, v0
	s_mov_b32 s46, 0xc000
	s_mov_b32 s45, 0
	s_mov_b32 s47, 0
	v_readfirstlane_b32 s10, v192
	v_readfirstlane_b32 s11, v193
	v_readfirstlane_b32 s100, v194
	v_readfirstlane_b32 s101, v195
	s_sub_u32 s10, s10, 0x100000
	s_subb_u32 s11, s11, 0
	s_sub_u32 s100, s100, 0x100000
	s_subb_u32 s101, s101, 0
	v_subrev_u32_e32 v238, s10, v192
	v_subrev_u32_e32 v239, s100, v194
	s_add_u32 vcc_lo, s10, s24
	s_addc_u32 vcc_hi, s11, s25
	s_add_u32 s70, s10, s36
	s_addc_u32 s71, s11, s37
	v_add3_u32 v226, v219, v0, 16
	v_add3_u32 v227, v218, v0, 16
	v_add3_u32 v228, v219, v220, 16
	v_add3_u32 v229, v218, v220, 16
	ds_read_b128 v[154:157], v226 offset:0
	ds_read_b128 v[182:185], v227 offset:8192
	ds_read_b128 v[178:181], v227 offset:10240
	ds_read_b128 v[158:161], v226 offset:2048
	ds_read_b128 v[174:177], v227 offset:12288
	ds_read_b128 v[170:173], v227 offset:14336
	s_mov_b64 s[56:57], 0x2080
	s_mov_b64 s[58:59], 0x4080
	s_setprio 1
	ds_read_b128 v[138:141], v228 offset:0
	ds_read_b128 v[162:165], v229 offset:8192
	ds_read_b128 v[166:169], v229 offset:10240
	ds_read_b128 v[142:145], v228 offset:2048
	ds_read_b128 v[146:149], v229 offset:12288
	ds_read_b128 v[150:153], v229 offset:14336
	s_add_i32 m0, s44, 0xc000
	s_waitcnt lgkmcnt(6)
	v_mfma_f32_32x32x16_bf16 v[114:129], v[182:185], v[154:157], 0
	global_load_lds_dwordx4 v238, vcc
	s_add_i32 m0, s44, 0xc400
	s_add_u32 vcc_lo, vcc_lo, 64
	s_addc_u32 vcc_hi, vcc_hi, 0
	v_mfma_f32_32x32x16_bf16 v[98:113], v[178:181], v[154:157], 0
	global_load_lds_dwordx4 v238, s[70:71]
	s_add_i32 m0, s43, 0xe000
	s_add_u32 s70, s70, 64
	s_addc_u32 s71, s71, 0
	v_mfma_f32_32x32x16_bf16 v[66:81], v[182:185], v[158:161], 0
	global_load_lds_dwordx4 v239, s[100:101]
	v_mfma_f32_32x32x16_bf16 v[34:49], v[178:181], v[158:161], 0
	global_load_lds_dwordx4 v239, s[100:101] offset:1024
	v_mfma_f32_32x32x16_bf16 v[82:97], v[174:177], v[154:157], 0
	global_load_lds_dwordx4 v239, s[100:101] offset:2048
	v_mfma_f32_32x32x16_bf16 v[50:65], v[170:173], v[154:157], 0
	global_load_lds_dwordx4 v239, s[100:101] offset:3072
	s_add_u32 s100, s100, 0x10000
	s_addc_u32 s101, s101, 0
	v_mfma_f32_32x32x16_bf16 v[18:33], v[174:177], v[158:161], 0
	v_mfma_f32_32x32x16_bf16 v[2:17], v[170:173], v[158:161], 0
	s_waitcnt vmcnt(6) lgkmcnt(0)
	s_barrier
; #define LAS __attribute__((address_space(3)))
; DI f32x16 mfma32(bf16x8 a, bf16x8 b, f32x16 c) { return __builtin_amdgcn_mfma_f32_32x32x16_bf16(a, b, c, 0, 0, 0); }
;     ...
;   for (int kt = 0; kt < nk; ++kt) {
;     const int kn = (kt + 2 < nk) ? (kt + 2) : (nk - 1);
;     const LAS char* cur = lds + s0;
;     bf16x8 af[2][2], bfr[2][4];
; #pragma unroll
;     for (int kk = 0; kk < 2; ++kk) {
;       const int xo = kk ? x1 : x0;
;       af[kk][0] = *(const LAS bf16x8*)(cur + a_rd + xo);
;       bfr[kk][0] = *(const LAS bf16x8*)(cur + b_rd + xo);
;       bfr[kk][1] = *(const LAS bf16x8*)(cur + b_rd + 2048 + xo);
;       af[kk][1] = *(const LAS bf16x8*)(cur + a_rd + 2048 + xo);
;       bfr[kk][2] = *(const LAS bf16x8*)(cur + b_rd + 4096 + xo);
;       bfr[kk][3] = *(const LAS bf16x8*)(cur + b_rd + 6144 + xo);
;     }
;     DMA_STEP_(kn, s2);
; #pragma unroll
;     for (int kk = 0; kk < 2; ++kk) {
;       acc[0][0] = mfma32(bfr[kk][0], af[kk][0], acc[0][0]); acc[0][1] = mfma32(bfr[kk][1], af[kk][0], acc[0][1]);
;       acc[1][0] = mfma32(bfr[kk][0], af[kk][1], acc[1][0]); acc[1][1] = mfma32(bfr[kk][1], af[kk][1], acc[1][1]);
;       acc[0][2] = mfma32(bfr[kk][2], af[kk][0], acc[0][2]); acc[0][3] = mfma32(bfr[kk][3], af[kk][0], acc[0][3]);
;       acc[1][2] = mfma32(bfr[kk][2], af[kk][1], acc[1][2]); acc[1][3] = mfma32(bfr[kk][3], af[kk][1], acc[1][3]);
;     }
;     __builtin_amdgcn_sched_group_barrier(0x100, 12, 0);
;     __builtin_amdgcn_sched_group_barrier(0x010, 6, 0);
;     __builtin_amdgcn_sched_group_barrier(0x008, 16, 0);
;     asm volatile("s_waitcnt vmcnt(6) lgkmcnt(0)" ::: "memory");
;     __builtin_amdgcn_s_barrier();
;     asm volatile("" ::: "memory");
;     s0 = (s0 == 2 * STG) ? 0 : s0 + STG;
;     s2 = (s2 == 2 * STG) ? 0 : s2 + STG;
	ds_read_b128 v[154:157], v226 offset:24576
	ds_read_b128 v[182:185], v227 offset:32768
	ds_read_b128 v[178:181], v227 offset:34816
	ds_read_b128 v[158:161], v226 offset:26624
	ds_read_b128 v[174:177], v227 offset:36864
	ds_read_b128 v[170:173], v227 offset:38912
	v_mfma_f32_32x32x16_bf16 v[114:129], v[162:165], v[138:141], v[114:129]
	v_mfma_f32_32x32x16_bf16 v[98:113], v[166:169], v[138:141], v[98:113]
	v_mfma_f32_32x32x16_bf16 v[66:81], v[162:165], v[142:145], v[66:81]
	v_mfma_f32_32x32x16_bf16 v[34:49], v[166:169], v[142:145], v[34:49]
	v_mfma_f32_32x32x16_bf16 v[82:97], v[146:149], v[138:141], v[82:97]
	v_mfma_f32_32x32x16_bf16 v[50:65], v[150:153], v[138:141], v[50:65]
	v_mfma_f32_32x32x16_bf16 v[18:33], v[146:149], v[142:145], v[18:33]
	v_mfma_f32_32x32x16_bf16 v[2:17], v[150:153], v[142:145], v[2:17]
	ds_read_b128 v[138:141], v228 offset:24576
	ds_read_b128 v[162:165], v229 offset:32768
	ds_read_b128 v[166:169], v229 offset:34816
	ds_read_b128 v[142:145], v228 offset:26624
	ds_read_b128 v[146:149], v229 offset:36864
	ds_read_b128 v[150:153], v229 offset:38912
	s_add_i32 m0, s44, 0x0
	s_waitcnt lgkmcnt(6)
	v_mfma_f32_32x32x16_bf16 v[114:129], v[182:185], v[154:157], v[114:129]
	global_load_lds_dwordx4 v238, vcc
	s_add_i32 m0, s44, 0x400
	s_add_u32 vcc_lo, vcc_lo, 64
	s_addc_u32 vcc_hi, vcc_hi, 0
	v_mfma_f32_32x32x16_bf16 v[98:113], v[178:181], v[154:157], v[98:113]
	global_load_lds_dwordx4 v238, s[70:71]
	s_add_i32 m0, s43, 0x2000
	s_add_u32 s70, s70, 64
	s_addc_u32 s71, s71, 0
	v_mfma_f32_32x32x16_bf16 v[66:81], v[182:185], v[158:161], v[66:81]
	global_load_lds_dwordx4 v239, s[100:101]
	v_mfma_f32_32x32x16_bf16 v[34:49], v[178:181], v[158:161], v[34:49]
	global_load_lds_dwordx4 v239, s[100:101] offset:1024
	v_mfma_f32_32x32x16_bf16 v[82:97], v[174:177], v[154:157], v[82:97]
	global_load_lds_dwordx4 v239, s[100:101] offset:2048
	v_mfma_f32_32x32x16_bf16 v[50:65], v[170:173], v[154:157], v[50:65]
	global_load_lds_dwordx4 v239, s[100:101] offset:3072
	s_add_u32 s100, s100, 0x10000
	s_addc_u32 s101, s101, 0
	v_mfma_f32_32x32x16_bf16 v[18:33], v[174:177], v[158:161], v[18:33]
	v_mfma_f32_32x32x16_bf16 v[2:17], v[170:173], v[158:161], v[2:17]
	s_waitcnt vmcnt(6) lgkmcnt(0)
	s_barrier
	ds_read_b128 v[154:157], v226 offset:49152
	ds_read_b128 v[182:185], v227 offset:57344
	ds_read_b128 v[178:181], v227 offset:59392
	ds_read_b128 v[158:161], v226 offset:51200
	ds_read_b128 v[174:177], v227 offset:61440
	ds_read_b128 v[170:173], v227 offset:63488
	v_mfma_f32_32x32x16_bf16 v[114:129], v[162:165], v[138:141], v[114:129]
	v_mfma_f32_32x32x16_bf16 v[98:113], v[166:169], v[138:141], v[98:113]
	v_mfma_f32_32x32x16_bf16 v[66:81], v[162:165], v[142:145], v[66:81]
	v_mfma_f32_32x32x16_bf16 v[34:49], v[166:169], v[142:145], v[34:49]
	v_mfma_f32_32x32x16_bf16 v[82:97], v[146:149], v[138:141], v[82:97]
	v_mfma_f32_32x32x16_bf16 v[50:65], v[150:153], v[138:141], v[50:65]
	v_mfma_f32_32x32x16_bf16 v[18:33], v[146:149], v[142:145], v[18:33]
	v_mfma_f32_32x32x16_bf16 v[2:17], v[150:153], v[142:145], v[2:17]
	ds_read_b128 v[138:141], v228 offset:49152
	ds_read_b128 v[162:165], v229 offset:57344
	ds_read_b128 v[166:169], v229 offset:59392
	ds_read_b128 v[142:145], v228 offset:51200
	ds_read_b128 v[146:149], v229 offset:61440
	ds_read_b128 v[150:153], v229 offset:63488
	s_add_i32 m0, s44, 0x6000
	s_waitcnt lgkmcnt(6)
	v_mfma_f32_32x32x16_bf16 v[114:129], v[182:185], v[154:157], v[114:129]
	global_load_lds_dwordx4 v238, vcc
	s_add_i32 m0, s44, 0x6400
	s_add_u32 vcc_lo, vcc_lo, 64
	s_addc_u32 vcc_hi, vcc_hi, 0
	v_mfma_f32_32x32x16_bf16 v[98:113], v[178:181], v[154:157], v[98:113]
	global_load_lds_dwordx4 v238, s[70:71]
	s_add_i32 m0, s43, 0x8000
	s_add_u32 s70, s70, 64
	s_addc_u32 s71, s71, 0
	v_mfma_f32_32x32x16_bf16 v[66:81], v[182:185], v[158:161], v[66:81]
	global_load_lds_dwordx4 v239, s[100:101]
	v_mfma_f32_32x32x16_bf16 v[34:49], v[178:181], v[158:161], v[34:49]
	global_load_lds_dwordx4 v239, s[100:101] offset:1024
	v_mfma_f32_32x32x16_bf16 v[82:97], v[174:177], v[154:157], v[82:97]
	global_load_lds_dwordx4 v239, s[100:101] offset:2048
	v_mfma_f32_32x32x16_bf16 v[50:65], v[170:173], v[154:157], v[50:65]
	global_load_lds_dwordx4 v239, s[100:101] offset:3072
	s_add_u32 s100, s100, 0x10000
	s_addc_u32 s101, s101, 0
	v_mfma_f32_32x32x16_bf16 v[18:33], v[174:177], v[158:161], v[18:33]
	v_mfma_f32_32x32x16_bf16 v[2:17], v[170:173], v[158:161], v[2:17]
	s_waitcnt vmcnt(6) lgkmcnt(0)
	s_barrier
	ds_read_b128 v[154:157], v226 offset:0
	ds_read_b128 v[182:185], v227 offset:8192
	ds_read_b128 v[178:181], v227 offset:10240
	ds_read_b128 v[158:161], v226 offset:2048
	ds_read_b128 v[174:177], v227 offset:12288
	ds_read_b128 v[170:173], v227 offset:14336
	v_mfma_f32_32x32x16_bf16 v[114:129], v[162:165], v[138:141], v[114:129]
	v_mfma_f32_32x32x16_bf16 v[98:113], v[166:169], v[138:141], v[98:113]
	v_mfma_f32_32x32x16_bf16 v[66:81], v[162:165], v[142:145], v[66:81]
	v_mfma_f32_32x32x16_bf16 v[34:49], v[166:169], v[142:145], v[34:49]
	v_mfma_f32_32x32x16_bf16 v[82:97], v[146:149], v[138:141], v[82:97]
	v_mfma_f32_32x32x16_bf16 v[50:65], v[150:153], v[138:141], v[50:65]
	v_mfma_f32_32x32x16_bf16 v[18:33], v[146:149], v[142:145], v[18:33]
	v_mfma_f32_32x32x16_bf16 v[2:17], v[150:153], v[142:145], v[2:17]
	ds_read_b128 v[138:141], v228 offset:0
	ds_read_b128 v[162:165], v229 offset:8192
	ds_read_b128 v[166:169], v229 offset:10240
	ds_read_b128 v[142:145], v228 offset:2048
	ds_read_b128 v[146:149], v229 offset:12288
	ds_read_b128 v[150:153], v229 offset:14336
	s_add_i32 m0, s44, 0xc000
	s_waitcnt lgkmcnt(6)
	v_mfma_f32_32x32x16_bf16 v[114:129], v[182:185], v[154:157], v[114:129]
	global_load_lds_dwordx4 v238, vcc
	s_add_i32 m0, s44, 0xc400
	s_add_u32 vcc_lo, vcc_lo, 64
	s_addc_u32 vcc_hi, vcc_hi, 0
	v_mfma_f32_32x32x16_bf16 v[98:113], v[178:181], v[154:157], v[98:113]
	global_load_lds_dwordx4 v238, s[70:71]
	s_add_i32 m0, s43, 0xe000
	s_add_u32 s70, s70, 64
	s_addc_u32 s71, s71, 0
	v_mfma_f32_32x32x16_bf16 v[66:81], v[182:185], v[158:161], v[66:81]
	global_load_lds_dwordx4 v239, s[100:101]
	v_mfma_f32_32x32x16_bf16 v[34:49], v[178:181], v[158:161], v[34:49]
	global_load_lds_dwordx4 v239, s[100:101] offset:1024
	v_mfma_f32_32x32x16_bf16 v[82:97], v[174:177], v[154:157], v[82:97]
	global_load_lds_dwordx4 v239, s[100:101] offset:2048
	v_mfma_f32_32x32x16_bf16 v[50:65], v[170:173], v[154:157], v[50:65]
	global_load_lds_dwordx4 v239, s[100:101] offset:3072
	s_add_u32 s100, s100, 0x10000
	s_addc_u32 s101, s101, 0
	v_mfma_f32_32x32x16_bf16 v[18:33], v[174:177], v[158:161], v[18:33]
	v_mfma_f32_32x32x16_bf16 v[2:17], v[170:173], v[158:161], v[2:17]
	s_waitcnt vmcnt(6) lgkmcnt(0)
	s_barrier
; #define LAS __attribute__((address_space(3)))
; DI f32x16 mfma32(bf16x8 a, bf16x8 b, f32x16 c) { return __builtin_amdgcn_mfma_f32_32x32x16_bf16(a, b, c, 0, 0, 0); }
;     ...
;   for (int kt = 0; kt < nk; ++kt) {
;     const int kn = (kt + 2 < nk) ? (kt + 2) : (nk - 1);
;     const LAS char* cur = lds + s0;
;     bf16x8 af[2][2], bfr[2][4];
; #pragma unroll
;     for (int kk = 0; kk < 2; ++kk) {
;       const int xo = kk ? x1 : x0;
;       af[kk][0] = *(const LAS bf16x8*)(cur + a_rd + xo);
;       bfr[kk][0] = *(const LAS bf16x8*)(cur + b_rd + xo);
;       bfr[kk][1] = *(const LAS bf16x8*)(cur + b_rd + 2048 + xo);
;       af[kk][1] = *(const LAS bf16x8*)(cur + a_rd + 2048 + xo);
;       bfr[kk][2] = *(const LAS bf16x8*)(cur + b_rd + 4096 + xo);
;       bfr[kk][3] = *(const LAS bf16x8*)(cur + b_rd + 6144 + xo);
;     }
;     DMA_STEP_(kn, s2);
; #pragma unroll
;     for (int kk = 0; kk < 2; ++kk) {
;       acc[0][0] = mfma32(bfr[kk][0], af[kk][0], acc[0][0]); acc[0][1] = mfma32(bfr[kk][1], af[kk][0], acc[0][1]);
;       acc[1][0] = mfma32(bfr[kk][0], af[kk][1], acc[1][0]); acc[1][1] = mfma32(bfr[kk][1], af[kk][1], acc[1][1]);
;       acc[0][2] = mfma32(bfr[kk][2], af[kk][0], acc[0][2]); acc[0][3] = mfma32(bfr[kk][3], af[kk][0], acc[0][3]);
;       acc[1][2] = mfma32(bfr[kk][2], af[kk][1], acc[1][2]); acc[1][3] = mfma32(bfr[kk][3], af[kk][1], acc[1][3]);
;     }
;     __builtin_amdgcn_sched_group_barrier(0x100, 12, 0);
;     __builtin_amdgcn_sched_group_barrier(0x010, 6, 0);
;     __builtin_amdgcn_sched_group_barrier(0x008, 16, 0);
;     asm volatile("s_waitcnt vmcnt(6) lgkmcnt(0)" ::: "memory");
;     __builtin_amdgcn_s_barrier();
;     asm volatile("" ::: "memory");
;     s0 = (s0 == 2 * STG) ? 0 : s0 + STG;
;     s2 = (s2 == 2 * STG) ? 0 : s2 + STG;
	ds_read_b128 v[154:157], v226 offset:24576
	ds_read_b128 v[182:185], v227 offset:32768
	ds_read_b128 v[178:181], v227 offset:34816
	ds_read_b128 v[158:161], v226 offset:26624
	ds_read_b128 v[174:177], v227 offset:36864
	ds_read_b128 v[170:173], v227 offset:38912
	v_mfma_f32_32x32x16_bf16 v[114:129], v[162:165], v[138:141], v[114:129]
	v_mfma_f32_32x32x16_bf16 v[98:113], v[166:169], v[138:141], v[98:113]
	v_mfma_f32_32x32x16_bf16 v[66:81], v[162:165], v[142:145], v[66:81]
	v_mfma_f32_32x32x16_bf16 v[34:49], v[166:169], v[142:145], v[34:49]
	v_mfma_f32_32x32x16_bf16 v[82:97], v[146:149], v[138:141], v[82:97]
	v_mfma_f32_32x32x16_bf16 v[50:65], v[150:153], v[138:141], v[50:65]
	v_mfma_f32_32x32x16_bf16 v[18:33], v[146:149], v[142:145], v[18:33]
	v_mfma_f32_32x32x16_bf16 v[2:17], v[150:153], v[142:145], v[2:17]
	ds_read_b128 v[138:141], v228 offset:24576
	ds_read_b128 v[162:165], v229 offset:32768
	ds_read_b128 v[166:169], v229 offset:34816
	ds_read_b128 v[142:145], v228 offset:26624
	ds_read_b128 v[146:149], v229 offset:36864
	ds_read_b128 v[150:153], v229 offset:38912
	s_add_i32 m0, s44, 0x0
	s_waitcnt lgkmcnt(6)
	v_mfma_f32_32x32x16_bf16 v[114:129], v[182:185], v[154:157], v[114:129]
	global_load_lds_dwordx4 v238, vcc
	s_add_i32 m0, s44, 0x400
	s_add_u32 vcc_lo, vcc_lo, 64
	s_addc_u32 vcc_hi, vcc_hi, 0
	v_mfma_f32_32x32x16_bf16 v[98:113], v[178:181], v[154:157], v[98:113]
	global_load_lds_dwordx4 v238, s[70:71]
	s_add_i32 m0, s43, 0x2000
	s_add_u32 s70, s70, 64
	s_addc_u32 s71, s71, 0
	v_mfma_f32_32x32x16_bf16 v[66:81], v[182:185], v[158:161], v[66:81]
	global_load_lds_dwordx4 v239, s[100:101]
	v_mfma_f32_32x32x16_bf16 v[34:49], v[178:181], v[158:161], v[34:49]
	global_load_lds_dwordx4 v239, s[100:101] offset:1024
	v_mfma_f32_32x32x16_bf16 v[82:97], v[174:177], v[154:157], v[82:97]
	global_load_lds_dwordx4 v239, s[100:101] offset:2048
	v_mfma_f32_32x32x16_bf16 v[50:65], v[170:173], v[154:157], v[50:65]
	global_load_lds_dwordx4 v239, s[100:101] offset:3072
	s_add_u32 s100, s100, 0x10000
	s_addc_u32 s101, s101, 0
	v_mfma_f32_32x32x16_bf16 v[18:33], v[174:177], v[158:161], v[18:33]
	v_mfma_f32_32x32x16_bf16 v[2:17], v[170:173], v[158:161], v[2:17]
	s_waitcnt vmcnt(6) lgkmcnt(0)
	s_barrier
	ds_read_b128 v[154:157], v226 offset:49152
	ds_read_b128 v[182:185], v227 offset:57344
	ds_read_b128 v[178:181], v227 offset:59392
	ds_read_b128 v[158:161], v226 offset:51200
	ds_read_b128 v[174:177], v227 offset:61440
	ds_read_b128 v[170:173], v227 offset:63488
	v_mfma_f32_32x32x16_bf16 v[114:129], v[162:165], v[138:141], v[114:129]
	v_mfma_f32_32x32x16_bf16 v[98:113], v[166:169], v[138:141], v[98:113]
	v_mfma_f32_32x32x16_bf16 v[66:81], v[162:165], v[142:145], v[66:81]
	v_mfma_f32_32x32x16_bf16 v[34:49], v[166:169], v[142:145], v[34:49]
	v_mfma_f32_32x32x16_bf16 v[82:97], v[146:149], v[138:141], v[82:97]
	v_mfma_f32_32x32x16_bf16 v[50:65], v[150:153], v[138:141], v[50:65]
	v_mfma_f32_32x32x16_bf16 v[18:33], v[146:149], v[142:145], v[18:33]
	v_mfma_f32_32x32x16_bf16 v[2:17], v[150:153], v[142:145], v[2:17]
	ds_read_b128 v[138:141], v228 offset:49152
	ds_read_b128 v[162:165], v229 offset:57344
	ds_read_b128 v[166:169], v229 offset:59392
	ds_read_b128 v[142:145], v228 offset:51200
	ds_read_b128 v[146:149], v229 offset:61440
	ds_read_b128 v[150:153], v229 offset:63488
	s_add_i32 m0, s44, 0x6000
	s_waitcnt lgkmcnt(6)
	v_mfma_f32_32x32x16_bf16 v[114:129], v[182:185], v[154:157], v[114:129]
	global_load_lds_dwordx4 v238, vcc
	s_add_i32 m0, s44, 0x6400
	s_add_u32 vcc_lo, vcc_lo, 64
	s_addc_u32 vcc_hi, vcc_hi, 0
	v_mfma_f32_32x32x16_bf16 v[98:113], v[178:181], v[154:157], v[98:113]
	global_load_lds_dwordx4 v238, s[70:71]
	s_add_i32 m0, s43, 0x8000
	s_add_u32 s70, s70, 64
	s_addc_u32 s71, s71, 0
	v_mfma_f32_32x32x16_bf16 v[66:81], v[182:185], v[158:161], v[66:81]
	global_load_lds_dwordx4 v239, s[100:101]
	v_mfma_f32_32x32x16_bf16 v[34:49], v[178:181], v[158:161], v[34:49]
	global_load_lds_dwordx4 v239, s[100:101] offset:1024
	v_mfma_f32_32x32x16_bf16 v[82:97], v[174:177], v[154:157], v[82:97]
	global_load_lds_dwordx4 v239, s[100:101] offset:2048
	v_mfma_f32_32x32x16_bf16 v[50:65], v[170:173], v[154:157], v[50:65]
	global_load_lds_dwordx4 v239, s[100:101] offset:3072
	s_add_u32 s100, s100, 0x10000
	s_addc_u32 s101, s101, 0
	v_mfma_f32_32x32x16_bf16 v[18:33], v[174:177], v[158:161], v[18:33]
	v_mfma_f32_32x32x16_bf16 v[2:17], v[170:173], v[158:161], v[2:17]
	s_waitcnt vmcnt(6) lgkmcnt(0)
	s_barrier
	ds_read_b128 v[154:157], v226 offset:0
	ds_read_b128 v[182:185], v227 offset:8192
	ds_read_b128 v[178:181], v227 offset:10240
	ds_read_b128 v[158:161], v226 offset:2048
	ds_read_b128 v[174:177], v227 offset:12288
	ds_read_b128 v[170:173], v227 offset:14336
	v_mfma_f32_32x32x16_bf16 v[114:129], v[162:165], v[138:141], v[114:129]
	v_mfma_f32_32x32x16_bf16 v[98:113], v[166:169], v[138:141], v[98:113]
	v_mfma_f32_32x32x16_bf16 v[66:81], v[162:165], v[142:145], v[66:81]
	v_mfma_f32_32x32x16_bf16 v[34:49], v[166:169], v[142:145], v[34:49]
	v_mfma_f32_32x32x16_bf16 v[82:97], v[146:149], v[138:141], v[82:97]
	v_mfma_f32_32x32x16_bf16 v[50:65], v[150:153], v[138:141], v[50:65]
	v_mfma_f32_32x32x16_bf16 v[18:33], v[146:149], v[142:145], v[18:33]
	v_mfma_f32_32x32x16_bf16 v[2:17], v[150:153], v[142:145], v[2:17]
	s_add_i32 s45, s45, 6
; #define LAS __attribute__((address_space(3)))
; DI f32x16 mfma32(bf16x8 a, bf16x8 b, f32x16 c) { return __builtin_amdgcn_mfma_f32_32x32x16_bf16(a, b, c, 0, 0, 0); }
;     ...
;   for (int kt = 0; kt < nk; ++kt) {
;     const int kn = (kt + 2 < nk) ? (kt + 2) : (nk - 1);
;     const LAS char* cur = lds + s0;
;     bf16x8 af[2][2], bfr[2][4];
; #pragma unroll
;     for (int kk = 0; kk < 2; ++kk) {
;       const int xo = kk ? x1 : x0;
;       af[kk][0] = *(const LAS bf16x8*)(cur + a_rd + xo);
;       bfr[kk][0] = *(const LAS bf16x8*)(cur + b_rd + xo);
;       bfr[kk][1] = *(const LAS bf16x8*)(cur + b_rd + 2048 + xo);
;       af[kk][1] = *(const LAS bf16x8*)(cur + a_rd + 2048 + xo);
;       bfr[kk][2] = *(const LAS bf16x8*)(cur + b_rd + 4096 + xo);
;       bfr[kk][3] = *(const LAS bf16x8*)(cur + b_rd + 6144 + xo);
;     }
;     DMA_STEP_(kn, s2);
; #pragma unroll
;     for (int kk = 0; kk < 2; ++kk) {
;       acc[0][0] = mfma32(bfr[kk][0], af[kk][0], acc[0][0]); acc[0][1] = mfma32(bfr[kk][1], af[kk][0], acc[0][1]);
;       acc[1][0] = mfma32(bfr[kk][0], af[kk][1], acc[1][0]); acc[1][1] = mfma32(bfr[kk][1], af[kk][1], acc[1][1]);
;       acc[0][2] = mfma32(bfr[kk][2], af[kk][0], acc[0][2]); acc[0][3] = mfma32(bfr[kk][3], af[kk][0], acc[0][3]);
;       acc[1][2] = mfma32(bfr[kk][2], af[kk][1], acc[1][2]); acc[1][3] = mfma32(bfr[kk][3], af[kk][1], acc[1][3]);
;     }
;     __builtin_amdgcn_sched_group_barrier(0x100, 12, 0);
;     __builtin_amdgcn_sched_group_barrier(0x010, 6, 0);
;     __builtin_amdgcn_sched_group_barrier(0x008, 16, 0);
;     asm volatile("s_waitcnt vmcnt(6) lgkmcnt(0)" ::: "memory");
;     __builtin_amdgcn_s_barrier();
;     asm volatile("" ::: "memory");
;     s0 = (s0 == 2 * STG) ? 0 : s0 + STG;
;     s2 = (s2 == 2 * STG) ? 0 : s2 + STG;
;   }
;   asm volatile("s_waitcnt vmcnt(0)" ::: "memory");
;   __builtin_amdgcn_s_barrier();
;   asm volatile("" ::: "memory");
;     ...
;   {
;     const int h = lane >> 5, cl = lane & 31;
; #pragma unroll
;     for (int i = 0; i < 2; ++i)
; #pragma unroll
;       for (int j = 0; j < 4; ++j)
; #pragma unroll
;         for (int g = 0; g < 4; ++g) {
;           u32x2 w; w.x = pk2(acc[i][j][4 * g], acc[i][j][4 * g + 1]); w.y = pk2(acc[i][j][4 * g + 2], acc[i][j][4 * g + 3]);
;           *(u32x2*)(smem + (wr * 64 + i * 32 + cl) * 528 + (wc * 128 + j * 32 + 8 * g + 4 * h) * 2) = w;
;         }
;   }
;   __syncthreads();
.LBB0_148:
	ds_read_b128 v[138:141], v228 offset:0
	ds_read_b128 v[162:165], v229 offset:8192
	ds_read_b128 v[166:169], v229 offset:10240
	ds_read_b128 v[142:145], v228 offset:2048
	ds_read_b128 v[146:149], v229 offset:12288
	ds_read_b128 v[150:153], v229 offset:14336
	s_waitcnt lgkmcnt(6)
	v_mfma_f32_32x32x16_bf16 v[114:129], v[182:185], v[154:157], v[114:129]
	v_mfma_f32_32x32x16_bf16 v[98:113], v[178:181], v[154:157], v[98:113]
	v_mfma_f32_32x32x16_bf16 v[66:81], v[182:185], v[158:161], v[66:81]
	v_mfma_f32_32x32x16_bf16 v[34:49], v[178:181], v[158:161], v[34:49]
	v_mfma_f32_32x32x16_bf16 v[82:97], v[174:177], v[154:157], v[82:97]
	v_mfma_f32_32x32x16_bf16 v[50:65], v[170:173], v[154:157], v[50:65]
	v_mfma_f32_32x32x16_bf16 v[18:33], v[174:177], v[158:161], v[18:33]
	v_mfma_f32_32x32x16_bf16 v[2:17], v[170:173], v[158:161], v[2:17]
	s_waitcnt vmcnt(0) lgkmcnt(0)
	s_barrier
	ds_read_b128 v[154:157], v226 offset:24576
	ds_read_b128 v[182:185], v227 offset:32768
	ds_read_b128 v[178:181], v227 offset:34816
	ds_read_b128 v[158:161], v226 offset:26624
	ds_read_b128 v[174:177], v227 offset:36864
	ds_read_b128 v[170:173], v227 offset:38912
	v_mfma_f32_32x32x16_bf16 v[114:129], v[162:165], v[138:141], v[114:129]
	v_mfma_f32_32x32x16_bf16 v[98:113], v[166:169], v[138:141], v[98:113]
	v_mfma_f32_32x32x16_bf16 v[66:81], v[162:165], v[142:145], v[66:81]
	v_mfma_f32_32x32x16_bf16 v[34:49], v[166:169], v[142:145], v[34:49]
	v_mfma_f32_32x32x16_bf16 v[82:97], v[146:149], v[138:141], v[82:97]
	v_mfma_f32_32x32x16_bf16 v[50:65], v[150:153], v[138:141], v[50:65]
	v_mfma_f32_32x32x16_bf16 v[18:33], v[146:149], v[142:145], v[18:33]
	v_mfma_f32_32x32x16_bf16 v[2:17], v[150:153], v[142:145], v[2:17]
	ds_read_b128 v[138:141], v228 offset:24576
	ds_read_b128 v[162:165], v229 offset:32768
	ds_read_b128 v[166:169], v229 offset:34816
	ds_read_b128 v[142:145], v228 offset:26624
	ds_read_b128 v[146:149], v229 offset:36864
	ds_read_b128 v[150:153], v229 offset:38912
	s_waitcnt lgkmcnt(6)
	v_mfma_f32_32x32x16_bf16 v[114:129], v[182:185], v[154:157], v[114:129]
	v_mfma_f32_32x32x16_bf16 v[98:113], v[178:181], v[154:157], v[98:113]
	v_mfma_f32_32x32x16_bf16 v[66:81], v[182:185], v[158:161], v[66:81]
	v_mfma_f32_32x32x16_bf16 v[34:49], v[178:181], v[158:161], v[34:49]
	v_mfma_f32_32x32x16_bf16 v[82:97], v[174:177], v[154:157], v[82:97]
	v_mfma_f32_32x32x16_bf16 v[50:65], v[170:173], v[154:157], v[50:65]
	v_mfma_f32_32x32x16_bf16 v[18:33], v[174:177], v[158:161], v[18:33]
	v_mfma_f32_32x32x16_bf16 v[2:17], v[170:173], v[158:161], v[2:17]
	s_waitcnt lgkmcnt(0)
	v_mfma_f32_32x32x16_bf16 v[114:129], v[162:165], v[138:141], v[114:129]
	v_mfma_f32_32x32x16_bf16 v[98:113], v[166:169], v[138:141], v[98:113]
	v_mfma_f32_32x32x16_bf16 v[66:81], v[162:165], v[142:145], v[66:81]
	v_mfma_f32_32x32x16_bf16 v[34:49], v[166:169], v[142:145], v[34:49]
	v_mfma_f32_32x32x16_bf16 v[82:97], v[146:149], v[138:141], v[82:97]
	v_mfma_f32_32x32x16_bf16 v[50:65], v[150:153], v[138:141], v[50:65]
	v_mfma_f32_32x32x16_bf16 v[18:33], v[146:149], v[142:145], v[18:33]
	v_mfma_f32_32x32x16_bf16 v[2:17], v[150:153], v[142:145], v[2:17]
	s_waitcnt lgkmcnt(0)
	s_mov_b32 s101, 0
	s_mov_b32 s71, 0
	s_setprio 0
	v_mul_lo_u32 v0, v197, s55
	v_add_u32_e32 v0, 16, v0
	s_nop 1
	v_cvt_pk_bf16_f32 v114, v114, v115
	v_cvt_pk_bf16_f32 v115, v116, v117
	v_lshlrev_b32_e32 v116, 3, v196
	s_lshl_b32 s10, s42, 1
	v_add3_u32 v0, v0, v116, s10
	v_cvt_pk_bf16_f32 v116, v118, v119
	v_cvt_pk_bf16_f32 v117, v120, v121
	v_cvt_pk_bf16_f32 v98, v98, v99
	v_cvt_pk_bf16_f32 v99, v100, v101
	v_cvt_pk_bf16_f32 v100, v102, v103
	v_cvt_pk_bf16_f32 v101, v104, v105
	v_cvt_pk_bf16_f32 v82, v82, v83
	v_cvt_pk_bf16_f32 v83, v84, v85
	v_cvt_pk_bf16_f32 v84, v86, v87
	v_cvt_pk_bf16_f32 v85, v88, v89
	v_cvt_pk_bf16_f32 v50, v50, v51
	v_cvt_pk_bf16_f32 v51, v52, v53
	v_cvt_pk_bf16_f32 v52, v54, v55
	v_cvt_pk_bf16_f32 v53, v56, v57
	s_waitcnt vmcnt(0)
	s_barrier
	ds_write2_b64 v0, v[114:115], v[116:117] offset1:2
	v_cvt_pk_bf16_f32 v114, v122, v123
	v_cvt_pk_bf16_f32 v115, v124, v125
	v_cvt_pk_bf16_f32 v116, v126, v127
	v_cvt_pk_bf16_f32 v117, v128, v129
	ds_write2_b64 v0, v[98:99], v[100:101] offset0:8 offset1:10
	v_cvt_pk_bf16_f32 v98, v106, v107
	v_cvt_pk_bf16_f32 v99, v108, v109
	v_cvt_pk_bf16_f32 v100, v110, v111
	v_cvt_pk_bf16_f32 v101, v112, v113
	ds_write2_b64 v0, v[82:83], v[84:85] offset0:16 offset1:18
	v_cvt_pk_bf16_f32 v82, v90, v91
	v_cvt_pk_bf16_f32 v83, v92, v93
	v_cvt_pk_bf16_f32 v84, v94, v95
	v_cvt_pk_bf16_f32 v85, v96, v97
	ds_write2_b64 v0, v[50:51], v[52:53] offset0:24 offset1:26
	v_cvt_pk_bf16_f32 v50, v58, v59
	v_cvt_pk_bf16_f32 v51, v60, v61
	v_cvt_pk_bf16_f32 v52, v62, v63
	v_cvt_pk_bf16_f32 v53, v64, v65
	ds_write2_b64 v0, v[114:115], v[116:117] offset0:4 offset1:6
	ds_write2_b64 v0, v[98:99], v[100:101] offset0:12 offset1:14
	ds_write2_b64 v0, v[82:83], v[84:85] offset0:20 offset1:22
	ds_write2_b64 v0, v[50:51], v[52:53] offset0:28 offset1:30
	v_cvt_pk_bf16_f32 v50, v66, v67
	v_cvt_pk_bf16_f32 v51, v68, v69
	v_cvt_pk_bf16_f32 v52, v70, v71
	v_cvt_pk_bf16_f32 v53, v72, v73
	v_add_u32_e32 v0, 0x4000, v0
	v_cvt_pk_bf16_f32 v34, v34, v35
	v_cvt_pk_bf16_f32 v35, v36, v37
	v_cvt_pk_bf16_f32 v36, v38, v39
	v_cvt_pk_bf16_f32 v37, v40, v41
	v_cvt_pk_bf16_f32 v18, v18, v19
	v_cvt_pk_bf16_f32 v19, v20, v21
	v_cvt_pk_bf16_f32 v20, v22, v23
	v_cvt_pk_bf16_f32 v21, v24, v25
	v_cvt_pk_bf16_f32 v2, v2, v3
	v_cvt_pk_bf16_f32 v3, v4, v5
	v_cvt_pk_bf16_f32 v4, v6, v7
	v_cvt_pk_bf16_f32 v5, v8, v9
	ds_write2_b64 v0, v[50:51], v[52:53] offset0:64 offset1:66
	v_cvt_pk_bf16_f32 v50, v74, v75
	v_cvt_pk_bf16_f32 v51, v76, v77
	v_cvt_pk_bf16_f32 v52, v78, v79
	v_cvt_pk_bf16_f32 v53, v80, v81
	ds_write2_b64 v0, v[34:35], v[36:37] offset0:72 offset1:74
	v_cvt_pk_bf16_f32 v34, v42, v43
	v_cvt_pk_bf16_f32 v35, v44, v45
	v_cvt_pk_bf16_f32 v36, v46, v47
	v_cvt_pk_bf16_f32 v37, v48, v49
	ds_write2_b64 v0, v[18:19], v[20:21] offset0:80 offset1:82
	v_cvt_pk_bf16_f32 v18, v26, v27
	v_cvt_pk_bf16_f32 v19, v28, v29
	v_cvt_pk_bf16_f32 v20, v30, v31
	v_cvt_pk_bf16_f32 v21, v32, v33
	ds_write2_b64 v0, v[2:3], v[4:5] offset0:88 offset1:90
	v_cvt_pk_bf16_f32 v2, v10, v11
	v_cvt_pk_bf16_f32 v3, v12, v13
	v_cvt_pk_bf16_f32 v4, v14, v15
	v_cvt_pk_bf16_f32 v5, v16, v17
	s_lshl_b64 s[12:13], s[12:13], 1
	ds_write2_b64 v0, v[50:51], v[52:53] offset0:68 offset1:70
	ds_write2_b64 v0, v[34:35], v[36:37] offset0:76 offset1:78
	ds_write2_b64 v0, v[18:19], v[20:21] offset0:84 offset1:86
	ds_write2_b64 v0, v[2:3], v[4:5] offset0:92 offset1:94
	s_waitcnt vmcnt(0) lgkmcnt(0)
	s_barrier
; #define GAS __attribute__((address_space(1)))
;     ...
;   int tid2 = tid; asm volatile("" : "+v"(tid2));
;   if (EPI == 0) {
; #pragma unroll
;     for (int i = 0; i < 16; ++i) {
;       const int id = tid2 + 256 * i, r = id >> 5, c8 = (id & 31) * 8;
;       const u32x4 v = *(const u32x4*)(smem + r * 528 + c8 * 2);
;       *(GAS u32x4*)(ea.out + (size_t)(m0 + r) * ea.ldo + n0 + c8) = v;
;     }
	s_add_u32 s12, s16, s12
	v_lshlrev_b32_e32 v0, 4, v189
	v_and_b32_e32 v0, 0x1f0, v0
	s_addc_u32 s13, s17, s13
	v_add_u32_e32 v10, 16, v0
	v_lshl_add_u64 v[12:13], s[12:13], 0, v[0:1]
	v_ashrrev_i32_e32 v0, 5, v189
	v_mad_u64_u32 v[2:3], s[12:13], v0, s55, v[10:11]
	ds_read_b128 v[2:5], v2
	v_add_u32_e32 v6, s41, v0
	v_ashrrev_i32_e32 v7, 31, v6
	v_add_u32_e32 v0, 0x100, v189
	v_lshlrev_b64 v[6:7], 11, v[6:7]
	v_ashrrev_i32_e32 v0, 5, v0
	v_lshl_add_u64 v[14:15], v[12:13], 0, v[6:7]
	v_mad_u64_u32 v[6:7], s[12:13], v0, s55, v[10:11]
	ds_read_b128 v[6:9], v6
	s_waitcnt lgkmcnt(1)
	global_store_dwordx4 v[14:15], v[2:5], off
	v_readlane_b32 s44, v250, 17
	s_nop 0
	v_add_u32_e32 v2, s41, v0
	v_ashrrev_i32_e32 v3, 31, v2
	v_lshlrev_b64 v[2:3], 11, v[2:3]
	v_add_u32_e32 v0, 0x200, v189
	v_lshl_add_u64 v[2:3], v[12:13], 0, v[2:3]
	v_ashrrev_i32_e32 v0, 5, v0
	s_waitcnt lgkmcnt(0)
	global_store_dwordx4 v[2:3], v[6:9], off
	v_mad_u64_u32 v[2:3], s[12:13], v0, s55, v[10:11]
	ds_read_b128 v[2:5], v2
	v_add_u32_e32 v6, s41, v0
	v_ashrrev_i32_e32 v7, 31, v6
	v_add_u32_e32 v0, 0x300, v189
	v_lshlrev_b64 v[6:7], 11, v[6:7]
	v_ashrrev_i32_e32 v0, 5, v0
	v_lshl_add_u64 v[14:15], v[12:13], 0, v[6:7]
	v_mad_u64_u32 v[6:7], s[12:13], v0, s55, v[10:11]
	ds_read_b128 v[6:9], v6
	s_waitcnt lgkmcnt(1)
	global_store_dwordx4 v[14:15], v[2:5], off
	s_nop 1
	v_add_u32_e32 v2, s41, v0
	v_ashrrev_i32_e32 v3, 31, v2
	v_lshlrev_b64 v[2:3], 11, v[2:3]
	v_add_u32_e32 v0, 0x400, v189
	v_lshl_add_u64 v[2:3], v[12:13], 0, v[2:3]
	v_ashrrev_i32_e32 v0, 5, v0
	s_waitcnt lgkmcnt(0)
	global_store_dwordx4 v[2:3], v[6:9], off
	v_mad_u64_u32 v[2:3], s[12:13], v0, s55, v[10:11]
	ds_read_b128 v[2:5], v2
	v_add_u32_e32 v6, s41, v0
	v_ashrrev_i32_e32 v7, 31, v6
	v_add_u32_e32 v0, 0x500, v189
	v_lshlrev_b64 v[6:7], 11, v[6:7]
	v_ashrrev_i32_e32 v0, 5, v0
	v_lshl_add_u64 v[14:15], v[12:13], 0, v[6:7]
	v_mad_u64_u32 v[6:7], s[12:13], v0, s55, v[10:11]
	ds_read_b128 v[6:9], v6
	s_waitcnt lgkmcnt(1)
	global_store_dwordx4 v[14:15], v[2:5], off
	s_nop 1
	v_add_u32_e32 v2, s41, v0
	v_ashrrev_i32_e32 v3, 31, v2
	v_lshlrev_b64 v[2:3], 11, v[2:3]
	v_add_u32_e32 v0, 0x600, v189
	v_lshl_add_u64 v[2:3], v[12:13], 0, v[2:3]
	v_ashrrev_i32_e32 v0, 5, v0
	s_waitcnt lgkmcnt(0)
	global_store_dwordx4 v[2:3], v[6:9], off
	v_mad_u64_u32 v[2:3], s[12:13], v0, s55, v[10:11]
	ds_read_b128 v[2:5], v2
	v_add_u32_e32 v6, s41, v0
	v_ashrrev_i32_e32 v7, 31, v6
	v_add_u32_e32 v0, 0x700, v189
	v_lshlrev_b64 v[6:7], 11, v[6:7]
	v_ashrrev_i32_e32 v0, 5, v0
	v_lshl_add_u64 v[14:15], v[12:13], 0, v[6:7]
	v_mad_u64_u32 v[6:7], s[12:13], v0, s55, v[10:11]
	ds_read_b128 v[6:9], v6
	s_waitcnt lgkmcnt(1)
	global_store_dwordx4 v[14:15], v[2:5], off
	s_nop 1
	v_add_u32_e32 v2, s41, v0
	v_ashrrev_i32_e32 v3, 31, v2
	v_lshlrev_b64 v[2:3], 11, v[2:3]
	v_add_u32_e32 v0, 0x800, v189
	v_lshl_add_u64 v[2:3], v[12:13], 0, v[2:3]
	v_ashrrev_i32_e32 v0, 5, v0
	s_waitcnt lgkmcnt(0)
	global_store_dwordx4 v[2:3], v[6:9], off
	v_mad_u64_u32 v[2:3], s[12:13], v0, s55, v[10:11]
	ds_read_b128 v[2:5], v2
	v_add_u32_e32 v6, s41, v0
	v_ashrrev_i32_e32 v7, 31, v6
	v_add_u32_e32 v0, 0x900, v189
	v_lshlrev_b64 v[6:7], 11, v[6:7]
	v_ashrrev_i32_e32 v0, 5, v0
	v_lshl_add_u64 v[14:15], v[12:13], 0, v[6:7]
	v_mad_u64_u32 v[6:7], s[12:13], v0, s55, v[10:11]
	ds_read_b128 v[6:9], v6
	s_waitcnt lgkmcnt(1)
	global_store_dwordx4 v[14:15], v[2:5], off
	s_nop 1
	v_add_u32_e32 v2, s41, v0
	v_ashrrev_i32_e32 v3, 31, v2
	v_lshlrev_b64 v[2:3], 11, v[2:3]
	v_add_u32_e32 v0, 0xa00, v189
	v_lshl_add_u64 v[2:3], v[12:13], 0, v[2:3]
	v_ashrrev_i32_e32 v0, 5, v0
	s_waitcnt lgkmcnt(0)
	global_store_dwordx4 v[2:3], v[6:9], off
	v_mad_u64_u32 v[2:3], s[12:13], v0, s55, v[10:11]
	ds_read_b128 v[2:5], v2
	v_add_u32_e32 v6, s41, v0
	v_ashrrev_i32_e32 v7, 31, v6
	v_add_u32_e32 v0, 0xb00, v189
	v_lshlrev_b64 v[6:7], 11, v[6:7]
	v_ashrrev_i32_e32 v0, 5, v0
	v_lshl_add_u64 v[14:15], v[12:13], 0, v[6:7]
	v_mad_u64_u32 v[6:7], s[12:13], v0, s55, v[10:11]
	ds_read_b128 v[6:9], v6
	s_waitcnt lgkmcnt(1)
	global_store_dwordx4 v[14:15], v[2:5], off
	s_nop 1
	v_add_u32_e32 v2, s41, v0
	v_ashrrev_i32_e32 v3, 31, v2
	v_lshlrev_b64 v[2:3], 11, v[2:3]
	v_add_u32_e32 v0, 0xc00, v189
	v_lshl_add_u64 v[2:3], v[12:13], 0, v[2:3]
	v_ashrrev_i32_e32 v0, 5, v0
	s_waitcnt lgkmcnt(0)
	global_store_dwordx4 v[2:3], v[6:9], off
	v_mad_u64_u32 v[2:3], s[12:13], v0, s55, v[10:11]
	ds_read_b128 v[2:5], v2
	v_add_u32_e32 v6, s41, v0
	v_ashrrev_i32_e32 v7, 31, v6
	v_add_u32_e32 v0, 0xd00, v189
	v_lshlrev_b64 v[6:7], 11, v[6:7]
	v_ashrrev_i32_e32 v0, 5, v0
	v_lshl_add_u64 v[14:15], v[12:13], 0, v[6:7]
	v_mad_u64_u32 v[6:7], s[12:13], v0, s55, v[10:11]
	ds_read_b128 v[6:9], v6
	s_waitcnt lgkmcnt(1)
	global_store_dwordx4 v[14:15], v[2:5], off
	s_nop 1
	v_add_u32_e32 v2, s41, v0
	v_ashrrev_i32_e32 v3, 31, v2
	v_lshlrev_b64 v[2:3], 11, v[2:3]
	v_add_u32_e32 v0, 0xe00, v189
	v_lshl_add_u64 v[2:3], v[12:13], 0, v[2:3]
	v_ashrrev_i32_e32 v0, 5, v0
	s_waitcnt lgkmcnt(0)
	global_store_dwordx4 v[2:3], v[6:9], off
	v_mad_u64_u32 v[2:3], s[12:13], v0, s55, v[10:11]
	ds_read_b128 v[2:5], v2
	v_add_u32_e32 v6, s41, v0
	v_ashrrev_i32_e32 v7, 31, v6
	v_add_u32_e32 v0, 0xf00, v189
	v_lshlrev_b64 v[6:7], 11, v[6:7]
	v_ashrrev_i32_e32 v0, 5, v0
	v_lshl_add_u64 v[14:15], v[12:13], 0, v[6:7]
	v_mad_u64_u32 v[6:7], s[12:13], v0, s55, v[10:11]
	ds_read_b128 v[6:9], v6
	s_waitcnt lgkmcnt(1)
	global_store_dwordx4 v[14:15], v[2:5], off
	s_mov_b64 s[12:13], 0
	s_nop 0
	v_add_u32_e32 v2, s41, v0
	v_ashrrev_i32_e32 v3, 31, v2
	v_lshlrev_b64 v[2:3], 11, v[2:3]
	v_lshl_add_u64 v[2:3], v[12:13], 0, v[2:3]
	s_waitcnt lgkmcnt(0)
	global_store_dwordx4 v[2:3], v[6:9], off
	s_barrier
;   int tid = tid_in; asm volatile("" : "+v"(tid));
;   const int lane = tid & 63, wid = __builtin_amdgcn_readfirstlane(tid >> 6), wr = wid >> 1, wc = wid & 1;
;   const int m0 = mt * 128, n0 = nt * 256;
;   const int r = lane & 31, h = lane >> 5, key = (r >> 2) & 3;
;   constexpr int STG = 24576;
;   const int rowl = lane >> 2, cch = (lane & 3) ^ ((lane >> 4) & 3);
;   const unsigned voffA = (unsigned)(rowl * lda * 2 + cch * 16), voffB = (unsigned)(rowl * K * 2 + cch * 16);
;   const char* Abase = (const char*)(A + (size_t)m0 * lda) + (size_t)(wid * 2) * 32 * lda;
;   const char* Bbase = (const char*)(Bt + (size_t)n0 * K) + (size_t)(wid * 4) * 32 * K;
;   const size_t ablk = (size_t)32 * lda, bblk = (size_t)32 * K;
;   LAS char* lds = (LAS char*)smem;
;   LAS char* ldsA = lds + (wid * 2) * 1024;
;   LAS char* ldsB = lds + 8192 + (wid * 4) * 1024;
;     ...
;   const int x0 = ((0 + h) ^ key) * 16, x1 = ((2 + h) ^ key) * 16;
;   const int a_rd = (wr * 64 + r) * 64, b_rd = 8192 + (wc * 128 + r) * 64;
;   f32x16 acc[2][4];
; #pragma unroll
;   for (int i = 0; i < 2; ++i)
; #pragma unroll
;     for (int j = 0; j < 4; ++j)
; #pragma unroll
;       for (int e = 0; e < 16; ++e) acc[i][j][e] = 0.f;
;   const int nk = K >> 5;
;   DMA_STEP_(0, 0);
;   DMA_STEP_(1, STG);
;   asm volatile("s_waitcnt vmcnt(6)" ::: "memory");
;   __builtin_amdgcn_s_barrier();
;   asm volatile("" ::: "memory");
;   int s0 = 0, s2 = 2 * STG;
;   for (int kt = 0; kt < nk; ++kt) {
;     const int kn = (kt + 2 < nk) ? (kt + 2) : (nk - 1);
;     const LAS char* cur = lds + s0;
;     bf16x8 af[2][2], bfr[2][4];
; #pragma unroll
;     for (int kk = 0; kk < 2; ++kk) {
;       const int xo = kk ? x1 : x0;
;       af[kk][0] = *(const LAS bf16x8*)(cur + a_rd + xo);
;       bfr[kk][0] = *(const LAS bf16x8*)(cur + b_rd + xo);
;       bfr[kk][1] = *(const LAS bf16x8*)(cur + b_rd + 2048 + xo);
;       af[kk][1] = *(const LAS bf16x8*)(cur + a_rd + 2048 + xo);
;       bfr[kk][2] = *(const LAS bf16x8*)(cur + b_rd + 4096 + xo);
;       bfr[kk][3] = *(const LAS bf16x8*)(cur + b_rd + 6144 + xo);
;     }
;     DMA_STEP_(kn, s2);
; #pragma unroll
;     for (int kk = 0; kk < 2; ++kk) {
;       acc[0][0] = mfma32(bfr[kk][0], af[kk][0], acc[0][0]); acc[0][1] = mfma32(bfr[kk][1], af[kk][0], acc[0][1]);
;       acc[1][0] = mfma32(bfr[kk][0], af[kk][1], acc[1][0]); acc[1][1] = mfma32(bfr[kk][1], af[kk][1], acc[1][1]);
.LBB0_150:
	s_and_b64 vcc, exec, s[12:13]
	s_cbranch_vccz .LBB0_145
	s_mul_hi_i32 s10, s40, 0x2aaaaaab
	s_lshr_b32 s11, s10, 31
	s_ashr_i32 s10, s10, 2
	s_add_i32 s10, s10, s11
	v_readlane_b32 s12, v252, 18
	v_mov_b32_e32 v189, v188
	s_mul_i32 s11, s10, 0xffffffe8
	s_lshl_b32 s10, s10, s12
	v_readlane_b32 s12, v252, 41
	s_add_i32 s10, s10, s12
	v_readfirstlane_b32 s43, v189
	s_ashr_i32 s45, s43, 6
	s_lshl_b32 s12, s40, 7
	s_add_i32 s11, s11, s40
	s_lshl_b32 s10, s10, 10
	s_and_b32 s12, s12, 0x380
	s_lshl_b32 s44, s45, 2
	s_ashr_i32 s43, s43, 1
	s_or_b32 s41, s10, s12
	s_lshl_b32 s10, s11, 5
	v_and_b32_e32 v0, 31, v189
	s_mov_b32 s59, 0
	s_lshl_b32 s44, s45, 12
	s_andn2_b32 s43, s43, 63
	s_and_b32 s12, s10, 0xffffff00
	s_add_i32 s44, s44, 16
	v_or_b32_e32 v197, s43, v0
	s_lshl_b32 s43, s45, 7
	s_lshl_b32 s10, s45, 1
	s_ashr_i32 s13, s12, 31
	s_add_i32 s60, s44, 0x2000
	s_and_b32 s43, s43, 0x80
	s_mul_i32 s57, s41, 0x1200
	s_mul_hi_i32 s56, s41, 0x1200
	s_add_u32 s57, s22, s57
	s_mul_i32 s11, s45, 0x24000
	s_addc_u32 s58, s23, s56
	s_mul_hi_i32 s10, s10, 0x12000
	s_add_u32 s56, s57, s11
	s_addc_u32 s57, s58, s10
	s_mul_i32 s11, s12, 64
	s_mov_b32 s10, 0
	s_add_u32 s11, s28, s11
	s_mul_i32 s47, s45, 0x1000
	s_addc_u32 s10, s29, s10
	v_bfe_u32 v2, v189, 2, 4
	v_lshlrev_b32_e32 v3, 4, v189
	s_add_u32 s58, s11, s47
	v_bitop3_b32 v5, v3, 48, v189 bitop3:0x48
	v_or_b32_e32 v3, s43, v0
	v_mul_u32_u24_e32 v0, 0x1200, v2
	s_addc_u32 s59, s10, s59
	s_lshl_b32 s10, s45, 11
	v_or_b32_e32 v0, v0, v5
	s_sub_i32 s45, s44, s10
	v_mul_u32_u24_e32 v6, 0x300, v2
	v_lshl_or_b32 v10, v2, 6, v5
	v_mov_b32_e32 v11, 0
	v_lshl_add_u64 v[192:193], s[56:57], 0, v[0:1]
	s_mov_b32 m0, s45
	s_mov_b64 s[10:11], 0x12000
	v_lshlrev_b32_e32 v218, 6, v3
	global_load_lds_dwordx4 v0, s[56:57]
	v_lshl_add_u64 v[2:3], v[192:193], 0, s[10:11]
	s_add_i32 m0, s45, 0x400
	v_or_b32_e32 v0, v6, v5
	global_load_lds_dwordx4 v[2:3], off
	v_lshl_add_u64 v[194:195], s[58:59], 0, v[10:11]
	s_mov_b32 m0, s60
	s_mov_b64 s[56:57], 0x3000
	global_load_lds_dwordx4 v[194:195], off
	global_load_lds_dwordx4 v[194:195], off offset:1024
	global_load_lds_dwordx4 v[194:195], off offset:2048
	global_load_lds_dwordx4 v[194:195], off offset:3072
	s_mov_b64 s[10:11], 0x6000
	s_mov_b64 s[56:57], 0x9000
	s_mov_b64 s[10:11], 0x12040
	s_add_i32 m0, s45, 0x6000
	v_lshl_add_u64 v[2:3], v[192:193], 0, 64
	global_load_lds_dwordx4 v[2:3], off
	v_lshl_add_u64 v[2:3], v[192:193], 0, s[10:11]
	s_add_i32 m0, s45, 0x6400
	s_mov_b64 s[56:57], 0x3040
	global_load_lds_dwordx4 v[2:3], off
	s_add_i32 m0, s44, 0x8000
	s_mov_b32 s100, 0xc000
	v_lshl_add_u64 v[2:3], v[194:195], 0, s[100:101]
	global_load_lds_dwordx4 v[2:3], off
	global_load_lds_dwordx4 v[2:3], off offset:1024
	global_load_lds_dwordx4 v[2:3], off offset:2048
	global_load_lds_dwordx4 v[2:3], off offset:3072
	s_mov_b64 s[10:11], 0x6040
	s_mov_b64 s[56:57], 0x9040
	v_bfe_u32 v196, v189, 5, 1
	v_bfe_u32 v5, v189, 2, 2
	v_lshrrev_b32_e32 v4, 2, v189
	s_lshl_b32 s100, s100, 1
	v_lshl_add_u64 v[194:195], v[194:195], 0, s[100:101]
	s_waitcnt vmcnt(6)
	s_barrier
	v_bitop3_b32 v2, v196, v5, 2 bitop3:0x36
	v_bitop3_b32 v0, v196, v4, 3 bitop3:0x78
	v_lshlrev_b32_e32 v220, 4, v2
	v_mov_b32_e32 v2, 0
	s_mov_b32 s42, 1
	s_mov_b32 s46, 0xc000
	v_lshlrev_b32_e32 v219, 6, v197
	v_lshlrev_b32_e32 v0, 4, v0
	s_mov_b32 s47, 0
	v_readfirstlane_b32 s10, v192
	v_readfirstlane_b32 s11, v193
	v_readfirstlane_b32 s100, v194
	v_readfirstlane_b32 s101, v195
	s_sub_u32 s10, s10, 0x100000
	s_subb_u32 s11, s11, 0
	s_sub_u32 s100, s100, 0x100000
	s_subb_u32 s101, s101, 0
	v_subrev_u32_e32 v238, s10, v192
	v_subrev_u32_e32 v239, s100, v194
	s_add_u32 vcc_lo, s10, s24
	s_addc_u32 vcc_hi, s11, s25
	s_add_u32 s70, s10, s36
	s_addc_u32 s71, s11, s37
	v_add3_u32 v226, v219, v0, 16
	v_add3_u32 v227, v218, v0, 16
	v_add3_u32 v228, v219, v220, 16
	v_add3_u32 v229, v218, v220, 16
	ds_read_b128 v[158:161], v226 offset:0
	ds_read_b128 v[182:185], v227 offset:8192
	ds_read_b128 v[178:181], v227 offset:10240
	ds_read_b128 v[162:165], v226 offset:2048
	ds_read_b128 v[174:177], v227 offset:12288
	ds_read_b128 v[170:173], v227 offset:14336
	s_mov_b64 s[56:57], 0x3080
	s_mov_b64 s[58:59], 0x9080
	s_setprio 1
	ds_read_b128 v[138:141], v228 offset:0
	ds_read_b128 v[166:169], v229 offset:8192
	ds_read_b128 v[154:157], v229 offset:10240
	ds_read_b128 v[142:145], v228 offset:2048
	ds_read_b128 v[146:149], v229 offset:12288
	ds_read_b128 v[150:153], v229 offset:14336
	s_add_i32 m0, s45, 0xc000
	s_waitcnt lgkmcnt(6)
	v_mfma_f32_32x32x16_bf16 v[114:129], v[182:185], v[158:161], 0
	global_load_lds_dwordx4 v238, vcc
	s_add_i32 m0, s45, 0xc400
	s_add_u32 vcc_lo, vcc_lo, 64
	s_addc_u32 vcc_hi, vcc_hi, 0
	v_mfma_f32_32x32x16_bf16 v[98:113], v[178:181], v[158:161], 0
	global_load_lds_dwordx4 v238, s[70:71]
	s_add_i32 m0, s44, 0xe000
	s_add_u32 s70, s70, 64
	s_addc_u32 s71, s71, 0
	v_mfma_f32_32x32x16_bf16 v[66:81], v[182:185], v[162:165], 0
	global_load_lds_dwordx4 v239, s[100:101]
	v_mfma_f32_32x32x16_bf16 v[34:49], v[178:181], v[162:165], 0
	global_load_lds_dwordx4 v239, s[100:101] offset:1024
	v_mfma_f32_32x32x16_bf16 v[82:97], v[174:177], v[158:161], 0
	global_load_lds_dwordx4 v239, s[100:101] offset:2048
	v_mfma_f32_32x32x16_bf16 v[50:65], v[170:173], v[158:161], 0
	global_load_lds_dwordx4 v239, s[100:101] offset:3072
	s_add_u32 s100, s100, 0xc000
	s_addc_u32 s101, s101, 0
	v_mfma_f32_32x32x16_bf16 v[18:33], v[174:177], v[162:165], 0
	v_mfma_f32_32x32x16_bf16 v[2:17], v[170:173], v[162:165], 0
	s_waitcnt vmcnt(6) lgkmcnt(0)
	s_barrier
; #define LAS __attribute__((address_space(3)))
; DI f32x16 mfma32(bf16x8 a, bf16x8 b, f32x16 c) { return __builtin_amdgcn_mfma_f32_32x32x16_bf16(a, b, c, 0, 0, 0); }
;     ...
;   for (int kt = 0; kt < nk; ++kt) {
;     const int kn = (kt + 2 < nk) ? (kt + 2) : (nk - 1);
;     const LAS char* cur = lds + s0;
;     bf16x8 af[2][2], bfr[2][4];
; #pragma unroll
;     for (int kk = 0; kk < 2; ++kk) {
;       const int xo = kk ? x1 : x0;
;       af[kk][0] = *(const LAS bf16x8*)(cur + a_rd + xo);
;       bfr[kk][0] = *(const LAS bf16x8*)(cur + b_rd + xo);
;       bfr[kk][1] = *(const LAS bf16x8*)(cur + b_rd + 2048 + xo);
;       af[kk][1] = *(const LAS bf16x8*)(cur + a_rd + 2048 + xo);
;       bfr[kk][2] = *(const LAS bf16x8*)(cur + b_rd + 4096 + xo);
;       bfr[kk][3] = *(const LAS bf16x8*)(cur + b_rd + 6144 + xo);
;     }
;     DMA_STEP_(kn, s2);
; #pragma unroll
;     for (int kk = 0; kk < 2; ++kk) {
;       acc[0][0] = mfma32(bfr[kk][0], af[kk][0], acc[0][0]); acc[0][1] = mfma32(bfr[kk][1], af[kk][0], acc[0][1]);
;       acc[1][0] = mfma32(bfr[kk][0], af[kk][1], acc[1][0]); acc[1][1] = mfma32(bfr[kk][1], af[kk][1], acc[1][1]);
;       acc[0][2] = mfma32(bfr[kk][2], af[kk][0], acc[0][2]); acc[0][3] = mfma32(bfr[kk][3], af[kk][0], acc[0][3]);
;       acc[1][2] = mfma32(bfr[kk][2], af[kk][1], acc[1][2]); acc[1][3] = mfma32(bfr[kk][3], af[kk][1], acc[1][3]);
;     }
;     __builtin_amdgcn_sched_group_barrier(0x100, 12, 0);
;     __builtin_amdgcn_sched_group_barrier(0x010, 6, 0);
;     __builtin_amdgcn_sched_group_barrier(0x008, 16, 0);
;     asm volatile("s_waitcnt vmcnt(6) lgkmcnt(0)" ::: "memory");
;     __builtin_amdgcn_s_barrier();
;     asm volatile("" ::: "memory");
;     s0 = (s0 == 2 * STG) ? 0 : s0 + STG;
;     s2 = (s2 == 2 * STG) ? 0 : s2 + STG;
;   }
	ds_read_b128 v[158:161], v226 offset:24576
	ds_read_b128 v[182:185], v227 offset:32768
	ds_read_b128 v[178:181], v227 offset:34816
	ds_read_b128 v[162:165], v226 offset:26624
	ds_read_b128 v[174:177], v227 offset:36864
	ds_read_b128 v[170:173], v227 offset:38912
	v_mfma_f32_32x32x16_bf16 v[114:129], v[166:169], v[138:141], v[114:129]
	v_mfma_f32_32x32x16_bf16 v[98:113], v[154:157], v[138:141], v[98:113]
	v_mfma_f32_32x32x16_bf16 v[66:81], v[166:169], v[142:145], v[66:81]
	v_mfma_f32_32x32x16_bf16 v[34:49], v[154:157], v[142:145], v[34:49]
	v_mfma_f32_32x32x16_bf16 v[82:97], v[146:149], v[138:141], v[82:97]
	v_mfma_f32_32x32x16_bf16 v[50:65], v[150:153], v[138:141], v[50:65]
	v_mfma_f32_32x32x16_bf16 v[18:33], v[146:149], v[142:145], v[18:33]
	v_mfma_f32_32x32x16_bf16 v[2:17], v[150:153], v[142:145], v[2:17]
	ds_read_b128 v[138:141], v228 offset:24576
	ds_read_b128 v[166:169], v229 offset:32768
	ds_read_b128 v[154:157], v229 offset:34816
	ds_read_b128 v[142:145], v228 offset:26624
	ds_read_b128 v[146:149], v229 offset:36864
	ds_read_b128 v[150:153], v229 offset:38912
	s_add_i32 m0, s45, 0x0
	s_waitcnt lgkmcnt(6)
	v_mfma_f32_32x32x16_bf16 v[114:129], v[182:185], v[158:161], v[114:129]
	global_load_lds_dwordx4 v238, vcc
	s_add_i32 m0, s45, 0x400
	s_add_u32 vcc_lo, vcc_lo, 64
	s_addc_u32 vcc_hi, vcc_hi, 0
	v_mfma_f32_32x32x16_bf16 v[98:113], v[178:181], v[158:161], v[98:113]
	global_load_lds_dwordx4 v238, s[70:71]
	s_add_i32 m0, s44, 0x2000
	s_add_u32 s70, s70, 64
	s_addc_u32 s71, s71, 0
	v_mfma_f32_32x32x16_bf16 v[66:81], v[182:185], v[162:165], v[66:81]
	global_load_lds_dwordx4 v239, s[100:101]
	v_mfma_f32_32x32x16_bf16 v[34:49], v[178:181], v[162:165], v[34:49]
	global_load_lds_dwordx4 v239, s[100:101] offset:1024
	v_mfma_f32_32x32x16_bf16 v[82:97], v[174:177], v[158:161], v[82:97]
	global_load_lds_dwordx4 v239, s[100:101] offset:2048
	v_mfma_f32_32x32x16_bf16 v[50:65], v[170:173], v[158:161], v[50:65]
	global_load_lds_dwordx4 v239, s[100:101] offset:3072
	s_add_u32 s100, s100, 0xc000
	s_addc_u32 s101, s101, 0
	v_mfma_f32_32x32x16_bf16 v[18:33], v[174:177], v[162:165], v[18:33]
	v_mfma_f32_32x32x16_bf16 v[2:17], v[170:173], v[162:165], v[2:17]
	s_waitcnt vmcnt(6) lgkmcnt(0)
	s_barrier
	ds_read_b128 v[158:161], v226 offset:49152
	ds_read_b128 v[182:185], v227 offset:57344
	ds_read_b128 v[178:181], v227 offset:59392
	ds_read_b128 v[162:165], v226 offset:51200
	ds_read_b128 v[174:177], v227 offset:61440
	ds_read_b128 v[170:173], v227 offset:63488
	v_mfma_f32_32x32x16_bf16 v[114:129], v[166:169], v[138:141], v[114:129]
	v_mfma_f32_32x32x16_bf16 v[98:113], v[154:157], v[138:141], v[98:113]
	v_mfma_f32_32x32x16_bf16 v[66:81], v[166:169], v[142:145], v[66:81]
	v_mfma_f32_32x32x16_bf16 v[34:49], v[154:157], v[142:145], v[34:49]
	v_mfma_f32_32x32x16_bf16 v[82:97], v[146:149], v[138:141], v[82:97]
	v_mfma_f32_32x32x16_bf16 v[50:65], v[150:153], v[138:141], v[50:65]
	v_mfma_f32_32x32x16_bf16 v[18:33], v[146:149], v[142:145], v[18:33]
	v_mfma_f32_32x32x16_bf16 v[2:17], v[150:153], v[142:145], v[2:17]
	ds_read_b128 v[138:141], v228 offset:49152
	ds_read_b128 v[166:169], v229 offset:57344
	ds_read_b128 v[154:157], v229 offset:59392
	ds_read_b128 v[142:145], v228 offset:51200
	ds_read_b128 v[146:149], v229 offset:61440
	ds_read_b128 v[150:153], v229 offset:63488
	s_add_i32 m0, s45, 0x6000
	s_waitcnt lgkmcnt(6)
	v_mfma_f32_32x32x16_bf16 v[114:129], v[182:185], v[158:161], v[114:129]
	global_load_lds_dwordx4 v238, vcc
	s_add_i32 m0, s45, 0x6400
	s_add_u32 vcc_lo, vcc_lo, 64
	s_addc_u32 vcc_hi, vcc_hi, 0
	v_mfma_f32_32x32x16_bf16 v[98:113], v[178:181], v[158:161], v[98:113]
	global_load_lds_dwordx4 v238, s[70:71]
	s_add_i32 m0, s44, 0x8000
	s_add_u32 s70, s70, 64
	s_addc_u32 s71, s71, 0
	v_mfma_f32_32x32x16_bf16 v[66:81], v[182:185], v[162:165], v[66:81]
	global_load_lds_dwordx4 v239, s[100:101]
	v_mfma_f32_32x32x16_bf16 v[34:49], v[178:181], v[162:165], v[34:49]
	global_load_lds_dwordx4 v239, s[100:101] offset:1024
	v_mfma_f32_32x32x16_bf16 v[82:97], v[174:177], v[158:161], v[82:97]
	global_load_lds_dwordx4 v239, s[100:101] offset:2048
	v_mfma_f32_32x32x16_bf16 v[50:65], v[170:173], v[158:161], v[50:65]
	global_load_lds_dwordx4 v239, s[100:101] offset:3072
	s_add_u32 s100, s100, 0xc000
	s_addc_u32 s101, s101, 0
	v_mfma_f32_32x32x16_bf16 v[18:33], v[174:177], v[162:165], v[18:33]
	v_mfma_f32_32x32x16_bf16 v[2:17], v[170:173], v[162:165], v[2:17]
	s_waitcnt vmcnt(6) lgkmcnt(0)
	s_barrier
	ds_read_b128 v[158:161], v226 offset:0
	ds_read_b128 v[182:185], v227 offset:8192
	ds_read_b128 v[178:181], v227 offset:10240
	ds_read_b128 v[162:165], v226 offset:2048
	ds_read_b128 v[174:177], v227 offset:12288
	ds_read_b128 v[170:173], v227 offset:14336
	v_mfma_f32_32x32x16_bf16 v[114:129], v[166:169], v[138:141], v[114:129]
	v_mfma_f32_32x32x16_bf16 v[98:113], v[154:157], v[138:141], v[98:113]
	v_mfma_f32_32x32x16_bf16 v[66:81], v[166:169], v[142:145], v[66:81]
	v_mfma_f32_32x32x16_bf16 v[34:49], v[154:157], v[142:145], v[34:49]
	v_mfma_f32_32x32x16_bf16 v[82:97], v[146:149], v[138:141], v[82:97]
	v_mfma_f32_32x32x16_bf16 v[50:65], v[150:153], v[138:141], v[50:65]
	v_mfma_f32_32x32x16_bf16 v[18:33], v[146:149], v[142:145], v[18:33]
	v_mfma_f32_32x32x16_bf16 v[2:17], v[150:153], v[142:145], v[2:17]
	ds_read_b128 v[138:141], v228 offset:0
	ds_read_b128 v[166:169], v229 offset:8192
	ds_read_b128 v[154:157], v229 offset:10240
	ds_read_b128 v[142:145], v228 offset:2048
	ds_read_b128 v[146:149], v229 offset:12288
	ds_read_b128 v[150:153], v229 offset:14336
	s_add_i32 m0, s45, 0xc000
	s_waitcnt lgkmcnt(6)
	v_mfma_f32_32x32x16_bf16 v[114:129], v[182:185], v[158:161], v[114:129]
	global_load_lds_dwordx4 v238, vcc
	s_add_i32 m0, s45, 0xc400
	s_add_u32 vcc_lo, vcc_lo, 64
	s_addc_u32 vcc_hi, vcc_hi, 0
	v_mfma_f32_32x32x16_bf16 v[98:113], v[178:181], v[158:161], v[98:113]
	global_load_lds_dwordx4 v238, s[70:71]
	s_add_i32 m0, s44, 0xe000
	s_add_u32 s70, s70, 64
	s_addc_u32 s71, s71, 0
	v_mfma_f32_32x32x16_bf16 v[66:81], v[182:185], v[162:165], v[66:81]
	global_load_lds_dwordx4 v239, s[100:101]
	v_mfma_f32_32x32x16_bf16 v[34:49], v[178:181], v[162:165], v[34:49]
	global_load_lds_dwordx4 v239, s[100:101] offset:1024
	v_mfma_f32_32x32x16_bf16 v[82:97], v[174:177], v[158:161], v[82:97]
	global_load_lds_dwordx4 v239, s[100:101] offset:2048
	v_mfma_f32_32x32x16_bf16 v[50:65], v[170:173], v[158:161], v[50:65]
	global_load_lds_dwordx4 v239, s[100:101] offset:3072
	s_add_u32 s100, s100, 0xc000
	s_addc_u32 s101, s101, 0
	v_mfma_f32_32x32x16_bf16 v[18:33], v[174:177], v[162:165], v[18:33]
	v_mfma_f32_32x32x16_bf16 v[2:17], v[170:173], v[162:165], v[2:17]
	s_waitcnt vmcnt(6) lgkmcnt(0)
	s_barrier
; #define LAS __attribute__((address_space(3)))
; DI f32x16 mfma32(bf16x8 a, bf16x8 b, f32x16 c) { return __builtin_amdgcn_mfma_f32_32x32x16_bf16(a, b, c, 0, 0, 0); }
;     ...
;   for (int kt = 0; kt < nk; ++kt) {
;     const int kn = (kt + 2 < nk) ? (kt + 2) : (nk - 1);
;     const LAS char* cur = lds + s0;
;     bf16x8 af[2][2], bfr[2][4];
; #pragma unroll
;     for (int kk = 0; kk < 2; ++kk) {
;       const int xo = kk ? x1 : x0;
;       af[kk][0] = *(const LAS bf16x8*)(cur + a_rd + xo);
;       bfr[kk][0] = *(const LAS bf16x8*)(cur + b_rd + xo);
;       bfr[kk][1] = *(const LAS bf16x8*)(cur + b_rd + 2048 + xo);
;       af[kk][1] = *(const LAS bf16x8*)(cur + a_rd + 2048 + xo);
;       bfr[kk][2] = *(const LAS bf16x8*)(cur + b_rd + 4096 + xo);
;       bfr[kk][3] = *(const LAS bf16x8*)(cur + b_rd + 6144 + xo);
;     }
;     DMA_STEP_(kn, s2);
; #pragma unroll
;     for (int kk = 0; kk < 2; ++kk) {
;       acc[0][0] = mfma32(bfr[kk][0], af[kk][0], acc[0][0]); acc[0][1] = mfma32(bfr[kk][1], af[kk][0], acc[0][1]);
;       acc[1][0] = mfma32(bfr[kk][0], af[kk][1], acc[1][0]); acc[1][1] = mfma32(bfr[kk][1], af[kk][1], acc[1][1]);
;       acc[0][2] = mfma32(bfr[kk][2], af[kk][0], acc[0][2]); acc[0][3] = mfma32(bfr[kk][3], af[kk][0], acc[0][3]);
;       acc[1][2] = mfma32(bfr[kk][2], af[kk][1], acc[1][2]); acc[1][3] = mfma32(bfr[kk][3], af[kk][1], acc[1][3]);
;     }
;     __builtin_amdgcn_sched_group_barrier(0x100, 12, 0);
;     __builtin_amdgcn_sched_group_barrier(0x010, 6, 0);
;     __builtin_amdgcn_sched_group_barrier(0x008, 16, 0);
;     asm volatile("s_waitcnt vmcnt(6) lgkmcnt(0)" ::: "memory");
;     __builtin_amdgcn_s_barrier();
;     asm volatile("" ::: "memory");
;     s0 = (s0 == 2 * STG) ? 0 : s0 + STG;
;     s2 = (s2 == 2 * STG) ? 0 : s2 + STG;
;   }
	ds_read_b128 v[158:161], v226 offset:24576
	ds_read_b128 v[182:185], v227 offset:32768
	ds_read_b128 v[178:181], v227 offset:34816
	ds_read_b128 v[162:165], v226 offset:26624
	ds_read_b128 v[174:177], v227 offset:36864
	ds_read_b128 v[170:173], v227 offset:38912
	v_mfma_f32_32x32x16_bf16 v[114:129], v[166:169], v[138:141], v[114:129]
	v_mfma_f32_32x32x16_bf16 v[98:113], v[154:157], v[138:141], v[98:113]
	v_mfma_f32_32x32x16_bf16 v[66:81], v[166:169], v[142:145], v[66:81]
	v_mfma_f32_32x32x16_bf16 v[34:49], v[154:157], v[142:145], v[34:49]
	v_mfma_f32_32x32x16_bf16 v[82:97], v[146:149], v[138:141], v[82:97]
	v_mfma_f32_32x32x16_bf16 v[50:65], v[150:153], v[138:141], v[50:65]
	v_mfma_f32_32x32x16_bf16 v[18:33], v[146:149], v[142:145], v[18:33]
	v_mfma_f32_32x32x16_bf16 v[2:17], v[150:153], v[142:145], v[2:17]
	ds_read_b128 v[138:141], v228 offset:24576
	ds_read_b128 v[166:169], v229 offset:32768
	ds_read_b128 v[154:157], v229 offset:34816
	ds_read_b128 v[142:145], v228 offset:26624
	ds_read_b128 v[146:149], v229 offset:36864
	ds_read_b128 v[150:153], v229 offset:38912
	s_add_i32 m0, s45, 0x0
	s_waitcnt lgkmcnt(6)
	v_mfma_f32_32x32x16_bf16 v[114:129], v[182:185], v[158:161], v[114:129]
	global_load_lds_dwordx4 v238, vcc
	s_add_i32 m0, s45, 0x400
	s_add_u32 vcc_lo, vcc_lo, 64
	s_addc_u32 vcc_hi, vcc_hi, 0
	v_mfma_f32_32x32x16_bf16 v[98:113], v[178:181], v[158:161], v[98:113]
	global_load_lds_dwordx4 v238, s[70:71]
	s_add_i32 m0, s44, 0x2000
	s_add_u32 s70, s70, 64
	s_addc_u32 s71, s71, 0
	v_mfma_f32_32x32x16_bf16 v[66:81], v[182:185], v[162:165], v[66:81]
	global_load_lds_dwordx4 v239, s[100:101]
	v_mfma_f32_32x32x16_bf16 v[34:49], v[178:181], v[162:165], v[34:49]
	global_load_lds_dwordx4 v239, s[100:101] offset:1024
	v_mfma_f32_32x32x16_bf16 v[82:97], v[174:177], v[158:161], v[82:97]
	global_load_lds_dwordx4 v239, s[100:101] offset:2048
	v_mfma_f32_32x32x16_bf16 v[50:65], v[170:173], v[158:161], v[50:65]
	global_load_lds_dwordx4 v239, s[100:101] offset:3072
	s_add_u32 s100, s100, 0xc000
	s_addc_u32 s101, s101, 0
	v_mfma_f32_32x32x16_bf16 v[18:33], v[174:177], v[162:165], v[18:33]
	v_mfma_f32_32x32x16_bf16 v[2:17], v[170:173], v[162:165], v[2:17]
	s_waitcnt vmcnt(6) lgkmcnt(0)
	s_barrier
	ds_read_b128 v[158:161], v226 offset:49152
	ds_read_b128 v[182:185], v227 offset:57344
	ds_read_b128 v[178:181], v227 offset:59392
	ds_read_b128 v[162:165], v226 offset:51200
	ds_read_b128 v[174:177], v227 offset:61440
	ds_read_b128 v[170:173], v227 offset:63488
	v_mfma_f32_32x32x16_bf16 v[114:129], v[166:169], v[138:141], v[114:129]
	v_mfma_f32_32x32x16_bf16 v[98:113], v[154:157], v[138:141], v[98:113]
	v_mfma_f32_32x32x16_bf16 v[66:81], v[166:169], v[142:145], v[66:81]
	v_mfma_f32_32x32x16_bf16 v[34:49], v[154:157], v[142:145], v[34:49]
	v_mfma_f32_32x32x16_bf16 v[82:97], v[146:149], v[138:141], v[82:97]
	v_mfma_f32_32x32x16_bf16 v[50:65], v[150:153], v[138:141], v[50:65]
	v_mfma_f32_32x32x16_bf16 v[18:33], v[146:149], v[142:145], v[18:33]
	v_mfma_f32_32x32x16_bf16 v[2:17], v[150:153], v[142:145], v[2:17]
	ds_read_b128 v[138:141], v228 offset:49152
	ds_read_b128 v[166:169], v229 offset:57344
	ds_read_b128 v[154:157], v229 offset:59392
	ds_read_b128 v[142:145], v228 offset:51200
	ds_read_b128 v[146:149], v229 offset:61440
	ds_read_b128 v[150:153], v229 offset:63488
	s_add_i32 m0, s45, 0x6000
	s_waitcnt lgkmcnt(6)
	v_mfma_f32_32x32x16_bf16 v[114:129], v[182:185], v[158:161], v[114:129]
	global_load_lds_dwordx4 v238, vcc
	s_add_i32 m0, s45, 0x6400
	s_add_u32 vcc_lo, vcc_lo, 64
	s_addc_u32 vcc_hi, vcc_hi, 0
	v_mfma_f32_32x32x16_bf16 v[98:113], v[178:181], v[158:161], v[98:113]
	global_load_lds_dwordx4 v238, s[70:71]
	s_add_i32 m0, s44, 0x8000
	s_add_u32 s70, s70, 64
	s_addc_u32 s71, s71, 0
	v_mfma_f32_32x32x16_bf16 v[66:81], v[182:185], v[162:165], v[66:81]
	global_load_lds_dwordx4 v239, s[100:101]
	v_mfma_f32_32x32x16_bf16 v[34:49], v[178:181], v[162:165], v[34:49]
	global_load_lds_dwordx4 v239, s[100:101] offset:1024
	v_mfma_f32_32x32x16_bf16 v[82:97], v[174:177], v[158:161], v[82:97]
	global_load_lds_dwordx4 v239, s[100:101] offset:2048
	v_mfma_f32_32x32x16_bf16 v[50:65], v[170:173], v[158:161], v[50:65]
	global_load_lds_dwordx4 v239, s[100:101] offset:3072
	s_add_u32 s100, s100, 0xc000
	s_addc_u32 s101, s101, 0
	v_mfma_f32_32x32x16_bf16 v[18:33], v[174:177], v[162:165], v[18:33]
	v_mfma_f32_32x32x16_bf16 v[2:17], v[170:173], v[162:165], v[2:17]
	s_waitcnt vmcnt(6) lgkmcnt(0)
	s_barrier
	ds_read_b128 v[158:161], v226 offset:0
	ds_read_b128 v[182:185], v227 offset:8192
	ds_read_b128 v[178:181], v227 offset:10240
	ds_read_b128 v[162:165], v226 offset:2048
	ds_read_b128 v[174:177], v227 offset:12288
	ds_read_b128 v[170:173], v227 offset:14336
	v_mfma_f32_32x32x16_bf16 v[114:129], v[166:169], v[138:141], v[114:129]
	v_mfma_f32_32x32x16_bf16 v[98:113], v[154:157], v[138:141], v[98:113]
	v_mfma_f32_32x32x16_bf16 v[66:81], v[166:169], v[142:145], v[66:81]
	v_mfma_f32_32x32x16_bf16 v[34:49], v[154:157], v[142:145], v[34:49]
	v_mfma_f32_32x32x16_bf16 v[82:97], v[146:149], v[138:141], v[82:97]
	v_mfma_f32_32x32x16_bf16 v[50:65], v[150:153], v[138:141], v[50:65]
	v_mfma_f32_32x32x16_bf16 v[18:33], v[146:149], v[142:145], v[18:33]
	v_mfma_f32_32x32x16_bf16 v[2:17], v[150:153], v[142:145], v[2:17]
	s_add_i32 s42, s42, 6
; #define LAS __attribute__((address_space(3)))
; DI f32x16 mfma32(bf16x8 a, bf16x8 b, f32x16 c) { return __builtin_amdgcn_mfma_f32_32x32x16_bf16(a, b, c, 0, 0, 0); }
;     ...
;   for (int kt = 0; kt < nk; ++kt) {
;     const int kn = (kt + 2 < nk) ? (kt + 2) : (nk - 1);
;     const LAS char* cur = lds + s0;
;     bf16x8 af[2][2], bfr[2][4];
; #pragma unroll
;     for (int kk = 0; kk < 2; ++kk) {
;       const int xo = kk ? x1 : x0;
;       af[kk][0] = *(const LAS bf16x8*)(cur + a_rd + xo);
;       bfr[kk][0] = *(const LAS bf16x8*)(cur + b_rd + xo);
;       bfr[kk][1] = *(const LAS bf16x8*)(cur + b_rd + 2048 + xo);
;       af[kk][1] = *(const LAS bf16x8*)(cur + a_rd + 2048 + xo);
;       bfr[kk][2] = *(const LAS bf16x8*)(cur + b_rd + 4096 + xo);
;       bfr[kk][3] = *(const LAS bf16x8*)(cur + b_rd + 6144 + xo);
;     }
;     DMA_STEP_(kn, s2);
; #pragma unroll
;     for (int kk = 0; kk < 2; ++kk) {
;       acc[0][0] = mfma32(bfr[kk][0], af[kk][0], acc[0][0]); acc[0][1] = mfma32(bfr[kk][1], af[kk][0], acc[0][1]);
;       acc[1][0] = mfma32(bfr[kk][0], af[kk][1], acc[1][0]); acc[1][1] = mfma32(bfr[kk][1], af[kk][1], acc[1][1]);
;       acc[0][2] = mfma32(bfr[kk][2], af[kk][0], acc[0][2]); acc[0][3] = mfma32(bfr[kk][3], af[kk][0], acc[0][3]);
;       acc[1][2] = mfma32(bfr[kk][2], af[kk][1], acc[1][2]); acc[1][3] = mfma32(bfr[kk][3], af[kk][1], acc[1][3]);
;     }
;     __builtin_amdgcn_sched_group_barrier(0x100, 12, 0);
;     __builtin_amdgcn_sched_group_barrier(0x010, 6, 0);
;     __builtin_amdgcn_sched_group_barrier(0x008, 16, 0);
;     asm volatile("s_waitcnt vmcnt(6) lgkmcnt(0)" ::: "memory");
;     __builtin_amdgcn_s_barrier();
;     asm volatile("" ::: "memory");
;     s0 = (s0 == 2 * STG) ? 0 : s0 + STG;
;     s2 = (s2 == 2 * STG) ? 0 : s2 + STG;
;   }
.LBB0_152:
	ds_read_b128 v[138:141], v228 offset:0
	ds_read_b128 v[166:169], v229 offset:8192
	ds_read_b128 v[154:157], v229 offset:10240
	ds_read_b128 v[142:145], v228 offset:2048
	ds_read_b128 v[146:149], v229 offset:12288
	ds_read_b128 v[150:153], v229 offset:14336
	s_add_i32 m0, s45, 0xc000
	s_waitcnt lgkmcnt(6)
	v_mfma_f32_32x32x16_bf16 v[114:129], v[182:185], v[158:161], v[114:129]
	global_load_lds_dwordx4 v238, vcc
	s_add_i32 m0, s45, 0xc400
	s_add_u32 vcc_lo, vcc_lo, 64
	s_addc_u32 vcc_hi, vcc_hi, 0
	v_mfma_f32_32x32x16_bf16 v[98:113], v[178:181], v[158:161], v[98:113]
	global_load_lds_dwordx4 v238, s[70:71]
	s_add_i32 m0, s44, 0xe000
	s_add_u32 s70, s70, 64
	s_addc_u32 s71, s71, 0
	v_mfma_f32_32x32x16_bf16 v[66:81], v[182:185], v[162:165], v[66:81]
	global_load_lds_dwordx4 v239, s[100:101]
	v_mfma_f32_32x32x16_bf16 v[34:49], v[178:181], v[162:165], v[34:49]
	global_load_lds_dwordx4 v239, s[100:101] offset:1024
	v_mfma_f32_32x32x16_bf16 v[82:97], v[174:177], v[158:161], v[82:97]
	global_load_lds_dwordx4 v239, s[100:101] offset:2048
	v_mfma_f32_32x32x16_bf16 v[50:65], v[170:173], v[158:161], v[50:65]
	global_load_lds_dwordx4 v239, s[100:101] offset:3072
	s_add_u32 s100, s100, 0xc000
	s_addc_u32 s101, s101, 0
	v_mfma_f32_32x32x16_bf16 v[18:33], v[174:177], v[162:165], v[18:33]
	v_mfma_f32_32x32x16_bf16 v[2:17], v[170:173], v[162:165], v[2:17]
	s_waitcnt vmcnt(6) lgkmcnt(0)
	s_barrier
	ds_read_b128 v[158:161], v226 offset:24576
	ds_read_b128 v[182:185], v227 offset:32768
	ds_read_b128 v[178:181], v227 offset:34816
	ds_read_b128 v[162:165], v226 offset:26624
	ds_read_b128 v[174:177], v227 offset:36864
	ds_read_b128 v[170:173], v227 offset:38912
	v_mfma_f32_32x32x16_bf16 v[114:129], v[166:169], v[138:141], v[114:129]
	v_mfma_f32_32x32x16_bf16 v[98:113], v[154:157], v[138:141], v[98:113]
	v_mfma_f32_32x32x16_bf16 v[66:81], v[166:169], v[142:145], v[66:81]
	v_mfma_f32_32x32x16_bf16 v[34:49], v[154:157], v[142:145], v[34:49]
	v_mfma_f32_32x32x16_bf16 v[82:97], v[146:149], v[138:141], v[82:97]
	v_mfma_f32_32x32x16_bf16 v[50:65], v[150:153], v[138:141], v[50:65]
	v_mfma_f32_32x32x16_bf16 v[18:33], v[146:149], v[142:145], v[18:33]
	v_mfma_f32_32x32x16_bf16 v[2:17], v[150:153], v[142:145], v[2:17]
	ds_read_b128 v[138:141], v228 offset:24576
	ds_read_b128 v[166:169], v229 offset:32768
	ds_read_b128 v[154:157], v229 offset:34816
	ds_read_b128 v[142:145], v228 offset:26624
	ds_read_b128 v[146:149], v229 offset:36864
	ds_read_b128 v[150:153], v229 offset:38912
	s_add_i32 m0, s45, 0x0
	s_waitcnt lgkmcnt(6)
	v_mfma_f32_32x32x16_bf16 v[114:129], v[182:185], v[158:161], v[114:129]
	global_load_lds_dwordx4 v238, vcc
	s_add_i32 m0, s45, 0x400
	s_add_u32 vcc_lo, vcc_lo, 64
	s_addc_u32 vcc_hi, vcc_hi, 0
	v_mfma_f32_32x32x16_bf16 v[98:113], v[178:181], v[158:161], v[98:113]
	global_load_lds_dwordx4 v238, s[70:71]
	s_add_i32 m0, s44, 0x2000
	s_add_u32 s70, s70, 64
	s_addc_u32 s71, s71, 0
	v_mfma_f32_32x32x16_bf16 v[66:81], v[182:185], v[162:165], v[66:81]
	global_load_lds_dwordx4 v239, s[100:101]
	v_mfma_f32_32x32x16_bf16 v[34:49], v[178:181], v[162:165], v[34:49]
	global_load_lds_dwordx4 v239, s[100:101] offset:1024
	v_mfma_f32_32x32x16_bf16 v[82:97], v[174:177], v[158:161], v[82:97]
	global_load_lds_dwordx4 v239, s[100:101] offset:2048
	v_mfma_f32_32x32x16_bf16 v[50:65], v[170:173], v[158:161], v[50:65]
	global_load_lds_dwordx4 v239, s[100:101] offset:3072
	s_add_u32 s100, s100, 0xc000
	s_addc_u32 s101, s101, 0
	v_mfma_f32_32x32x16_bf16 v[18:33], v[174:177], v[162:165], v[18:33]
	v_mfma_f32_32x32x16_bf16 v[2:17], v[170:173], v[162:165], v[2:17]
	s_waitcnt vmcnt(6) lgkmcnt(0)
	s_barrier
	ds_read_b128 v[158:161], v226 offset:49152
	ds_read_b128 v[182:185], v227 offset:57344
	ds_read_b128 v[178:181], v227 offset:59392
	ds_read_b128 v[162:165], v226 offset:51200
	ds_read_b128 v[174:177], v227 offset:61440
	ds_read_b128 v[170:173], v227 offset:63488
	v_mfma_f32_32x32x16_bf16 v[114:129], v[166:169], v[138:141], v[114:129]
	v_mfma_f32_32x32x16_bf16 v[98:113], v[154:157], v[138:141], v[98:113]
	v_mfma_f32_32x32x16_bf16 v[66:81], v[166:169], v[142:145], v[66:81]
	v_mfma_f32_32x32x16_bf16 v[34:49], v[154:157], v[142:145], v[34:49]
	v_mfma_f32_32x32x16_bf16 v[82:97], v[146:149], v[138:141], v[82:97]
	v_mfma_f32_32x32x16_bf16 v[50:65], v[150:153], v[138:141], v[50:65]
	v_mfma_f32_32x32x16_bf16 v[18:33], v[146:149], v[142:145], v[18:33]
	v_mfma_f32_32x32x16_bf16 v[2:17], v[150:153], v[142:145], v[2:17]
	ds_read_b128 v[138:141], v228 offset:49152
	ds_read_b128 v[166:169], v229 offset:57344
	ds_read_b128 v[154:157], v229 offset:59392
	ds_read_b128 v[142:145], v228 offset:51200
	ds_read_b128 v[146:149], v229 offset:61440
	ds_read_b128 v[150:153], v229 offset:63488
	s_add_i32 m0, s45, 0x6000
	s_waitcnt lgkmcnt(6)
	v_mfma_f32_32x32x16_bf16 v[114:129], v[182:185], v[158:161], v[114:129]
	global_load_lds_dwordx4 v238, vcc
	s_add_i32 m0, s45, 0x6400
	s_add_u32 vcc_lo, vcc_lo, 64
	s_addc_u32 vcc_hi, vcc_hi, 0
	v_mfma_f32_32x32x16_bf16 v[98:113], v[178:181], v[158:161], v[98:113]
	global_load_lds_dwordx4 v238, s[70:71]
	s_add_i32 m0, s44, 0x8000
	s_add_u32 s70, s70, 64
	s_addc_u32 s71, s71, 0
	v_mfma_f32_32x32x16_bf16 v[66:81], v[182:185], v[162:165], v[66:81]
	global_load_lds_dwordx4 v239, s[100:101]
	v_mfma_f32_32x32x16_bf16 v[34:49], v[178:181], v[162:165], v[34:49]
	global_load_lds_dwordx4 v239, s[100:101] offset:1024
	v_mfma_f32_32x32x16_bf16 v[82:97], v[174:177], v[158:161], v[82:97]
	global_load_lds_dwordx4 v239, s[100:101] offset:2048
	v_mfma_f32_32x32x16_bf16 v[50:65], v[170:173], v[158:161], v[50:65]
	global_load_lds_dwordx4 v239, s[100:101] offset:3072
	s_add_u32 s100, s100, 0xc000
	s_addc_u32 s101, s101, 0
	v_mfma_f32_32x32x16_bf16 v[18:33], v[174:177], v[162:165], v[18:33]
	v_mfma_f32_32x32x16_bf16 v[2:17], v[170:173], v[162:165], v[2:17]
	s_waitcnt vmcnt(6) lgkmcnt(0)
	s_barrier
; #define LAS __attribute__((address_space(3)))
; DI unsigned pk2(float a, float b) { f32x2 v = {a, b}; bf2_t r = __builtin_convertvector(v, bf2_t); return __builtin_bit_cast(unsigned, r); }
;     ...
;   for (int kt = 0; kt < nk; ++kt) {
;     const int kn = (kt + 2 < nk) ? (kt + 2) : (nk - 1);
;     const LAS char* cur = lds + s0;
;     bf16x8 af[2][2], bfr[2][4];
; #pragma unroll
;     for (int kk = 0; kk < 2; ++kk) {
;       const int xo = kk ? x1 : x0;
;       af[kk][0] = *(const LAS bf16x8*)(cur + a_rd + xo);
;       bfr[kk][0] = *(const LAS bf16x8*)(cur + b_rd + xo);
;       bfr[kk][1] = *(const LAS bf16x8*)(cur + b_rd + 2048 + xo);
;       af[kk][1] = *(const LAS bf16x8*)(cur + a_rd + 2048 + xo);
;       bfr[kk][2] = *(const LAS bf16x8*)(cur + b_rd + 4096 + xo);
;       bfr[kk][3] = *(const LAS bf16x8*)(cur + b_rd + 6144 + xo);
;     }
;     DMA_STEP_(kn, s2);
; #pragma unroll
;     for (int kk = 0; kk < 2; ++kk) {
;       acc[0][0] = mfma32(bfr[kk][0], af[kk][0], acc[0][0]); acc[0][1] = mfma32(bfr[kk][1], af[kk][0], acc[0][1]);
;       acc[1][0] = mfma32(bfr[kk][0], af[kk][1], acc[1][0]); acc[1][1] = mfma32(bfr[kk][1], af[kk][1], acc[1][1]);
;       acc[0][2] = mfma32(bfr[kk][2], af[kk][0], acc[0][2]); acc[0][3] = mfma32(bfr[kk][3], af[kk][0], acc[0][3]);
;       acc[1][2] = mfma32(bfr[kk][2], af[kk][1], acc[1][2]); acc[1][3] = mfma32(bfr[kk][3], af[kk][1], acc[1][3]);
;     }
;     __builtin_amdgcn_sched_group_barrier(0x100, 12, 0);
;     __builtin_amdgcn_sched_group_barrier(0x010, 6, 0);
;     __builtin_amdgcn_sched_group_barrier(0x008, 16, 0);
;     asm volatile("s_waitcnt vmcnt(6) lgkmcnt(0)" ::: "memory");
;     __builtin_amdgcn_s_barrier();
;     asm volatile("" ::: "memory");
;     s0 = (s0 == 2 * STG) ? 0 : s0 + STG;
;     s2 = (s2 == 2 * STG) ? 0 : s2 + STG;
;   }
;   asm volatile("s_waitcnt vmcnt(0)" ::: "memory");
;   __builtin_amdgcn_s_barrier();
;   asm volatile("" ::: "memory");
;     ...
;   {
;     const int h = lane >> 5, cl = lane & 31;
; #pragma unroll
;     for (int i = 0; i < 2; ++i)
; #pragma unroll
;       for (int j = 0; j < 4; ++j)
; #pragma unroll
;         for (int g = 0; g < 4; ++g) {
;           u32x2 w; w.x = pk2(acc[i][j][4 * g], acc[i][j][4 * g + 1]); w.y = pk2(acc[i][j][4 * g + 2], acc[i][j][4 * g + 3]);
;           *(u32x2*)(smem + (wr * 64 + i * 32 + cl) * 528 + (wc * 128 + j * 32 + 8 * g + 4 * h) * 2) = w;
	ds_read_b128 v[158:161], v226 offset:0
	ds_read_b128 v[182:185], v227 offset:8192
	ds_read_b128 v[178:181], v227 offset:10240
	ds_read_b128 v[162:165], v226 offset:2048
	ds_read_b128 v[174:177], v227 offset:12288
	ds_read_b128 v[170:173], v227 offset:14336
	v_mfma_f32_32x32x16_bf16 v[114:129], v[166:169], v[138:141], v[114:129]
	v_mfma_f32_32x32x16_bf16 v[98:113], v[154:157], v[138:141], v[98:113]
	v_mfma_f32_32x32x16_bf16 v[66:81], v[166:169], v[142:145], v[66:81]
	v_mfma_f32_32x32x16_bf16 v[34:49], v[154:157], v[142:145], v[34:49]
	v_mfma_f32_32x32x16_bf16 v[82:97], v[146:149], v[138:141], v[82:97]
	v_mfma_f32_32x32x16_bf16 v[50:65], v[150:153], v[138:141], v[50:65]
	v_mfma_f32_32x32x16_bf16 v[18:33], v[146:149], v[142:145], v[18:33]
	v_mfma_f32_32x32x16_bf16 v[2:17], v[150:153], v[142:145], v[2:17]
	ds_read_b128 v[138:141], v228 offset:0
	ds_read_b128 v[166:169], v229 offset:8192
	ds_read_b128 v[154:157], v229 offset:10240
	ds_read_b128 v[142:145], v228 offset:2048
	ds_read_b128 v[146:149], v229 offset:12288
	ds_read_b128 v[150:153], v229 offset:14336
	s_add_i32 m0, s45, 0xc000
	s_waitcnt lgkmcnt(6)
	v_mfma_f32_32x32x16_bf16 v[114:129], v[182:185], v[158:161], v[114:129]
	global_load_lds_dwordx4 v238, vcc
	s_add_i32 m0, s45, 0xc400
	s_add_u32 vcc_lo, vcc_lo, 64
	s_addc_u32 vcc_hi, vcc_hi, 0
	v_mfma_f32_32x32x16_bf16 v[98:113], v[178:181], v[158:161], v[98:113]
	global_load_lds_dwordx4 v238, s[70:71]
	s_add_i32 m0, s44, 0xe000
	s_add_u32 s70, s70, 64
	s_addc_u32 s71, s71, 0
	v_mfma_f32_32x32x16_bf16 v[66:81], v[182:185], v[162:165], v[66:81]
	global_load_lds_dwordx4 v239, s[100:101]
	v_mfma_f32_32x32x16_bf16 v[34:49], v[178:181], v[162:165], v[34:49]
	global_load_lds_dwordx4 v239, s[100:101] offset:1024
	v_mfma_f32_32x32x16_bf16 v[82:97], v[174:177], v[158:161], v[82:97]
	global_load_lds_dwordx4 v239, s[100:101] offset:2048
	v_mfma_f32_32x32x16_bf16 v[50:65], v[170:173], v[158:161], v[50:65]
	global_load_lds_dwordx4 v239, s[100:101] offset:3072
	s_add_u32 s100, s100, 0xc000
	s_addc_u32 s101, s101, 0
	v_mfma_f32_32x32x16_bf16 v[18:33], v[174:177], v[162:165], v[18:33]
	v_mfma_f32_32x32x16_bf16 v[2:17], v[170:173], v[162:165], v[2:17]
	s_waitcnt vmcnt(6) lgkmcnt(0)
	s_barrier
	ds_read_b128 v[158:161], v226 offset:24576
	ds_read_b128 v[182:185], v227 offset:32768
	ds_read_b128 v[178:181], v227 offset:34816
	ds_read_b128 v[162:165], v226 offset:26624
	ds_read_b128 v[174:177], v227 offset:36864
	ds_read_b128 v[170:173], v227 offset:38912
	v_mfma_f32_32x32x16_bf16 v[114:129], v[166:169], v[138:141], v[114:129]
	v_mfma_f32_32x32x16_bf16 v[98:113], v[154:157], v[138:141], v[98:113]
	v_mfma_f32_32x32x16_bf16 v[66:81], v[166:169], v[142:145], v[66:81]
	v_mfma_f32_32x32x16_bf16 v[34:49], v[154:157], v[142:145], v[34:49]
	v_mfma_f32_32x32x16_bf16 v[82:97], v[146:149], v[138:141], v[82:97]
	v_mfma_f32_32x32x16_bf16 v[50:65], v[150:153], v[138:141], v[50:65]
	v_mfma_f32_32x32x16_bf16 v[18:33], v[146:149], v[142:145], v[18:33]
	v_mfma_f32_32x32x16_bf16 v[2:17], v[150:153], v[142:145], v[2:17]
	ds_read_b128 v[138:141], v228 offset:24576
	ds_read_b128 v[166:169], v229 offset:32768
	ds_read_b128 v[154:157], v229 offset:34816
	ds_read_b128 v[142:145], v228 offset:26624
	ds_read_b128 v[146:149], v229 offset:36864
	ds_read_b128 v[150:153], v229 offset:38912
	s_waitcnt lgkmcnt(6)
	v_mfma_f32_32x32x16_bf16 v[114:129], v[182:185], v[158:161], v[114:129]
	v_mfma_f32_32x32x16_bf16 v[98:113], v[178:181], v[158:161], v[98:113]
	v_mfma_f32_32x32x16_bf16 v[66:81], v[182:185], v[162:165], v[66:81]
	v_mfma_f32_32x32x16_bf16 v[34:49], v[178:181], v[162:165], v[34:49]
	v_mfma_f32_32x32x16_bf16 v[82:97], v[174:177], v[158:161], v[82:97]
	v_mfma_f32_32x32x16_bf16 v[50:65], v[170:173], v[158:161], v[50:65]
	v_mfma_f32_32x32x16_bf16 v[18:33], v[174:177], v[162:165], v[18:33]
	v_mfma_f32_32x32x16_bf16 v[2:17], v[170:173], v[162:165], v[2:17]
	s_waitcnt vmcnt(0) lgkmcnt(0)
	s_barrier
	ds_read_b128 v[158:161], v226 offset:49152
	ds_read_b128 v[182:185], v227 offset:57344
	ds_read_b128 v[178:181], v227 offset:59392
	ds_read_b128 v[162:165], v226 offset:51200
	ds_read_b128 v[174:177], v227 offset:61440
	ds_read_b128 v[170:173], v227 offset:63488
	v_mfma_f32_32x32x16_bf16 v[114:129], v[166:169], v[138:141], v[114:129]
	v_mfma_f32_32x32x16_bf16 v[98:113], v[154:157], v[138:141], v[98:113]
	v_mfma_f32_32x32x16_bf16 v[66:81], v[166:169], v[142:145], v[66:81]
	v_mfma_f32_32x32x16_bf16 v[34:49], v[154:157], v[142:145], v[34:49]
	v_mfma_f32_32x32x16_bf16 v[82:97], v[146:149], v[138:141], v[82:97]
	v_mfma_f32_32x32x16_bf16 v[50:65], v[150:153], v[138:141], v[50:65]
	v_mfma_f32_32x32x16_bf16 v[18:33], v[146:149], v[142:145], v[18:33]
	v_mfma_f32_32x32x16_bf16 v[2:17], v[150:153], v[142:145], v[2:17]
	ds_read_b128 v[138:141], v228 offset:49152
	ds_read_b128 v[166:169], v229 offset:57344
	ds_read_b128 v[154:157], v229 offset:59392
	ds_read_b128 v[142:145], v228 offset:51200
	ds_read_b128 v[146:149], v229 offset:61440
	ds_read_b128 v[150:153], v229 offset:63488
	s_waitcnt lgkmcnt(6)
	v_mfma_f32_32x32x16_bf16 v[114:129], v[182:185], v[158:161], v[114:129]
	v_mfma_f32_32x32x16_bf16 v[98:113], v[178:181], v[158:161], v[98:113]
	v_mfma_f32_32x32x16_bf16 v[66:81], v[182:185], v[162:165], v[66:81]
	v_mfma_f32_32x32x16_bf16 v[34:49], v[178:181], v[162:165], v[34:49]
	v_mfma_f32_32x32x16_bf16 v[82:97], v[174:177], v[158:161], v[82:97]
	v_mfma_f32_32x32x16_bf16 v[50:65], v[170:173], v[158:161], v[50:65]
	v_mfma_f32_32x32x16_bf16 v[18:33], v[174:177], v[162:165], v[18:33]
	v_mfma_f32_32x32x16_bf16 v[2:17], v[170:173], v[162:165], v[2:17]
	s_waitcnt lgkmcnt(0)
	v_mfma_f32_32x32x16_bf16 v[114:129], v[166:169], v[138:141], v[114:129]
	v_mfma_f32_32x32x16_bf16 v[98:113], v[154:157], v[138:141], v[98:113]
	v_mfma_f32_32x32x16_bf16 v[66:81], v[166:169], v[142:145], v[66:81]
	v_mfma_f32_32x32x16_bf16 v[34:49], v[154:157], v[142:145], v[34:49]
	v_mfma_f32_32x32x16_bf16 v[82:97], v[146:149], v[138:141], v[82:97]
	v_mfma_f32_32x32x16_bf16 v[50:65], v[150:153], v[138:141], v[50:65]
	v_mfma_f32_32x32x16_bf16 v[18:33], v[146:149], v[142:145], v[18:33]
	v_mfma_f32_32x32x16_bf16 v[2:17], v[150:153], v[142:145], v[2:17]
	s_waitcnt lgkmcnt(0)
	s_mov_b32 s101, 0
	s_mov_b32 s71, 0
	s_setprio 0
	v_mul_lo_u32 v0, v197, s55
	v_add_u32_e32 v0, 16, v0
	s_nop 1
	v_cvt_pk_bf16_f32 v114, v114, v115
	v_cvt_pk_bf16_f32 v115, v116, v117
	v_lshlrev_b32_e32 v116, 3, v196
	s_lshl_b32 s10, s43, 1
	v_add3_u32 v0, v0, v116, s10
	v_cvt_pk_bf16_f32 v116, v118, v119
	v_cvt_pk_bf16_f32 v117, v120, v121
	v_cvt_pk_bf16_f32 v98, v98, v99
	v_cvt_pk_bf16_f32 v99, v100, v101
	v_cvt_pk_bf16_f32 v100, v102, v103
	v_cvt_pk_bf16_f32 v101, v104, v105
	v_cvt_pk_bf16_f32 v82, v82, v83
	v_cvt_pk_bf16_f32 v83, v84, v85
	v_cvt_pk_bf16_f32 v84, v86, v87
	v_cvt_pk_bf16_f32 v85, v88, v89
	v_cvt_pk_bf16_f32 v50, v50, v51
	v_cvt_pk_bf16_f32 v51, v52, v53
	v_cvt_pk_bf16_f32 v52, v54, v55
	v_cvt_pk_bf16_f32 v53, v56, v57
	s_waitcnt vmcnt(0)
	s_barrier
; DI unsigned pk2(float a, float b) { f32x2 v = {a, b}; bf2_t r = __builtin_convertvector(v, bf2_t); return __builtin_bit_cast(unsigned, r); }
;     ...
;   {
;     const int h = lane >> 5, cl = lane & 31;
; #pragma unroll
;     for (int i = 0; i < 2; ++i)
; #pragma unroll
;       for (int j = 0; j < 4; ++j)
; #pragma unroll
;         for (int g = 0; g < 4; ++g) {
;           u32x2 w; w.x = pk2(acc[i][j][4 * g], acc[i][j][4 * g + 1]); w.y = pk2(acc[i][j][4 * g + 2], acc[i][j][4 * g + 3]);
;           *(u32x2*)(smem + (wr * 64 + i * 32 + cl) * 528 + (wc * 128 + j * 32 + 8 * g + 4 * h) * 2) = w;
;         }
;   }
;   __syncthreads();
	ds_write2_b64 v0, v[114:115], v[116:117] offset1:2
	v_cvt_pk_bf16_f32 v114, v122, v123
	v_cvt_pk_bf16_f32 v115, v124, v125
	v_cvt_pk_bf16_f32 v116, v126, v127
	v_cvt_pk_bf16_f32 v117, v128, v129
	ds_write2_b64 v0, v[98:99], v[100:101] offset0:8 offset1:10
	v_cvt_pk_bf16_f32 v98, v106, v107
	v_cvt_pk_bf16_f32 v99, v108, v109
	v_cvt_pk_bf16_f32 v100, v110, v111
	v_cvt_pk_bf16_f32 v101, v112, v113
	ds_write2_b64 v0, v[82:83], v[84:85] offset0:16 offset1:18
	v_cvt_pk_bf16_f32 v82, v90, v91
	v_cvt_pk_bf16_f32 v83, v92, v93
	v_cvt_pk_bf16_f32 v84, v94, v95
	v_cvt_pk_bf16_f32 v85, v96, v97
	ds_write2_b64 v0, v[50:51], v[52:53] offset0:24 offset1:26
	v_cvt_pk_bf16_f32 v50, v58, v59
	v_cvt_pk_bf16_f32 v51, v60, v61
	v_cvt_pk_bf16_f32 v52, v62, v63
	v_cvt_pk_bf16_f32 v53, v64, v65
	ds_write2_b64 v0, v[114:115], v[116:117] offset0:4 offset1:6
	ds_write2_b64 v0, v[98:99], v[100:101] offset0:12 offset1:14
	ds_write2_b64 v0, v[82:83], v[84:85] offset0:20 offset1:22
	ds_write2_b64 v0, v[50:51], v[52:53] offset0:28 offset1:30
	v_cvt_pk_bf16_f32 v50, v66, v67
	v_cvt_pk_bf16_f32 v51, v68, v69
	v_cvt_pk_bf16_f32 v52, v70, v71
	v_cvt_pk_bf16_f32 v53, v72, v73
	v_add_u32_e32 v0, 0x4000, v0
	v_cvt_pk_bf16_f32 v34, v34, v35
	v_cvt_pk_bf16_f32 v35, v36, v37
	v_cvt_pk_bf16_f32 v36, v38, v39
	v_cvt_pk_bf16_f32 v37, v40, v41
	v_cvt_pk_bf16_f32 v18, v18, v19
	v_cvt_pk_bf16_f32 v19, v20, v21
	v_cvt_pk_bf16_f32 v20, v22, v23
	v_cvt_pk_bf16_f32 v21, v24, v25
	v_cvt_pk_bf16_f32 v2, v2, v3
	v_cvt_pk_bf16_f32 v3, v4, v5
	v_cvt_pk_bf16_f32 v4, v6, v7
	v_cvt_pk_bf16_f32 v5, v8, v9
	ds_write2_b64 v0, v[50:51], v[52:53] offset0:64 offset1:66
	v_cvt_pk_bf16_f32 v50, v74, v75
	v_cvt_pk_bf16_f32 v51, v76, v77
	v_cvt_pk_bf16_f32 v52, v78, v79
	v_cvt_pk_bf16_f32 v53, v80, v81
	ds_write2_b64 v0, v[34:35], v[36:37] offset0:72 offset1:74
	v_cvt_pk_bf16_f32 v34, v42, v43
	v_cvt_pk_bf16_f32 v35, v44, v45
	v_cvt_pk_bf16_f32 v36, v46, v47
	v_cvt_pk_bf16_f32 v37, v48, v49
	ds_write2_b64 v0, v[18:19], v[20:21] offset0:80 offset1:82
	v_cvt_pk_bf16_f32 v18, v26, v27
	v_cvt_pk_bf16_f32 v19, v28, v29
	v_cvt_pk_bf16_f32 v20, v30, v31
	v_cvt_pk_bf16_f32 v21, v32, v33
	ds_write2_b64 v0, v[2:3], v[4:5] offset0:88 offset1:90
	v_cvt_pk_bf16_f32 v2, v10, v11
	v_cvt_pk_bf16_f32 v3, v12, v13
	v_cvt_pk_bf16_f32 v4, v14, v15
	v_cvt_pk_bf16_f32 v5, v16, v17
	s_lshl_b64 s[12:13], s[12:13], 1
	ds_write2_b64 v0, v[50:51], v[52:53] offset0:68 offset1:70
	ds_write2_b64 v0, v[34:35], v[36:37] offset0:76 offset1:78
	ds_write2_b64 v0, v[18:19], v[20:21] offset0:84 offset1:86
	ds_write2_b64 v0, v[2:3], v[4:5] offset0:92 offset1:94
	s_waitcnt vmcnt(0) lgkmcnt(0)
	s_barrier
; #define GAS __attribute__((address_space(1)))
;     ...
;   int tid2 = tid; asm volatile("" : "+v"(tid2));
;   if (EPI == 0) {
; #pragma unroll
;     for (int i = 0; i < 16; ++i) {
;       const int id = tid2 + 256 * i, r = id >> 5, c8 = (id & 31) * 8;
;       const u32x4 v = *(const u32x4*)(smem + r * 528 + c8 * 2);
;       *(GAS u32x4*)(ea.out + (size_t)(m0 + r) * ea.ldo + n0 + c8) = v;
;     }
	s_add_u32 s12, s14, s12
	v_lshlrev_b32_e32 v0, 4, v189
	v_and_b32_e32 v0, 0x1f0, v0
	s_addc_u32 s13, s15, s13
	v_add_u32_e32 v10, 16, v0
	v_lshl_add_u64 v[12:13], s[12:13], 0, v[0:1]
	v_ashrrev_i32_e32 v0, 5, v189
	v_mad_u64_u32 v[2:3], s[12:13], v0, s55, v[10:11]
	v_add_u32_e32 v0, s41, v0
	s_movk_i32 s10, 0x600
	v_mad_i64_i32 v[14:15], s[12:13], v0, s10, v[12:13]
	v_add_u32_e32 v0, 0x100, v189
	ds_read_b128 v[2:5], v2
	v_ashrrev_i32_e32 v0, 5, v0
	v_mad_u64_u32 v[6:7], s[12:13], v0, s55, v[10:11]
	ds_read_b128 v[6:9], v6
	v_add_u32_e32 v0, s41, v0
	s_waitcnt lgkmcnt(1)
	global_store_dwordx4 v[14:15], v[2:5], off
	v_readlane_b32 s44, v250, 17
	s_nop 0
	v_mad_i64_i32 v[2:3], s[12:13], v0, s10, v[12:13]
	v_add_u32_e32 v0, 0x200, v189
	v_ashrrev_i32_e32 v0, 5, v0
	s_waitcnt lgkmcnt(0)
	global_store_dwordx4 v[2:3], v[6:9], off
	v_mad_u64_u32 v[2:3], s[12:13], v0, s55, v[10:11]
	v_add_u32_e32 v0, s41, v0
	v_mad_i64_i32 v[14:15], s[12:13], v0, s10, v[12:13]
	v_add_u32_e32 v0, 0x300, v189
	ds_read_b128 v[2:5], v2
	v_ashrrev_i32_e32 v0, 5, v0
	v_mad_u64_u32 v[6:7], s[12:13], v0, s55, v[10:11]
	ds_read_b128 v[6:9], v6
	v_add_u32_e32 v0, s41, v0
	s_waitcnt lgkmcnt(1)
	global_store_dwordx4 v[14:15], v[2:5], off
	s_nop 1
	v_mad_i64_i32 v[2:3], s[12:13], v0, s10, v[12:13]
	v_add_u32_e32 v0, 0x400, v189
	v_ashrrev_i32_e32 v0, 5, v0
	s_waitcnt lgkmcnt(0)
	global_store_dwordx4 v[2:3], v[6:9], off
	v_mad_u64_u32 v[2:3], s[12:13], v0, s55, v[10:11]
	v_add_u32_e32 v0, s41, v0
	v_mad_i64_i32 v[14:15], s[12:13], v0, s10, v[12:13]
	v_add_u32_e32 v0, 0x500, v189
	ds_read_b128 v[2:5], v2
	v_ashrrev_i32_e32 v0, 5, v0
	v_mad_u64_u32 v[6:7], s[12:13], v0, s55, v[10:11]
	ds_read_b128 v[6:9], v6
	v_add_u32_e32 v0, s41, v0
	s_waitcnt lgkmcnt(1)
	global_store_dwordx4 v[14:15], v[2:5], off
	s_nop 1
	v_mad_i64_i32 v[2:3], s[12:13], v0, s10, v[12:13]
	v_add_u32_e32 v0, 0x600, v189
	v_ashrrev_i32_e32 v0, 5, v0
	s_waitcnt lgkmcnt(0)
	global_store_dwordx4 v[2:3], v[6:9], off
	v_mad_u64_u32 v[2:3], s[12:13], v0, s55, v[10:11]
	v_add_u32_e32 v0, s41, v0
	v_mad_i64_i32 v[14:15], s[12:13], v0, s10, v[12:13]
	v_add_u32_e32 v0, 0x700, v189
	ds_read_b128 v[2:5], v2
	v_ashrrev_i32_e32 v0, 5, v0
	v_mad_u64_u32 v[6:7], s[12:13], v0, s55, v[10:11]
	ds_read_b128 v[6:9], v6
	v_add_u32_e32 v0, s41, v0
	s_waitcnt lgkmcnt(1)
	global_store_dwordx4 v[14:15], v[2:5], off
	s_nop 1
	v_mad_i64_i32 v[2:3], s[12:13], v0, s10, v[12:13]
	v_add_u32_e32 v0, 0x800, v189
	v_ashrrev_i32_e32 v0, 5, v0
	s_waitcnt lgkmcnt(0)
	global_store_dwordx4 v[2:3], v[6:9], off
	v_mad_u64_u32 v[2:3], s[12:13], v0, s55, v[10:11]
	v_add_u32_e32 v0, s41, v0
	v_mad_i64_i32 v[14:15], s[12:13], v0, s10, v[12:13]
	v_add_u32_e32 v0, 0x900, v189
	ds_read_b128 v[2:5], v2
	v_ashrrev_i32_e32 v0, 5, v0
	v_mad_u64_u32 v[6:7], s[12:13], v0, s55, v[10:11]
	ds_read_b128 v[6:9], v6
	v_add_u32_e32 v0, s41, v0
	s_waitcnt lgkmcnt(1)
	global_store_dwordx4 v[14:15], v[2:5], off
	s_nop 1
	v_mad_i64_i32 v[2:3], s[12:13], v0, s10, v[12:13]
	v_add_u32_e32 v0, 0xa00, v189
	v_ashrrev_i32_e32 v0, 5, v0
	s_waitcnt lgkmcnt(0)
	global_store_dwordx4 v[2:3], v[6:9], off
	v_mad_u64_u32 v[2:3], s[12:13], v0, s55, v[10:11]
	v_add_u32_e32 v0, s41, v0
	v_mad_i64_i32 v[14:15], s[12:13], v0, s10, v[12:13]
	v_add_u32_e32 v0, 0xb00, v189
	ds_read_b128 v[2:5], v2
	v_ashrrev_i32_e32 v0, 5, v0
	v_mad_u64_u32 v[6:7], s[12:13], v0, s55, v[10:11]
	ds_read_b128 v[6:9], v6
	v_add_u32_e32 v0, s41, v0
	s_waitcnt lgkmcnt(1)
	global_store_dwordx4 v[14:15], v[2:5], off
	s_nop 1
	v_mad_i64_i32 v[2:3], s[12:13], v0, s10, v[12:13]
	v_add_u32_e32 v0, 0xc00, v189
	v_ashrrev_i32_e32 v0, 5, v0
	s_waitcnt lgkmcnt(0)
	global_store_dwordx4 v[2:3], v[6:9], off
	v_mad_u64_u32 v[2:3], s[12:13], v0, s55, v[10:11]
	v_add_u32_e32 v0, s41, v0
	v_mad_i64_i32 v[14:15], s[12:13], v0, s10, v[12:13]
	v_add_u32_e32 v0, 0xd00, v189
	ds_read_b128 v[2:5], v2
	v_ashrrev_i32_e32 v0, 5, v0
	v_mad_u64_u32 v[6:7], s[12:13], v0, s55, v[10:11]
	ds_read_b128 v[6:9], v6
	v_add_u32_e32 v0, s41, v0
	s_waitcnt lgkmcnt(1)
	global_store_dwordx4 v[14:15], v[2:5], off
	s_nop 1
	v_mad_i64_i32 v[2:3], s[12:13], v0, s10, v[12:13]
	v_add_u32_e32 v0, 0xe00, v189
	v_ashrrev_i32_e32 v0, 5, v0
	s_waitcnt lgkmcnt(0)
	global_store_dwordx4 v[2:3], v[6:9], off
	v_mad_u64_u32 v[2:3], s[12:13], v0, s55, v[10:11]
	v_add_u32_e32 v0, s41, v0
	v_mad_i64_i32 v[14:15], s[12:13], v0, s10, v[12:13]
	v_add_u32_e32 v0, 0xf00, v189
	v_ashrrev_i32_e32 v0, 5, v0
	ds_read_b128 v[2:5], v2
	v_mad_u64_u32 v[6:7], s[12:13], v0, s55, v[10:11]
	ds_read_b128 v[6:9], v6
	v_add_u32_e32 v0, s41, v0
	s_waitcnt lgkmcnt(1)
	global_store_dwordx4 v[14:15], v[2:5], off
	s_nop 1
	v_mad_i64_i32 v[2:3], s[12:13], v0, s10, v[12:13]
	s_waitcnt lgkmcnt(0)
	global_store_dwordx4 v[2:3], v[6:9], off
	s_barrier
	s_branch .LBB0_145

;   int tid = tid_in; asm volatile("" : "+v"(tid));
;   const int lane = tid & 63, wid = __builtin_amdgcn_readfirstlane(tid >> 6), wr = wid >> 1, wc = wid & 1;
;   const int m0 = mt * 128, n0 = nt * 256;
;   const int r = lane & 31, h = lane >> 5, key = (r >> 2) & 3;
;   constexpr int STG = 24576;
;   const int rowl = lane >> 2, cch = (lane & 3) ^ ((lane >> 4) & 3);
;   const unsigned voffA = (unsigned)(rowl * lda * 2 + cch * 16), voffB = (unsigned)(rowl * K * 2 + cch * 16);
;   const char* Abase = (const char*)(A + (size_t)m0 * lda) + (size_t)(wid * 2) * 32 * lda;
;   const char* Bbase = (const char*)(Bt + (size_t)n0 * K) + (size_t)(wid * 4) * 32 * K;
;   const size_t ablk = (size_t)32 * lda, bblk = (size_t)32 * K;
;   LAS char* lds = (LAS char*)smem;
;   LAS char* ldsA = lds + (wid * 2) * 1024;
;   LAS char* ldsB = lds + 8192 + (wid * 4) * 1024;
;     ...
;   const int x0 = ((0 + h) ^ key) * 16, x1 = ((2 + h) ^ key) * 16;
;   const int a_rd = (wr * 64 + r) * 64, b_rd = 8192 + (wc * 128 + r) * 64;
;   f32x16 acc[2][4];
; #pragma unroll
;   for (int i = 0; i < 2; ++i)
; #pragma unroll
;     for (int j = 0; j < 4; ++j)
; #pragma unroll
;       for (int e = 0; e < 16; ++e) acc[i][j][e] = 0.f;
;   const int nk = K >> 5;
;   DMA_STEP_(0, 0);
;   DMA_STEP_(1, STG);
;   asm volatile("s_waitcnt vmcnt(6)" ::: "memory");
;   __builtin_amdgcn_s_barrier();
;   asm volatile("" ::: "memory");
;   int s0 = 0, s2 = 2 * STG;
;   for (int kt = 0; kt < nk; ++kt) {
;     const int kn = (kt + 2 < nk) ? (kt + 2) : (nk - 1);
;     const LAS char* cur = lds + s0;
;     bf16x8 af[2][2], bfr[2][4];
; #pragma unroll
;     for (int kk = 0; kk < 2; ++kk) {
;       const int xo = kk ? x1 : x0;
;       af[kk][0] = *(const LAS bf16x8*)(cur + a_rd + xo);
;       bfr[kk][0] = *(const LAS bf16x8*)(cur + b_rd + xo);
;       bfr[kk][1] = *(const LAS bf16x8*)(cur + b_rd + 2048 + xo);
;       af[kk][1] = *(const LAS bf16x8*)(cur + a_rd + 2048 + xo);
;       bfr[kk][2] = *(const LAS bf16x8*)(cur + b_rd + 4096 + xo);
;       bfr[kk][3] = *(const LAS bf16x8*)(cur + b_rd + 6144 + xo);
;     }
;     DMA_STEP_(kn, s2);
; #pragma unroll
;     for (int kk = 0; kk < 2; ++kk) {
;       acc[0][0] = mfma32(bfr[kk][0], af[kk][0], acc[0][0]); acc[0][1] = mfma32(bfr[kk][1], af[kk][0], acc[0][1]);
;       acc[1][0] = mfma32(bfr[kk][0], af[kk][1], acc[1][0]); acc[1][1] = mfma32(bfr[kk][1], af[kk][1], acc[1][1]);
.LBB0_183:
	s_mul_hi_i32 s10, s20, 0x38e38e39
	s_lshr_b32 s11, s10, 31
	s_ashr_i32 s10, s10, 4
	v_mov_b32_e32 v189, v188
	s_add_i32 s10, s10, s11
	v_readlane_b32 s12, v252, 18
	s_mul_i32 s11, s10, 0xffffffb8
	v_readfirstlane_b32 s21, v189
	s_lshl_b32 s10, s10, s12
	v_readlane_b32 s12, v252, 41
	s_ashr_i32 s44, s21, 6
	s_add_i32 s10, s10, s12
	s_lshl_b32 s12, s20, 7
	s_lshl_b32 s22, s44, 1
	s_add_i32 s11, s11, s20
	s_lshl_b32 s10, s10, 10
	s_and_b32 s12, s12, 0x380
	s_ashr_i32 s23, s22, 31
	s_or_b32 s12, s10, s12
	s_lshl_b32 s10, s11, 5
	s_lshl_b64 s[28:29], s[22:23], 10
	s_lshl_b32 s22, s44, 2
	s_ashr_i32 s11, s21, 1
	s_and_b32 s14, s10, 0xffffff00
	v_and_b32_e32 v0, 31, v189
	s_ashr_i32 s23, s22, 31
	s_lshl_b32 s10, s44, 12
	s_andn2_b32 s11, s11, 63
	v_lshlrev_b32_e32 v2, 4, v189
	s_ashr_i32 s13, s12, 31
	s_lshl_b64 s[40:41], s[22:23], 10
	s_add_i32 s22, s10, 16
	v_or_b32_e32 v197, s11, v0
	s_lshl_b32 s11, s44, 7
	v_bitop3_b32 v2, v2, 48, v189 bitop3:0x48
	v_lshlrev_b32_e32 v3, 9, v189
	s_ashr_i32 s15, s14, 31
	s_add_i32 s10, s22, 0x2000
	s_and_b32 s21, s11, 0x80
	s_movk_i32 s11, 0x7800
	s_lshl_b64 s[42:43], s[12:13], 6
	v_or_b32_e32 v4, s21, v0
	v_and_or_b32 v0, v3, s11, v2
	v_lshlrev_b32_e32 v10, 4, v189
	v_and_b32_e32 v10, 0x3c0, v10
	v_or_b32_e32 v10, v10, v2
	v_mov_b32_e32 v11, 0
	s_add_u32 s11, s18, s42
	s_addc_u32 s13, s19, s43
	s_add_u32 s28, s11, s28
	s_addc_u32 s29, s13, s29
	s_lshl_b64 s[42:43], s[14:15], 6
	v_readlane_b32 s46, v250, 18
	v_readlane_b32 s47, v250, 19
	s_add_u32 s11, s46, s42
	s_addc_u32 s13, s47, s43
	s_add_u32 s40, s11, s40
	s_addc_u32 s41, s13, s41
	s_lshl_b32 s11, s44, 11
	s_sub_i32 s13, s22, s11
	v_lshl_add_u64 v[192:193], s[28:29], 0, v[10:11]
	s_mov_b32 m0, s13
	s_nop 0
	global_load_lds_dwordx4 v[192:193], off
	global_load_lds_dwordx4 v[192:193], off offset:1024
	v_lshl_add_u64 v[194:195], s[40:41], 0, v[10:11]
	s_mov_b32 m0, s10
	s_nop 0
	global_load_lds_dwordx4 v[194:195], off
	global_load_lds_dwordx4 v[194:195], off offset:1024
	global_load_lds_dwordx4 v[194:195], off offset:2048
	global_load_lds_dwordx4 v[194:195], off offset:3072
	s_mov_b64 s[10:11], 0x10000
	s_mov_b64 s[10:11], 0x18000
	s_mov_b64 s[10:11], 0x8040
	s_add_i32 m0, s13, 0x6000
	s_mov_b32 vcc_lo, 0x480000
	s_mov_b32 vcc_hi, 0
	v_lshl_add_u64 v[2:3], v[192:193], 0, vcc
	global_load_lds_dwordx4 v[2:3], off
	global_load_lds_dwordx4 v[2:3], off offset:1024
	v_bfe_u32 v196, v189, 5, 1
	s_add_i32 m0, s22, 0x8000
	s_mov_b32 s100, 0x24000
	v_lshl_add_u64 v[2:3], v[194:195], 0, s[100:101]
	global_load_lds_dwordx4 v[2:3], off
	global_load_lds_dwordx4 v[2:3], off offset:1024
	global_load_lds_dwordx4 v[2:3], off offset:2048
	global_load_lds_dwordx4 v[2:3], off offset:3072
	s_mov_b64 s[10:11], 0x10040
	s_mov_b64 s[10:11], 0x18040
	v_lshlrev_b32_e32 v218, 6, v4
	v_bfe_u32 v4, v189, 2, 2
	v_lshrrev_b32_e32 v5, 5, v189
	s_lshl_b32 s100, s100, 1
	v_lshl_add_u64 v[194:195], v[194:195], 0, s[100:101]
	s_lshl_b32 vcc_lo, vcc_lo, 1
	v_lshl_add_u64 v[192:193], v[192:193], 0, vcc
	s_waitcnt vmcnt(6)
	s_barrier
	v_bitop3_b32 v2, v196, v4, 2 bitop3:0x36
	v_bitop3_b32 v0, v5, v4, 1 bitop3:0x6c
	v_lshlrev_b32_e32 v220, 4, v2
	v_mov_b32_e32 v2, 0
	v_lshlrev_b32_e32 v219, 6, v197
	v_lshlrev_b32_e32 v0, 4, v0
	s_mov_b32 s28, 0xc000
	s_mov_b32 s23, 0
	s_mov_b32 s29, 0
	v_readfirstlane_b32 vcc_lo, v192
	v_readfirstlane_b32 vcc_hi, v193
	v_readfirstlane_b32 s100, v194
	v_readfirstlane_b32 s101, v195
	s_sub_u32 vcc_lo, vcc_lo, 0x100000
	s_subb_u32 vcc_hi, vcc_hi, 0
	s_sub_u32 s100, s100, 0x100000
	s_subb_u32 s101, s101, 0
	v_subrev_u32_e32 v238, vcc_lo, v192
	v_subrev_u32_e32 v239, s100, v194
	v_add3_u32 v226, v219, v0, 16
	v_add3_u32 v227, v218, v0, 16
	v_add3_u32 v228, v219, v220, 16
	v_add3_u32 v229, v218, v220, 16
	ds_read_b128 v[154:157], v226 offset:0
	ds_read_b128 v[182:185], v227 offset:8192
	ds_read_b128 v[178:181], v227 offset:10240
	ds_read_b128 v[158:161], v226 offset:2048
	ds_read_b128 v[174:177], v227 offset:12288
	ds_read_b128 v[170:173], v227 offset:14336
	s_setprio 1
	ds_read_b128 v[138:141], v228 offset:0
	ds_read_b128 v[162:165], v229 offset:8192
	ds_read_b128 v[166:169], v229 offset:10240
	ds_read_b128 v[142:145], v228 offset:2048
	ds_read_b128 v[146:149], v229 offset:12288
	ds_read_b128 v[150:153], v229 offset:14336
	s_add_i32 m0, s13, 0xc000
	s_waitcnt lgkmcnt(6)
	v_mfma_f32_32x32x16_bf16 v[114:129], v[182:185], v[154:157], 0
	global_load_lds_dwordx4 v238, vcc
	v_mfma_f32_32x32x16_bf16 v[98:113], v[178:181], v[154:157], 0
	global_load_lds_dwordx4 v238, vcc offset:1024
	s_add_i32 m0, s22, 0xe000
	s_add_u32 vcc_lo, vcc_lo, 0x480000
	s_addc_u32 vcc_hi, vcc_hi, 0
	v_mfma_f32_32x32x16_bf16 v[66:81], v[182:185], v[158:161], 0
	global_load_lds_dwordx4 v239, s[100:101]
	v_mfma_f32_32x32x16_bf16 v[34:49], v[178:181], v[158:161], 0
	global_load_lds_dwordx4 v239, s[100:101] offset:1024
	v_mfma_f32_32x32x16_bf16 v[82:97], v[174:177], v[154:157], 0
	global_load_lds_dwordx4 v239, s[100:101] offset:2048
	v_mfma_f32_32x32x16_bf16 v[50:65], v[170:173], v[154:157], 0
	global_load_lds_dwordx4 v239, s[100:101] offset:3072
	s_add_u32 s100, s100, 0x24000
	s_addc_u32 s101, s101, 0
	v_mfma_f32_32x32x16_bf16 v[18:33], v[174:177], v[158:161], 0
	v_mfma_f32_32x32x16_bf16 v[2:17], v[170:173], v[158:161], 0
	s_waitcnt vmcnt(6) lgkmcnt(0)
	s_barrier
; #define LAS __attribute__((address_space(3)))
; DI f32x16 mfma32(bf16x8 a, bf16x8 b, f32x16 c) { return __builtin_amdgcn_mfma_f32_32x32x16_bf16(a, b, c, 0, 0, 0); }
;     ...
;   for (int kt = 0; kt < nk; ++kt) {
;     const int kn = (kt + 2 < nk) ? (kt + 2) : (nk - 1);
;     const LAS char* cur = lds + s0;
;     bf16x8 af[2][2], bfr[2][4];
; #pragma unroll
;     for (int kk = 0; kk < 2; ++kk) {
;       const int xo = kk ? x1 : x0;
;       af[kk][0] = *(const LAS bf16x8*)(cur + a_rd + xo);
;       bfr[kk][0] = *(const LAS bf16x8*)(cur + b_rd + xo);
;       bfr[kk][1] = *(const LAS bf16x8*)(cur + b_rd + 2048 + xo);
;       af[kk][1] = *(const LAS bf16x8*)(cur + a_rd + 2048 + xo);
;       bfr[kk][2] = *(const LAS bf16x8*)(cur + b_rd + 4096 + xo);
;       bfr[kk][3] = *(const LAS bf16x8*)(cur + b_rd + 6144 + xo);
;     }
;     DMA_STEP_(kn, s2);
; #pragma unroll
;     for (int kk = 0; kk < 2; ++kk) {
;       acc[0][0] = mfma32(bfr[kk][0], af[kk][0], acc[0][0]); acc[0][1] = mfma32(bfr[kk][1], af[kk][0], acc[0][1]);
;       acc[1][0] = mfma32(bfr[kk][0], af[kk][1], acc[1][0]); acc[1][1] = mfma32(bfr[kk][1], af[kk][1], acc[1][1]);
;       acc[0][2] = mfma32(bfr[kk][2], af[kk][0], acc[0][2]); acc[0][3] = mfma32(bfr[kk][3], af[kk][0], acc[0][3]);
;       acc[1][2] = mfma32(bfr[kk][2], af[kk][1], acc[1][2]); acc[1][3] = mfma32(bfr[kk][3], af[kk][1], acc[1][3]);
;     }
;     __builtin_amdgcn_sched_group_barrier(0x100, 12, 0);
;     __builtin_amdgcn_sched_group_barrier(0x010, 6, 0);
;     __builtin_amdgcn_sched_group_barrier(0x008, 16, 0);
;     asm volatile("s_waitcnt vmcnt(6) lgkmcnt(0)" ::: "memory");
;     __builtin_amdgcn_s_barrier();
;     asm volatile("" ::: "memory");
;     s0 = (s0 == 2 * STG) ? 0 : s0 + STG;
;     s2 = (s2 == 2 * STG) ? 0 : s2 + STG;
;   }
	ds_read_b128 v[154:157], v226 offset:24576
	ds_read_b128 v[182:185], v227 offset:32768
	ds_read_b128 v[178:181], v227 offset:34816
	ds_read_b128 v[158:161], v226 offset:26624
	ds_read_b128 v[174:177], v227 offset:36864
	ds_read_b128 v[170:173], v227 offset:38912
	v_mfma_f32_32x32x16_bf16 v[114:129], v[162:165], v[138:141], v[114:129]
	v_mfma_f32_32x32x16_bf16 v[98:113], v[166:169], v[138:141], v[98:113]
	v_mfma_f32_32x32x16_bf16 v[66:81], v[162:165], v[142:145], v[66:81]
	v_mfma_f32_32x32x16_bf16 v[34:49], v[166:169], v[142:145], v[34:49]
	v_mfma_f32_32x32x16_bf16 v[82:97], v[146:149], v[138:141], v[82:97]
	v_mfma_f32_32x32x16_bf16 v[50:65], v[150:153], v[138:141], v[50:65]
	v_mfma_f32_32x32x16_bf16 v[18:33], v[146:149], v[142:145], v[18:33]
	v_mfma_f32_32x32x16_bf16 v[2:17], v[150:153], v[142:145], v[2:17]
	ds_read_b128 v[138:141], v228 offset:24576
	ds_read_b128 v[162:165], v229 offset:32768
	ds_read_b128 v[166:169], v229 offset:34816
	ds_read_b128 v[142:145], v228 offset:26624
	ds_read_b128 v[146:149], v229 offset:36864
	ds_read_b128 v[150:153], v229 offset:38912
	s_add_i32 m0, s13, 0x0
	s_waitcnt lgkmcnt(6)
	v_mfma_f32_32x32x16_bf16 v[114:129], v[182:185], v[154:157], v[114:129]
	global_load_lds_dwordx4 v238, vcc
	v_mfma_f32_32x32x16_bf16 v[98:113], v[178:181], v[154:157], v[98:113]
	global_load_lds_dwordx4 v238, vcc offset:1024
	s_add_i32 m0, s22, 0x2000
	s_add_u32 vcc_lo, vcc_lo, 0x480000
	s_addc_u32 vcc_hi, vcc_hi, 0
	v_mfma_f32_32x32x16_bf16 v[66:81], v[182:185], v[158:161], v[66:81]
	global_load_lds_dwordx4 v239, s[100:101]
	v_mfma_f32_32x32x16_bf16 v[34:49], v[178:181], v[158:161], v[34:49]
	global_load_lds_dwordx4 v239, s[100:101] offset:1024
	v_mfma_f32_32x32x16_bf16 v[82:97], v[174:177], v[154:157], v[82:97]
	global_load_lds_dwordx4 v239, s[100:101] offset:2048
	v_mfma_f32_32x32x16_bf16 v[50:65], v[170:173], v[154:157], v[50:65]
	global_load_lds_dwordx4 v239, s[100:101] offset:3072
	s_add_u32 s100, s100, 0x24000
	s_addc_u32 s101, s101, 0
	v_mfma_f32_32x32x16_bf16 v[18:33], v[174:177], v[158:161], v[18:33]
	v_mfma_f32_32x32x16_bf16 v[2:17], v[170:173], v[158:161], v[2:17]
	s_waitcnt vmcnt(6) lgkmcnt(0)
	s_barrier
	ds_read_b128 v[154:157], v226 offset:49152
	ds_read_b128 v[182:185], v227 offset:57344
	ds_read_b128 v[178:181], v227 offset:59392
	ds_read_b128 v[158:161], v226 offset:51200
	ds_read_b128 v[174:177], v227 offset:61440
	ds_read_b128 v[170:173], v227 offset:63488
	v_mfma_f32_32x32x16_bf16 v[114:129], v[162:165], v[138:141], v[114:129]
	v_mfma_f32_32x32x16_bf16 v[98:113], v[166:169], v[138:141], v[98:113]
	v_mfma_f32_32x32x16_bf16 v[66:81], v[162:165], v[142:145], v[66:81]
	v_mfma_f32_32x32x16_bf16 v[34:49], v[166:169], v[142:145], v[34:49]
	v_mfma_f32_32x32x16_bf16 v[82:97], v[146:149], v[138:141], v[82:97]
	v_mfma_f32_32x32x16_bf16 v[50:65], v[150:153], v[138:141], v[50:65]
	v_mfma_f32_32x32x16_bf16 v[18:33], v[146:149], v[142:145], v[18:33]
	v_mfma_f32_32x32x16_bf16 v[2:17], v[150:153], v[142:145], v[2:17]
	ds_read_b128 v[138:141], v228 offset:49152
	ds_read_b128 v[162:165], v229 offset:57344
	ds_read_b128 v[166:169], v229 offset:59392
	ds_read_b128 v[142:145], v228 offset:51200
	ds_read_b128 v[146:149], v229 offset:61440
	ds_read_b128 v[150:153], v229 offset:63488
	s_add_i32 m0, s13, 0x6000
	s_waitcnt lgkmcnt(6)
	v_mfma_f32_32x32x16_bf16 v[114:129], v[182:185], v[154:157], v[114:129]
	global_load_lds_dwordx4 v238, vcc
	v_mfma_f32_32x32x16_bf16 v[98:113], v[178:181], v[154:157], v[98:113]
	global_load_lds_dwordx4 v238, vcc offset:1024
	s_add_i32 m0, s22, 0x8000
	s_add_u32 vcc_lo, vcc_lo, 0x480000
	s_addc_u32 vcc_hi, vcc_hi, 0
	v_mfma_f32_32x32x16_bf16 v[66:81], v[182:185], v[158:161], v[66:81]
	global_load_lds_dwordx4 v239, s[100:101]
	v_mfma_f32_32x32x16_bf16 v[34:49], v[178:181], v[158:161], v[34:49]
	global_load_lds_dwordx4 v239, s[100:101] offset:1024
	v_mfma_f32_32x32x16_bf16 v[82:97], v[174:177], v[154:157], v[82:97]
	global_load_lds_dwordx4 v239, s[100:101] offset:2048
	v_mfma_f32_32x32x16_bf16 v[50:65], v[170:173], v[154:157], v[50:65]
	global_load_lds_dwordx4 v239, s[100:101] offset:3072
	s_add_u32 s100, s100, 0x24000
	s_addc_u32 s101, s101, 0
	v_mfma_f32_32x32x16_bf16 v[18:33], v[174:177], v[158:161], v[18:33]
	v_mfma_f32_32x32x16_bf16 v[2:17], v[170:173], v[158:161], v[2:17]
	s_waitcnt vmcnt(6) lgkmcnt(0)
	s_barrier
	ds_read_b128 v[154:157], v226 offset:0
	ds_read_b128 v[182:185], v227 offset:8192
	ds_read_b128 v[178:181], v227 offset:10240
	ds_read_b128 v[158:161], v226 offset:2048
	ds_read_b128 v[174:177], v227 offset:12288
	ds_read_b128 v[170:173], v227 offset:14336
	v_mfma_f32_32x32x16_bf16 v[114:129], v[162:165], v[138:141], v[114:129]
	v_mfma_f32_32x32x16_bf16 v[98:113], v[166:169], v[138:141], v[98:113]
	v_mfma_f32_32x32x16_bf16 v[66:81], v[162:165], v[142:145], v[66:81]
	v_mfma_f32_32x32x16_bf16 v[34:49], v[166:169], v[142:145], v[34:49]
	v_mfma_f32_32x32x16_bf16 v[82:97], v[146:149], v[138:141], v[82:97]
	v_mfma_f32_32x32x16_bf16 v[50:65], v[150:153], v[138:141], v[50:65]
	v_mfma_f32_32x32x16_bf16 v[18:33], v[146:149], v[142:145], v[18:33]
	v_mfma_f32_32x32x16_bf16 v[2:17], v[150:153], v[142:145], v[2:17]
	ds_read_b128 v[138:141], v228 offset:0
	ds_read_b128 v[162:165], v229 offset:8192
	ds_read_b128 v[166:169], v229 offset:10240
	ds_read_b128 v[142:145], v228 offset:2048
	ds_read_b128 v[146:149], v229 offset:12288
	ds_read_b128 v[150:153], v229 offset:14336
	s_add_i32 m0, s13, 0xc000
	s_waitcnt lgkmcnt(6)
	v_mfma_f32_32x32x16_bf16 v[114:129], v[182:185], v[154:157], v[114:129]
	global_load_lds_dwordx4 v238, vcc
	v_mfma_f32_32x32x16_bf16 v[98:113], v[178:181], v[154:157], v[98:113]
	global_load_lds_dwordx4 v238, vcc offset:1024
	s_add_i32 m0, s22, 0xe000
	s_add_u32 vcc_lo, vcc_lo, 0x480000
	s_addc_u32 vcc_hi, vcc_hi, 0
	v_mfma_f32_32x32x16_bf16 v[66:81], v[182:185], v[158:161], v[66:81]
	global_load_lds_dwordx4 v239, s[100:101]
	v_mfma_f32_32x32x16_bf16 v[34:49], v[178:181], v[158:161], v[34:49]
	global_load_lds_dwordx4 v239, s[100:101] offset:1024
	v_mfma_f32_32x32x16_bf16 v[82:97], v[174:177], v[154:157], v[82:97]
	global_load_lds_dwordx4 v239, s[100:101] offset:2048
	v_mfma_f32_32x32x16_bf16 v[50:65], v[170:173], v[154:157], v[50:65]
	global_load_lds_dwordx4 v239, s[100:101] offset:3072
	s_add_u32 s100, s100, 0x24000
	s_addc_u32 s101, s101, 0
	v_mfma_f32_32x32x16_bf16 v[18:33], v[174:177], v[158:161], v[18:33]
	v_mfma_f32_32x32x16_bf16 v[2:17], v[170:173], v[158:161], v[2:17]
	s_waitcnt vmcnt(6) lgkmcnt(0)
	s_barrier
; #define LAS __attribute__((address_space(3)))
; DI f32x16 mfma32(bf16x8 a, bf16x8 b, f32x16 c) { return __builtin_amdgcn_mfma_f32_32x32x16_bf16(a, b, c, 0, 0, 0); }
;     ...
;   for (int kt = 0; kt < nk; ++kt) {
;     const int kn = (kt + 2 < nk) ? (kt + 2) : (nk - 1);
;     const LAS char* cur = lds + s0;
;     bf16x8 af[2][2], bfr[2][4];
; #pragma unroll
;     for (int kk = 0; kk < 2; ++kk) {
;       const int xo = kk ? x1 : x0;
;       af[kk][0] = *(const LAS bf16x8*)(cur + a_rd + xo);
;       bfr[kk][0] = *(const LAS bf16x8*)(cur + b_rd + xo);
;       bfr[kk][1] = *(const LAS bf16x8*)(cur + b_rd + 2048 + xo);
;       af[kk][1] = *(const LAS bf16x8*)(cur + a_rd + 2048 + xo);
;       bfr[kk][2] = *(const LAS bf16x8*)(cur + b_rd + 4096 + xo);
;       bfr[kk][3] = *(const LAS bf16x8*)(cur + b_rd + 6144 + xo);
;     }
;     DMA_STEP_(kn, s2);
; #pragma unroll
;     for (int kk = 0; kk < 2; ++kk) {
;       acc[0][0] = mfma32(bfr[kk][0], af[kk][0], acc[0][0]); acc[0][1] = mfma32(bfr[kk][1], af[kk][0], acc[0][1]);
;       acc[1][0] = mfma32(bfr[kk][0], af[kk][1], acc[1][0]); acc[1][1] = mfma32(bfr[kk][1], af[kk][1], acc[1][1]);
;       acc[0][2] = mfma32(bfr[kk][2], af[kk][0], acc[0][2]); acc[0][3] = mfma32(bfr[kk][3], af[kk][0], acc[0][3]);
;       acc[1][2] = mfma32(bfr[kk][2], af[kk][1], acc[1][2]); acc[1][3] = mfma32(bfr[kk][3], af[kk][1], acc[1][3]);
;     }
;     __builtin_amdgcn_sched_group_barrier(0x100, 12, 0);
;     __builtin_amdgcn_sched_group_barrier(0x010, 6, 0);
;     __builtin_amdgcn_sched_group_barrier(0x008, 16, 0);
;     asm volatile("s_waitcnt vmcnt(6) lgkmcnt(0)" ::: "memory");
;     __builtin_amdgcn_s_barrier();
;     asm volatile("" ::: "memory");
;     s0 = (s0 == 2 * STG) ? 0 : s0 + STG;
;     s2 = (s2 == 2 * STG) ? 0 : s2 + STG;
;   }
	ds_read_b128 v[154:157], v226 offset:24576
	ds_read_b128 v[182:185], v227 offset:32768
	ds_read_b128 v[178:181], v227 offset:34816
	ds_read_b128 v[158:161], v226 offset:26624
	ds_read_b128 v[174:177], v227 offset:36864
	ds_read_b128 v[170:173], v227 offset:38912
	v_mfma_f32_32x32x16_bf16 v[114:129], v[162:165], v[138:141], v[114:129]
	v_mfma_f32_32x32x16_bf16 v[98:113], v[166:169], v[138:141], v[98:113]
	v_mfma_f32_32x32x16_bf16 v[66:81], v[162:165], v[142:145], v[66:81]
	v_mfma_f32_32x32x16_bf16 v[34:49], v[166:169], v[142:145], v[34:49]
	v_mfma_f32_32x32x16_bf16 v[82:97], v[146:149], v[138:141], v[82:97]
	v_mfma_f32_32x32x16_bf16 v[50:65], v[150:153], v[138:141], v[50:65]
	v_mfma_f32_32x32x16_bf16 v[18:33], v[146:149], v[142:145], v[18:33]
	v_mfma_f32_32x32x16_bf16 v[2:17], v[150:153], v[142:145], v[2:17]
	ds_read_b128 v[138:141], v228 offset:24576
	ds_read_b128 v[162:165], v229 offset:32768
	ds_read_b128 v[166:169], v229 offset:34816
	ds_read_b128 v[142:145], v228 offset:26624
	ds_read_b128 v[146:149], v229 offset:36864
	ds_read_b128 v[150:153], v229 offset:38912
	s_add_i32 m0, s13, 0x0
	s_waitcnt lgkmcnt(6)
	v_mfma_f32_32x32x16_bf16 v[114:129], v[182:185], v[154:157], v[114:129]
	global_load_lds_dwordx4 v238, vcc
	v_mfma_f32_32x32x16_bf16 v[98:113], v[178:181], v[154:157], v[98:113]
	global_load_lds_dwordx4 v238, vcc offset:1024
	s_add_i32 m0, s22, 0x2000
	s_add_u32 vcc_lo, vcc_lo, 0x480000
	s_addc_u32 vcc_hi, vcc_hi, 0
	v_mfma_f32_32x32x16_bf16 v[66:81], v[182:185], v[158:161], v[66:81]
	global_load_lds_dwordx4 v239, s[100:101]
	v_mfma_f32_32x32x16_bf16 v[34:49], v[178:181], v[158:161], v[34:49]
	global_load_lds_dwordx4 v239, s[100:101] offset:1024
	v_mfma_f32_32x32x16_bf16 v[82:97], v[174:177], v[154:157], v[82:97]
	global_load_lds_dwordx4 v239, s[100:101] offset:2048
	v_mfma_f32_32x32x16_bf16 v[50:65], v[170:173], v[154:157], v[50:65]
	global_load_lds_dwordx4 v239, s[100:101] offset:3072
	s_add_u32 s100, s100, 0x24000
	s_addc_u32 s101, s101, 0
	v_mfma_f32_32x32x16_bf16 v[18:33], v[174:177], v[158:161], v[18:33]
	v_mfma_f32_32x32x16_bf16 v[2:17], v[170:173], v[158:161], v[2:17]
	s_waitcnt vmcnt(6) lgkmcnt(0)
	s_barrier
	ds_read_b128 v[154:157], v226 offset:49152
	ds_read_b128 v[182:185], v227 offset:57344
	ds_read_b128 v[178:181], v227 offset:59392
	ds_read_b128 v[158:161], v226 offset:51200
	ds_read_b128 v[174:177], v227 offset:61440
	ds_read_b128 v[170:173], v227 offset:63488
	v_mfma_f32_32x32x16_bf16 v[114:129], v[162:165], v[138:141], v[114:129]
	v_mfma_f32_32x32x16_bf16 v[98:113], v[166:169], v[138:141], v[98:113]
	v_mfma_f32_32x32x16_bf16 v[66:81], v[162:165], v[142:145], v[66:81]
	v_mfma_f32_32x32x16_bf16 v[34:49], v[166:169], v[142:145], v[34:49]
	v_mfma_f32_32x32x16_bf16 v[82:97], v[146:149], v[138:141], v[82:97]
	v_mfma_f32_32x32x16_bf16 v[50:65], v[150:153], v[138:141], v[50:65]
	v_mfma_f32_32x32x16_bf16 v[18:33], v[146:149], v[142:145], v[18:33]
	v_mfma_f32_32x32x16_bf16 v[2:17], v[150:153], v[142:145], v[2:17]
	ds_read_b128 v[138:141], v228 offset:49152
	ds_read_b128 v[162:165], v229 offset:57344
	ds_read_b128 v[166:169], v229 offset:59392
	ds_read_b128 v[142:145], v228 offset:51200
	ds_read_b128 v[146:149], v229 offset:61440
	ds_read_b128 v[150:153], v229 offset:63488
	s_add_i32 m0, s13, 0x6000
	s_waitcnt lgkmcnt(6)
	v_mfma_f32_32x32x16_bf16 v[114:129], v[182:185], v[154:157], v[114:129]
	global_load_lds_dwordx4 v238, vcc
	v_mfma_f32_32x32x16_bf16 v[98:113], v[178:181], v[154:157], v[98:113]
	global_load_lds_dwordx4 v238, vcc offset:1024
	s_add_i32 m0, s22, 0x8000
	s_add_u32 vcc_lo, vcc_lo, 0x480000
	s_addc_u32 vcc_hi, vcc_hi, 0
	v_mfma_f32_32x32x16_bf16 v[66:81], v[182:185], v[158:161], v[66:81]
	global_load_lds_dwordx4 v239, s[100:101]
	v_mfma_f32_32x32x16_bf16 v[34:49], v[178:181], v[158:161], v[34:49]
	global_load_lds_dwordx4 v239, s[100:101] offset:1024
	v_mfma_f32_32x32x16_bf16 v[82:97], v[174:177], v[154:157], v[82:97]
	global_load_lds_dwordx4 v239, s[100:101] offset:2048
	v_mfma_f32_32x32x16_bf16 v[50:65], v[170:173], v[154:157], v[50:65]
	global_load_lds_dwordx4 v239, s[100:101] offset:3072
	s_add_u32 s100, s100, 0x24000
	s_addc_u32 s101, s101, 0
	v_mfma_f32_32x32x16_bf16 v[18:33], v[174:177], v[158:161], v[18:33]
	v_mfma_f32_32x32x16_bf16 v[2:17], v[170:173], v[158:161], v[2:17]
	s_waitcnt vmcnt(6) lgkmcnt(0)
	s_barrier
	ds_read_b128 v[154:157], v226 offset:0
	ds_read_b128 v[182:185], v227 offset:8192
	ds_read_b128 v[178:181], v227 offset:10240
	ds_read_b128 v[158:161], v226 offset:2048
	ds_read_b128 v[174:177], v227 offset:12288
	ds_read_b128 v[170:173], v227 offset:14336
	v_mfma_f32_32x32x16_bf16 v[114:129], v[162:165], v[138:141], v[114:129]
	v_mfma_f32_32x32x16_bf16 v[98:113], v[166:169], v[138:141], v[98:113]
	v_mfma_f32_32x32x16_bf16 v[66:81], v[162:165], v[142:145], v[66:81]
	v_mfma_f32_32x32x16_bf16 v[34:49], v[166:169], v[142:145], v[34:49]
	v_mfma_f32_32x32x16_bf16 v[82:97], v[146:149], v[138:141], v[82:97]
	v_mfma_f32_32x32x16_bf16 v[50:65], v[150:153], v[138:141], v[50:65]
	v_mfma_f32_32x32x16_bf16 v[18:33], v[146:149], v[142:145], v[18:33]
	v_mfma_f32_32x32x16_bf16 v[2:17], v[150:153], v[142:145], v[2:17]
	s_add_i32 s23, s23, 6

;   int tid = tid_in; asm volatile("" : "+v"(tid));
;   const int lane = tid & 63, wid = __builtin_amdgcn_readfirstlane(tid >> 6), wr = wid >> 1, wc = wid & 1;
;   const int m0 = mt * 128, n0 = nt * 256;
;   const int r = lane & 31, h = lane >> 5, key = (r >> 2) & 3;
;   constexpr int STG = 24576;
;   const int rowl = lane >> 2, cch = (lane & 3) ^ ((lane >> 4) & 3);
;   const unsigned voffA = (unsigned)(rowl * lda * 2 + cch * 16), voffB = (unsigned)(rowl * K * 2 + cch * 16);
;   const char* Abase = (const char*)(A + (size_t)m0 * lda) + (size_t)(wid * 2) * 32 * lda;
;   const char* Bbase = (const char*)(Bt + (size_t)n0 * K) + (size_t)(wid * 4) * 32 * K;
;   const size_t ablk = (size_t)32 * lda, bblk = (size_t)32 * K;
;   LAS char* lds = (LAS char*)smem;
;   LAS char* ldsA = lds + (wid * 2) * 1024;
;   LAS char* ldsB = lds + 8192 + (wid * 4) * 1024;
;     ...
;   const int x0 = ((0 + h) ^ key) * 16, x1 = ((2 + h) ^ key) * 16;
;   const int a_rd = (wr * 64 + r) * 64, b_rd = 8192 + (wc * 128 + r) * 64;
;   f32x16 acc[2][4];
; #pragma unroll
;   for (int i = 0; i < 2; ++i)
; #pragma unroll
;     for (int j = 0; j < 4; ++j)
; #pragma unroll
;       for (int e = 0; e < 16; ++e) acc[i][j][e] = 0.f;
;   const int nk = K >> 5;
;   DMA_STEP_(0, 0);
;   DMA_STEP_(1, STG);
;   asm volatile("s_waitcnt vmcnt(6)" ::: "memory");
;   __builtin_amdgcn_s_barrier();
;   asm volatile("" ::: "memory");
;   int s0 = 0, s2 = 2 * STG;
;   for (int kt = 0; kt < nk; ++kt) {
;     const int kn = (kt + 2 < nk) ? (kt + 2) : (nk - 1);
;     const LAS char* cur = lds + s0;
;     bf16x8 af[2][2], bfr[2][4];
; #pragma unroll
;     for (int kk = 0; kk < 2; ++kk) {
;       const int xo = kk ? x1 : x0;
;       af[kk][0] = *(const LAS bf16x8*)(cur + a_rd + xo);
;       bfr[kk][0] = *(const LAS bf16x8*)(cur + b_rd + xo);
;       bfr[kk][1] = *(const LAS bf16x8*)(cur + b_rd + 2048 + xo);
;       af[kk][1] = *(const LAS bf16x8*)(cur + a_rd + 2048 + xo);
;       bfr[kk][2] = *(const LAS bf16x8*)(cur + b_rd + 4096 + xo);
;       bfr[kk][3] = *(const LAS bf16x8*)(cur + b_rd + 6144 + xo);
;     }
;     DMA_STEP_(kn, s2);
; #pragma unroll
;     for (int kk = 0; kk < 2; ++kk) {
;       acc[0][0] = mfma32(bfr[kk][0], af[kk][0], acc[0][0]); acc[0][1] = mfma32(bfr[kk][1], af[kk][0], acc[0][1]);
;       acc[1][0] = mfma32(bfr[kk][0], af[kk][1], acc[1][0]); acc[1][1] = mfma32(bfr[kk][1], af[kk][1], acc[1][1]);
.LBB0_234:
	v_mov_b32_e32 v189, v188
	s_lshl_b32 s12, s23, 7
	v_readfirstlane_b32 s42, v189
	s_ashr_i32 s44, s42, 6
	s_lshl_b32 s28, s44, 2
	s_ashr_i32 s29, s28, 31
	s_lshl_b32 s23, s44, 12
	s_lshl_b64 s[40:41], s[28:29], 10
	s_add_i32 s28, s23, 16
	s_ashr_i32 s23, s42, 1
	v_and_b32_e32 v0, 31, v189
	s_andn2_b32 s23, s23, 63
	v_lshlrev_b32_e32 v2, 4, v189
	s_lshl_b32 s10, s44, 1
	v_or_b32_e32 v197, s23, v0
	s_lshl_b32 s23, s44, 7
	v_bitop3_b32 v2, v2, 48, v189 bitop3:0x48
	v_lshlrev_b32_e32 v3, 9, v189
	s_ashr_i32 s13, s12, 31
	s_ashr_i32 s11, s10, 31
	s_and_b32 s23, s23, 0x80
	s_movk_i32 s42, 0x7800
	s_lshl_b64 s[10:11], s[10:11], 10
	s_add_i32 s29, s28, 0x2000
	v_or_b32_e32 v4, s23, v0
	v_and_or_b32 v0, v3, s42, v2
	v_lshlrev_b32_e32 v10, 4, v189
	v_and_b32_e32 v10, 0x3c0, v10
	v_or_b32_e32 v10, v10, v2
	v_mov_b32_e32 v11, 0
	s_lshl_b64 s[42:43], s[12:13], 6
	s_add_u32 s13, s18, s42
	s_addc_u32 s42, s19, s43
	s_add_u32 s10, s13, s10
	s_addc_u32 s11, s42, s11
	s_lshl_b64 s[42:43], s[14:15], 6
	s_add_u32 s13, s20, s42
	s_addc_u32 s42, s21, s43
	s_add_u32 s40, s13, s40
	s_addc_u32 s41, s42, s41
	s_lshl_b32 s13, s44, 11
	s_sub_i32 s13, s28, s13
	v_lshl_add_u64 v[192:193], s[10:11], 0, v[10:11]
	s_mov_b32 m0, s13
	s_nop 0
	global_load_lds_dwordx4 v[192:193], off
	global_load_lds_dwordx4 v[192:193], off offset:1024
	v_lshl_add_u64 v[194:195], s[40:41], 0, v[10:11]
	s_mov_b32 m0, s29
	s_nop 0
	global_load_lds_dwordx4 v[194:195], off
	global_load_lds_dwordx4 v[194:195], off offset:1024
	global_load_lds_dwordx4 v[194:195], off offset:2048
	global_load_lds_dwordx4 v[194:195], off offset:3072
	s_mov_b64 s[10:11], 0x10000
	s_mov_b64 s[10:11], 0x18000
	s_mov_b64 s[10:11], 0x8040
	s_add_i32 m0, s13, 0x6000
	s_mov_b32 vcc_lo, 0x480000
	s_mov_b32 vcc_hi, 0
	v_lshl_add_u64 v[2:3], v[192:193], 0, vcc
	global_load_lds_dwordx4 v[2:3], off
	global_load_lds_dwordx4 v[2:3], off offset:1024
	v_bfe_u32 v196, v189, 5, 1
	s_add_i32 m0, s28, 0x8000
	s_mov_b32 s100, 0x24000
	v_lshl_add_u64 v[2:3], v[194:195], 0, s[100:101]
	global_load_lds_dwordx4 v[2:3], off
	global_load_lds_dwordx4 v[2:3], off offset:1024
	global_load_lds_dwordx4 v[2:3], off offset:2048
	global_load_lds_dwordx4 v[2:3], off offset:3072
	s_mov_b64 s[10:11], 0x10040
	s_mov_b64 s[10:11], 0x18040
	v_lshlrev_b32_e32 v218, 6, v4
	v_bfe_u32 v4, v189, 2, 2
	v_lshrrev_b32_e32 v5, 5, v189
	s_lshl_b32 s100, s100, 1
	v_lshl_add_u64 v[194:195], v[194:195], 0, s[100:101]
	s_lshl_b32 vcc_lo, vcc_lo, 1
	v_lshl_add_u64 v[192:193], v[192:193], 0, vcc
	s_waitcnt vmcnt(6)
	s_barrier
	v_bitop3_b32 v2, v196, v4, 2 bitop3:0x36
	v_bitop3_b32 v0, v5, v4, 1 bitop3:0x6c
	v_lshlrev_b32_e32 v220, 4, v2
	v_mov_b32_e32 v2, 0
	v_lshlrev_b32_e32 v219, 6, v197
	v_lshlrev_b32_e32 v0, 4, v0
	s_mov_b32 s40, 0xc000
	s_mov_b32 s29, 0
	s_mov_b32 s41, 0
	v_readfirstlane_b32 vcc_lo, v192
	v_readfirstlane_b32 vcc_hi, v193
	v_readfirstlane_b32 s100, v194
	v_readfirstlane_b32 s101, v195
	s_sub_u32 vcc_lo, vcc_lo, 0x100000
	s_subb_u32 vcc_hi, vcc_hi, 0
	s_sub_u32 s100, s100, 0x100000
	s_subb_u32 s101, s101, 0
	v_subrev_u32_e32 v238, vcc_lo, v192
	v_subrev_u32_e32 v239, s100, v194
	v_add3_u32 v226, v219, v0, 16
	v_add3_u32 v227, v218, v0, 16
	v_add3_u32 v228, v219, v220, 16
	v_add3_u32 v229, v218, v220, 16
	ds_read_b128 v[154:157], v226 offset:0
	ds_read_b128 v[182:185], v227 offset:8192
	ds_read_b128 v[178:181], v227 offset:10240
	ds_read_b128 v[158:161], v226 offset:2048
	ds_read_b128 v[174:177], v227 offset:12288
	ds_read_b128 v[170:173], v227 offset:14336
	s_setprio 1
	ds_read_b128 v[138:141], v228 offset:0
	ds_read_b128 v[162:165], v229 offset:8192
	ds_read_b128 v[166:169], v229 offset:10240
	ds_read_b128 v[142:145], v228 offset:2048
	ds_read_b128 v[146:149], v229 offset:12288
	ds_read_b128 v[150:153], v229 offset:14336
	s_add_i32 m0, s13, 0xc000
	s_waitcnt lgkmcnt(6)
	v_mfma_f32_32x32x16_bf16 v[114:129], v[182:185], v[154:157], 0
	global_load_lds_dwordx4 v238, vcc
	v_mfma_f32_32x32x16_bf16 v[98:113], v[178:181], v[154:157], 0
	global_load_lds_dwordx4 v238, vcc offset:1024
	s_add_i32 m0, s28, 0xe000
	s_add_u32 vcc_lo, vcc_lo, 0x480000
	s_addc_u32 vcc_hi, vcc_hi, 0
	v_mfma_f32_32x32x16_bf16 v[66:81], v[182:185], v[158:161], 0
	global_load_lds_dwordx4 v239, s[100:101]
	v_mfma_f32_32x32x16_bf16 v[34:49], v[178:181], v[158:161], 0
	global_load_lds_dwordx4 v239, s[100:101] offset:1024
	v_mfma_f32_32x32x16_bf16 v[82:97], v[174:177], v[154:157], 0
	global_load_lds_dwordx4 v239, s[100:101] offset:2048
	v_mfma_f32_32x32x16_bf16 v[50:65], v[170:173], v[154:157], 0
	global_load_lds_dwordx4 v239, s[100:101] offset:3072
	s_add_u32 s100, s100, 0x24000
	s_addc_u32 s101, s101, 0
	v_mfma_f32_32x32x16_bf16 v[18:33], v[174:177], v[158:161], 0
	v_mfma_f32_32x32x16_bf16 v[2:17], v[170:173], v[158:161], 0
	s_waitcnt vmcnt(6) lgkmcnt(0)
	s_barrier
; #define LAS __attribute__((address_space(3)))
; DI f32x16 mfma32(bf16x8 a, bf16x8 b, f32x16 c) { return __builtin_amdgcn_mfma_f32_32x32x16_bf16(a, b, c, 0, 0, 0); }
;     ...
;   for (int kt = 0; kt < nk; ++kt) {
;     const int kn = (kt + 2 < nk) ? (kt + 2) : (nk - 1);
;     const LAS char* cur = lds + s0;
;     bf16x8 af[2][2], bfr[2][4];
; #pragma unroll
;     for (int kk = 0; kk < 2; ++kk) {
;       const int xo = kk ? x1 : x0;
;       af[kk][0] = *(const LAS bf16x8*)(cur + a_rd + xo);
;       bfr[kk][0] = *(const LAS bf16x8*)(cur + b_rd + xo);
;       bfr[kk][1] = *(const LAS bf16x8*)(cur + b_rd + 2048 + xo);
;       af[kk][1] = *(const LAS bf16x8*)(cur + a_rd + 2048 + xo);
;       bfr[kk][2] = *(const LAS bf16x8*)(cur + b_rd + 4096 + xo);
;       bfr[kk][3] = *(const LAS bf16x8*)(cur + b_rd + 6144 + xo);
;     }
;     DMA_STEP_(kn, s2);
; #pragma unroll
;     for (int kk = 0; kk < 2; ++kk) {
;       acc[0][0] = mfma32(bfr[kk][0], af[kk][0], acc[0][0]); acc[0][1] = mfma32(bfr[kk][1], af[kk][0], acc[0][1]);
;       acc[1][0] = mfma32(bfr[kk][0], af[kk][1], acc[1][0]); acc[1][1] = mfma32(bfr[kk][1], af[kk][1], acc[1][1]);
;       acc[0][2] = mfma32(bfr[kk][2], af[kk][0], acc[0][2]); acc[0][3] = mfma32(bfr[kk][3], af[kk][0], acc[0][3]);
;       acc[1][2] = mfma32(bfr[kk][2], af[kk][1], acc[1][2]); acc[1][3] = mfma32(bfr[kk][3], af[kk][1], acc[1][3]);
;     }
;     __builtin_amdgcn_sched_group_barrier(0x100, 12, 0);
;     __builtin_amdgcn_sched_group_barrier(0x010, 6, 0);
;     __builtin_amdgcn_sched_group_barrier(0x008, 16, 0);
;     asm volatile("s_waitcnt vmcnt(6) lgkmcnt(0)" ::: "memory");
;     __builtin_amdgcn_s_barrier();
;     asm volatile("" ::: "memory");
;     s0 = (s0 == 2 * STG) ? 0 : s0 + STG;
;     s2 = (s2 == 2 * STG) ? 0 : s2 + STG;
;   }
	ds_read_b128 v[154:157], v226 offset:24576
	ds_read_b128 v[182:185], v227 offset:32768
	ds_read_b128 v[178:181], v227 offset:34816
	ds_read_b128 v[158:161], v226 offset:26624
	ds_read_b128 v[174:177], v227 offset:36864
	ds_read_b128 v[170:173], v227 offset:38912
	v_mfma_f32_32x32x16_bf16 v[114:129], v[162:165], v[138:141], v[114:129]
	v_mfma_f32_32x32x16_bf16 v[98:113], v[166:169], v[138:141], v[98:113]
	v_mfma_f32_32x32x16_bf16 v[66:81], v[162:165], v[142:145], v[66:81]
	v_mfma_f32_32x32x16_bf16 v[34:49], v[166:169], v[142:145], v[34:49]
	v_mfma_f32_32x32x16_bf16 v[82:97], v[146:149], v[138:141], v[82:97]
	v_mfma_f32_32x32x16_bf16 v[50:65], v[150:153], v[138:141], v[50:65]
	v_mfma_f32_32x32x16_bf16 v[18:33], v[146:149], v[142:145], v[18:33]
	v_mfma_f32_32x32x16_bf16 v[2:17], v[150:153], v[142:145], v[2:17]
	ds_read_b128 v[138:141], v228 offset:24576
	ds_read_b128 v[162:165], v229 offset:32768
	ds_read_b128 v[166:169], v229 offset:34816
	ds_read_b128 v[142:145], v228 offset:26624
	ds_read_b128 v[146:149], v229 offset:36864
	ds_read_b128 v[150:153], v229 offset:38912
	s_add_i32 m0, s13, 0x0
	s_waitcnt lgkmcnt(6)
	v_mfma_f32_32x32x16_bf16 v[114:129], v[182:185], v[154:157], v[114:129]
	global_load_lds_dwordx4 v238, vcc
	v_mfma_f32_32x32x16_bf16 v[98:113], v[178:181], v[154:157], v[98:113]
	global_load_lds_dwordx4 v238, vcc offset:1024
	s_add_i32 m0, s28, 0x2000
	s_add_u32 vcc_lo, vcc_lo, 0x480000
	s_addc_u32 vcc_hi, vcc_hi, 0
	v_mfma_f32_32x32x16_bf16 v[66:81], v[182:185], v[158:161], v[66:81]
	global_load_lds_dwordx4 v239, s[100:101]
	v_mfma_f32_32x32x16_bf16 v[34:49], v[178:181], v[158:161], v[34:49]
	global_load_lds_dwordx4 v239, s[100:101] offset:1024
	v_mfma_f32_32x32x16_bf16 v[82:97], v[174:177], v[154:157], v[82:97]
	global_load_lds_dwordx4 v239, s[100:101] offset:2048
	v_mfma_f32_32x32x16_bf16 v[50:65], v[170:173], v[154:157], v[50:65]
	global_load_lds_dwordx4 v239, s[100:101] offset:3072
	s_add_u32 s100, s100, 0x24000
	s_addc_u32 s101, s101, 0
	v_mfma_f32_32x32x16_bf16 v[18:33], v[174:177], v[158:161], v[18:33]
	v_mfma_f32_32x32x16_bf16 v[2:17], v[170:173], v[158:161], v[2:17]
	s_waitcnt vmcnt(6) lgkmcnt(0)
	s_barrier
	ds_read_b128 v[154:157], v226 offset:49152
	ds_read_b128 v[182:185], v227 offset:57344
	ds_read_b128 v[178:181], v227 offset:59392
	ds_read_b128 v[158:161], v226 offset:51200
	ds_read_b128 v[174:177], v227 offset:61440
	ds_read_b128 v[170:173], v227 offset:63488
	v_mfma_f32_32x32x16_bf16 v[114:129], v[162:165], v[138:141], v[114:129]
	v_mfma_f32_32x32x16_bf16 v[98:113], v[166:169], v[138:141], v[98:113]
	v_mfma_f32_32x32x16_bf16 v[66:81], v[162:165], v[142:145], v[66:81]
	v_mfma_f32_32x32x16_bf16 v[34:49], v[166:169], v[142:145], v[34:49]
	v_mfma_f32_32x32x16_bf16 v[82:97], v[146:149], v[138:141], v[82:97]
	v_mfma_f32_32x32x16_bf16 v[50:65], v[150:153], v[138:141], v[50:65]
	v_mfma_f32_32x32x16_bf16 v[18:33], v[146:149], v[142:145], v[18:33]
	v_mfma_f32_32x32x16_bf16 v[2:17], v[150:153], v[142:145], v[2:17]
	ds_read_b128 v[138:141], v228 offset:49152
	ds_read_b128 v[162:165], v229 offset:57344
	ds_read_b128 v[166:169], v229 offset:59392
	ds_read_b128 v[142:145], v228 offset:51200
	ds_read_b128 v[146:149], v229 offset:61440
	ds_read_b128 v[150:153], v229 offset:63488
	s_add_i32 m0, s13, 0x6000
	s_waitcnt lgkmcnt(6)
	v_mfma_f32_32x32x16_bf16 v[114:129], v[182:185], v[154:157], v[114:129]
	global_load_lds_dwordx4 v238, vcc
	v_mfma_f32_32x32x16_bf16 v[98:113], v[178:181], v[154:157], v[98:113]
	global_load_lds_dwordx4 v238, vcc offset:1024
	s_add_i32 m0, s28, 0x8000
	s_add_u32 vcc_lo, vcc_lo, 0x480000
	s_addc_u32 vcc_hi, vcc_hi, 0
	v_mfma_f32_32x32x16_bf16 v[66:81], v[182:185], v[158:161], v[66:81]
	global_load_lds_dwordx4 v239, s[100:101]
	v_mfma_f32_32x32x16_bf16 v[34:49], v[178:181], v[158:161], v[34:49]
	global_load_lds_dwordx4 v239, s[100:101] offset:1024
	v_mfma_f32_32x32x16_bf16 v[82:97], v[174:177], v[154:157], v[82:97]
	global_load_lds_dwordx4 v239, s[100:101] offset:2048
	v_mfma_f32_32x32x16_bf16 v[50:65], v[170:173], v[154:157], v[50:65]
	global_load_lds_dwordx4 v239, s[100:101] offset:3072
	s_add_u32 s100, s100, 0x24000
	s_addc_u32 s101, s101, 0
	v_mfma_f32_32x32x16_bf16 v[18:33], v[174:177], v[158:161], v[18:33]
	v_mfma_f32_32x32x16_bf16 v[2:17], v[170:173], v[158:161], v[2:17]
	s_waitcnt vmcnt(6) lgkmcnt(0)
	s_barrier
	ds_read_b128 v[154:157], v226 offset:0
	ds_read_b128 v[182:185], v227 offset:8192
	ds_read_b128 v[178:181], v227 offset:10240
	ds_read_b128 v[158:161], v226 offset:2048
	ds_read_b128 v[174:177], v227 offset:12288
	ds_read_b128 v[170:173], v227 offset:14336
	v_mfma_f32_32x32x16_bf16 v[114:129], v[162:165], v[138:141], v[114:129]
	v_mfma_f32_32x32x16_bf16 v[98:113], v[166:169], v[138:141], v[98:113]
	v_mfma_f32_32x32x16_bf16 v[66:81], v[162:165], v[142:145], v[66:81]
	v_mfma_f32_32x32x16_bf16 v[34:49], v[166:169], v[142:145], v[34:49]
	v_mfma_f32_32x32x16_bf16 v[82:97], v[146:149], v[138:141], v[82:97]
	v_mfma_f32_32x32x16_bf16 v[50:65], v[150:153], v[138:141], v[50:65]
	v_mfma_f32_32x32x16_bf16 v[18:33], v[146:149], v[142:145], v[18:33]
	v_mfma_f32_32x32x16_bf16 v[2:17], v[150:153], v[142:145], v[2:17]
	ds_read_b128 v[138:141], v228 offset:0
	ds_read_b128 v[162:165], v229 offset:8192
	ds_read_b128 v[166:169], v229 offset:10240
	ds_read_b128 v[142:145], v228 offset:2048
	ds_read_b128 v[146:149], v229 offset:12288
	ds_read_b128 v[150:153], v229 offset:14336
	s_add_i32 m0, s13, 0xc000
	s_waitcnt lgkmcnt(6)
	v_mfma_f32_32x32x16_bf16 v[114:129], v[182:185], v[154:157], v[114:129]
	global_load_lds_dwordx4 v238, vcc
	v_mfma_f32_32x32x16_bf16 v[98:113], v[178:181], v[154:157], v[98:113]
	global_load_lds_dwordx4 v238, vcc offset:1024
	s_add_i32 m0, s28, 0xe000
	s_add_u32 vcc_lo, vcc_lo, 0x480000
	s_addc_u32 vcc_hi, vcc_hi, 0
	v_mfma_f32_32x32x16_bf16 v[66:81], v[182:185], v[158:161], v[66:81]
	global_load_lds_dwordx4 v239, s[100:101]
	v_mfma_f32_32x32x16_bf16 v[34:49], v[178:181], v[158:161], v[34:49]
	global_load_lds_dwordx4 v239, s[100:101] offset:1024
	v_mfma_f32_32x32x16_bf16 v[82:97], v[174:177], v[154:157], v[82:97]
	global_load_lds_dwordx4 v239, s[100:101] offset:2048
	v_mfma_f32_32x32x16_bf16 v[50:65], v[170:173], v[154:157], v[50:65]
	global_load_lds_dwordx4 v239, s[100:101] offset:3072
	s_add_u32 s100, s100, 0x24000
	s_addc_u32 s101, s101, 0
	v_mfma_f32_32x32x16_bf16 v[18:33], v[174:177], v[158:161], v[18:33]
	v_mfma_f32_32x32x16_bf16 v[2:17], v[170:173], v[158:161], v[2:17]
	s_waitcnt vmcnt(6) lgkmcnt(0)
	s_barrier
; #define LAS __attribute__((address_space(3)))
; DI f32x16 mfma32(bf16x8 a, bf16x8 b, f32x16 c) { return __builtin_amdgcn_mfma_f32_32x32x16_bf16(a, b, c, 0, 0, 0); }
;     ...
;   for (int kt = 0; kt < nk; ++kt) {
;     const int kn = (kt + 2 < nk) ? (kt + 2) : (nk - 1);
;     const LAS char* cur = lds + s0;
;     bf16x8 af[2][2], bfr[2][4];
; #pragma unroll
;     for (int kk = 0; kk < 2; ++kk) {
;       const int xo = kk ? x1 : x0;
;       af[kk][0] = *(const LAS bf16x8*)(cur + a_rd + xo);
;       bfr[kk][0] = *(const LAS bf16x8*)(cur + b_rd + xo);
;       bfr[kk][1] = *(const LAS bf16x8*)(cur + b_rd + 2048 + xo);
;       af[kk][1] = *(const LAS bf16x8*)(cur + a_rd + 2048 + xo);
;       bfr[kk][2] = *(const LAS bf16x8*)(cur + b_rd + 4096 + xo);
;       bfr[kk][3] = *(const LAS bf16x8*)(cur + b_rd + 6144 + xo);
;     }
;     DMA_STEP_(kn, s2);
; #pragma unroll
;     for (int kk = 0; kk < 2; ++kk) {
;       acc[0][0] = mfma32(bfr[kk][0], af[kk][0], acc[0][0]); acc[0][1] = mfma32(bfr[kk][1], af[kk][0], acc[0][1]);
;       acc[1][0] = mfma32(bfr[kk][0], af[kk][1], acc[1][0]); acc[1][1] = mfma32(bfr[kk][1], af[kk][1], acc[1][1]);
;       acc[0][2] = mfma32(bfr[kk][2], af[kk][0], acc[0][2]); acc[0][3] = mfma32(bfr[kk][3], af[kk][0], acc[0][3]);
;       acc[1][2] = mfma32(bfr[kk][2], af[kk][1], acc[1][2]); acc[1][3] = mfma32(bfr[kk][3], af[kk][1], acc[1][3]);
;     }
;     __builtin_amdgcn_sched_group_barrier(0x100, 12, 0);
;     __builtin_amdgcn_sched_group_barrier(0x010, 6, 0);
;     __builtin_amdgcn_sched_group_barrier(0x008, 16, 0);
;     asm volatile("s_waitcnt vmcnt(6) lgkmcnt(0)" ::: "memory");
;     __builtin_amdgcn_s_barrier();
;     asm volatile("" ::: "memory");
;     s0 = (s0 == 2 * STG) ? 0 : s0 + STG;
;     s2 = (s2 == 2 * STG) ? 0 : s2 + STG;
;   }
	ds_read_b128 v[154:157], v226 offset:24576
	ds_read_b128 v[182:185], v227 offset:32768
	ds_read_b128 v[178:181], v227 offset:34816
	ds_read_b128 v[158:161], v226 offset:26624
	ds_read_b128 v[174:177], v227 offset:36864
	ds_read_b128 v[170:173], v227 offset:38912
	v_mfma_f32_32x32x16_bf16 v[114:129], v[162:165], v[138:141], v[114:129]
	v_mfma_f32_32x32x16_bf16 v[98:113], v[166:169], v[138:141], v[98:113]
	v_mfma_f32_32x32x16_bf16 v[66:81], v[162:165], v[142:145], v[66:81]
	v_mfma_f32_32x32x16_bf16 v[34:49], v[166:169], v[142:145], v[34:49]
	v_mfma_f32_32x32x16_bf16 v[82:97], v[146:149], v[138:141], v[82:97]
	v_mfma_f32_32x32x16_bf16 v[50:65], v[150:153], v[138:141], v[50:65]
	v_mfma_f32_32x32x16_bf16 v[18:33], v[146:149], v[142:145], v[18:33]
	v_mfma_f32_32x32x16_bf16 v[2:17], v[150:153], v[142:145], v[2:17]
	ds_read_b128 v[138:141], v228 offset:24576
	ds_read_b128 v[162:165], v229 offset:32768
	ds_read_b128 v[166:169], v229 offset:34816
	ds_read_b128 v[142:145], v228 offset:26624
	ds_read_b128 v[146:149], v229 offset:36864
	ds_read_b128 v[150:153], v229 offset:38912
	s_add_i32 m0, s13, 0x0
	s_waitcnt lgkmcnt(6)
	v_mfma_f32_32x32x16_bf16 v[114:129], v[182:185], v[154:157], v[114:129]
	global_load_lds_dwordx4 v238, vcc
	v_mfma_f32_32x32x16_bf16 v[98:113], v[178:181], v[154:157], v[98:113]
	global_load_lds_dwordx4 v238, vcc offset:1024
	s_add_i32 m0, s28, 0x2000
	s_add_u32 vcc_lo, vcc_lo, 0x480000
	s_addc_u32 vcc_hi, vcc_hi, 0
	v_mfma_f32_32x32x16_bf16 v[66:81], v[182:185], v[158:161], v[66:81]
	global_load_lds_dwordx4 v239, s[100:101]
	v_mfma_f32_32x32x16_bf16 v[34:49], v[178:181], v[158:161], v[34:49]
	global_load_lds_dwordx4 v239, s[100:101] offset:1024
	v_mfma_f32_32x32x16_bf16 v[82:97], v[174:177], v[154:157], v[82:97]
	global_load_lds_dwordx4 v239, s[100:101] offset:2048
	v_mfma_f32_32x32x16_bf16 v[50:65], v[170:173], v[154:157], v[50:65]
	global_load_lds_dwordx4 v239, s[100:101] offset:3072
	s_add_u32 s100, s100, 0x24000
	s_addc_u32 s101, s101, 0
	v_mfma_f32_32x32x16_bf16 v[18:33], v[174:177], v[158:161], v[18:33]
	v_mfma_f32_32x32x16_bf16 v[2:17], v[170:173], v[158:161], v[2:17]
	s_waitcnt vmcnt(6) lgkmcnt(0)
	s_barrier
	ds_read_b128 v[154:157], v226 offset:49152
	ds_read_b128 v[182:185], v227 offset:57344
	ds_read_b128 v[178:181], v227 offset:59392
	ds_read_b128 v[158:161], v226 offset:51200
	ds_read_b128 v[174:177], v227 offset:61440
	ds_read_b128 v[170:173], v227 offset:63488
	v_mfma_f32_32x32x16_bf16 v[114:129], v[162:165], v[138:141], v[114:129]
	v_mfma_f32_32x32x16_bf16 v[98:113], v[166:169], v[138:141], v[98:113]
	v_mfma_f32_32x32x16_bf16 v[66:81], v[162:165], v[142:145], v[66:81]
	v_mfma_f32_32x32x16_bf16 v[34:49], v[166:169], v[142:145], v[34:49]
	v_mfma_f32_32x32x16_bf16 v[82:97], v[146:149], v[138:141], v[82:97]
	v_mfma_f32_32x32x16_bf16 v[50:65], v[150:153], v[138:141], v[50:65]
	v_mfma_f32_32x32x16_bf16 v[18:33], v[146:149], v[142:145], v[18:33]
	v_mfma_f32_32x32x16_bf16 v[2:17], v[150:153], v[142:145], v[2:17]
	ds_read_b128 v[138:141], v228 offset:49152
	ds_read_b128 v[162:165], v229 offset:57344
	ds_read_b128 v[166:169], v229 offset:59392
	ds_read_b128 v[142:145], v228 offset:51200
	ds_read_b128 v[146:149], v229 offset:61440
	ds_read_b128 v[150:153], v229 offset:63488
	s_add_i32 m0, s13, 0x6000
	s_waitcnt lgkmcnt(6)
	v_mfma_f32_32x32x16_bf16 v[114:129], v[182:185], v[154:157], v[114:129]
	global_load_lds_dwordx4 v238, vcc
	v_mfma_f32_32x32x16_bf16 v[98:113], v[178:181], v[154:157], v[98:113]
	global_load_lds_dwordx4 v238, vcc offset:1024
	s_add_i32 m0, s28, 0x8000
	s_add_u32 vcc_lo, vcc_lo, 0x480000
	s_addc_u32 vcc_hi, vcc_hi, 0
	v_mfma_f32_32x32x16_bf16 v[66:81], v[182:185], v[158:161], v[66:81]
	global_load_lds_dwordx4 v239, s[100:101]
	v_mfma_f32_32x32x16_bf16 v[34:49], v[178:181], v[158:161], v[34:49]
	global_load_lds_dwordx4 v239, s[100:101] offset:1024
	v_mfma_f32_32x32x16_bf16 v[82:97], v[174:177], v[154:157], v[82:97]
	global_load_lds_dwordx4 v239, s[100:101] offset:2048
	v_mfma_f32_32x32x16_bf16 v[50:65], v[170:173], v[154:157], v[50:65]
	global_load_lds_dwordx4 v239, s[100:101] offset:3072
	s_add_u32 s100, s100, 0x24000
	s_addc_u32 s101, s101, 0
	v_mfma_f32_32x32x16_bf16 v[18:33], v[174:177], v[158:161], v[18:33]
	v_mfma_f32_32x32x16_bf16 v[2:17], v[170:173], v[158:161], v[2:17]
	s_waitcnt vmcnt(6) lgkmcnt(0)
	s_barrier
	ds_read_b128 v[154:157], v226 offset:0
	ds_read_b128 v[182:185], v227 offset:8192
	ds_read_b128 v[178:181], v227 offset:10240
	ds_read_b128 v[158:161], v226 offset:2048
	ds_read_b128 v[174:177], v227 offset:12288
	ds_read_b128 v[170:173], v227 offset:14336
	v_mfma_f32_32x32x16_bf16 v[114:129], v[162:165], v[138:141], v[114:129]
	v_mfma_f32_32x32x16_bf16 v[98:113], v[166:169], v[138:141], v[98:113]
	v_mfma_f32_32x32x16_bf16 v[66:81], v[162:165], v[142:145], v[66:81]
	v_mfma_f32_32x32x16_bf16 v[34:49], v[166:169], v[142:145], v[34:49]
	v_mfma_f32_32x32x16_bf16 v[82:97], v[146:149], v[138:141], v[82:97]
	v_mfma_f32_32x32x16_bf16 v[50:65], v[150:153], v[138:141], v[50:65]
	v_mfma_f32_32x32x16_bf16 v[18:33], v[146:149], v[142:145], v[18:33]
	v_mfma_f32_32x32x16_bf16 v[2:17], v[150:153], v[142:145], v[2:17]
	s_add_i32 s29, s29, 6

;   int tid = tid_in; asm volatile("" : "+v"(tid));
;   const int lane = tid & 63, wid = __builtin_amdgcn_readfirstlane(tid >> 6), wr = wid >> 1, wc = wid & 1;
;   const int m0 = mt * 128, n0 = nt * 256;
;   const int r = lane & 31, h = lane >> 5, key = (r >> 2) & 3;
;   constexpr int STG = 24576;
;   const int rowl = lane >> 2, cch = (lane & 3) ^ ((lane >> 4) & 3);
;   const unsigned voffA = (unsigned)(rowl * lda * 2 + cch * 16), voffB = (unsigned)(rowl * K * 2 + cch * 16);
;   const char* Abase = (const char*)(A + (size_t)m0 * lda) + (size_t)(wid * 2) * 32 * lda;
;   const char* Bbase = (const char*)(Bt + (size_t)n0 * K) + (size_t)(wid * 4) * 32 * K;
;   const size_t ablk = (size_t)32 * lda, bblk = (size_t)32 * K;
;   LAS char* lds = (LAS char*)smem;
;   LAS char* ldsA = lds + (wid * 2) * 1024;
;   LAS char* ldsB = lds + 8192 + (wid * 4) * 1024;
;     ...
;   const int x0 = ((0 + h) ^ key) * 16, x1 = ((2 + h) ^ key) * 16;
;   const int a_rd = (wr * 64 + r) * 64, b_rd = 8192 + (wc * 128 + r) * 64;
;   f32x16 acc[2][4];
; #pragma unroll
;   for (int i = 0; i < 2; ++i)
; #pragma unroll
;     for (int j = 0; j < 4; ++j)
; #pragma unroll
;       for (int e = 0; e < 16; ++e) acc[i][j][e] = 0.f;
;   const int nk = K >> 5;
;   DMA_STEP_(0, 0);
;   DMA_STEP_(1, STG);
;   asm volatile("s_waitcnt vmcnt(6)" ::: "memory");
;   __builtin_amdgcn_s_barrier();
;   asm volatile("" ::: "memory");
;   int s0 = 0, s2 = 2 * STG;
;   for (int kt = 0; kt < nk; ++kt) {
;     const int kn = (kt + 2 < nk) ? (kt + 2) : (nk - 1);
;     const LAS char* cur = lds + s0;
;     bf16x8 af[2][2], bfr[2][4];
; #pragma unroll
;     for (int kk = 0; kk < 2; ++kk) {
;       const int xo = kk ? x1 : x0;
;       af[kk][0] = *(const LAS bf16x8*)(cur + a_rd + xo);
;       bfr[kk][0] = *(const LAS bf16x8*)(cur + b_rd + xo);
;       bfr[kk][1] = *(const LAS bf16x8*)(cur + b_rd + 2048 + xo);
;       af[kk][1] = *(const LAS bf16x8*)(cur + a_rd + 2048 + xo);
;       bfr[kk][2] = *(const LAS bf16x8*)(cur + b_rd + 4096 + xo);
;       bfr[kk][3] = *(const LAS bf16x8*)(cur + b_rd + 6144 + xo);
;     }
;     DMA_STEP_(kn, s2);
; #pragma unroll
;     for (int kk = 0; kk < 2; ++kk) {
;       acc[0][0] = mfma32(bfr[kk][0], af[kk][0], acc[0][0]); acc[0][1] = mfma32(bfr[kk][1], af[kk][0], acc[0][1]);
;       acc[1][0] = mfma32(bfr[kk][0], af[kk][1], acc[1][0]); acc[1][1] = mfma32(bfr[kk][1], af[kk][1], acc[1][1]);
.LBB0_271:
	s_mul_hi_i32 s10, s14, 0x2e8ba2e9
	s_lshr_b32 s11, s10, 31
	s_ashr_i32 s10, s10, 4
	s_add_i32 s10, s10, s11
	v_readlane_b32 s15, v252, 18
	s_mul_i32 s11, s10, 0xffffffa8
	s_lshl_b32 s10, s10, s15
	v_readlane_b32 s15, v252, 41
	s_add_i32 s10, s10, s15
	s_lshr_b32 s15, s10, 31
	s_add_i32 s15, s10, s15
	s_and_b32 s18, s15, -2
	s_add_i32 s11, s11, s14
	s_sub_i32 s10, s10, s18
	s_mul_i32 s22, s10, 11
	s_ashr_i32 s10, s11, 3
	v_mov_b32_e32 v189, v188
	s_lshl_b32 s15, s15, 2
	s_add_i32 s22, s22, s10
	s_and_b32 s15, s15, -8
	v_readfirstlane_b32 s10, v189
	s_and_b32 s18, s14, 7
	s_ashr_i32 s11, s10, 6
	s_or_b32 s15, s15, s18
	s_lshl_b32 s18, s11, 1
	s_ashr_i32 s19, s18, 31
	s_lshl_b64 s[28:29], s[18:19], 10
	s_lshl_b32 s18, s11, 2
	s_ashr_i32 s19, s18, 31
	s_ashr_i32 s10, s10, 1
	s_lshl_b32 s46, s15, 7
	s_lshl_b32 s66, s22, 8
	v_and_b32_e32 v0, 31, v189
	s_lshl_b64 s[74:75], s[18:19], 10
	s_lshl_b32 s18, s11, 12
	s_andn2_b32 s10, s10, 63
	v_lshlrev_b32_e32 v3, 4, v189
	s_ashr_i32 s47, s46, 31
	s_ashr_i32 s67, s66, 31
	s_add_i32 s19, s18, 16
	v_or_b32_e32 v197, s10, v0
	s_lshl_b32 s10, s11, 7
	v_lshlrev_b32_e32 v2, 9, v189
	v_bitop3_b32 v3, v3, 48, v189 bitop3:0x48
	s_lshl_b64 s[20:21], s[46:47], 6
	s_lshl_b64 s[40:41], s[66:67], 6
	s_add_i32 s23, s19, 0x2000
	s_and_b32 s18, s10, 0x80
	s_movk_i32 s10, 0x7800
	v_or_b32_e32 v4, s18, v0
	v_and_or_b32 v0, v2, s10, v3
	v_lshlrev_b32_e32 v10, 4, v189
	v_and_b32_e32 v10, 0x3c0, v10
	v_or_b32_e32 v10, v10, v3
	v_mov_b32_e32 v11, 0
	s_add_u32 s10, s42, s20
	s_addc_u32 s20, s43, s21
	s_add_u32 s28, s10, s28
	s_addc_u32 s29, s20, s29
	s_add_u32 s10, s87, s40
	s_addc_u32 s21, s76, s41
	s_lshl_b32 s11, s11, 11
	s_sub_i32 s20, s19, s11
	s_mov_b32 m0, s20
	v_lshl_add_u64 v[192:193], s[28:29], 0, v[10:11]
	global_load_lds_dwordx4 v[192:193], off
	global_load_lds_dwordx4 v[192:193], off offset:1024
	s_add_u32 s28, s10, s74
	s_addc_u32 s29, s21, s75
	v_lshl_add_u64 v[194:195], s[28:29], 0, v[10:11]
	s_mov_b32 m0, s23
	s_nop 0
	global_load_lds_dwordx4 v[194:195], off
	global_load_lds_dwordx4 v[194:195], off offset:1024
	global_load_lds_dwordx4 v[194:195], off offset:2048
	global_load_lds_dwordx4 v[194:195], off offset:3072
	s_mov_b64 s[10:11], 0x10000
	s_mov_b64 s[10:11], 0x18000
	s_mov_b64 s[10:11], 0x8040
	s_add_i32 m0, s20, 0x6000
	s_mov_b32 vcc_lo, 0x480000
	s_mov_b32 vcc_hi, 0
	v_lshl_add_u64 v[2:3], v[192:193], 0, vcc
	global_load_lds_dwordx4 v[2:3], off
	global_load_lds_dwordx4 v[2:3], off offset:1024
	v_lshrrev_b32_e32 v5, 5, v189
	s_add_i32 m0, s19, 0x8000
	s_mov_b32 s100, 0x58000
	v_lshl_add_u64 v[2:3], v[194:195], 0, s[100:101]
	global_load_lds_dwordx4 v[2:3], off
	global_load_lds_dwordx4 v[2:3], off offset:1024
	global_load_lds_dwordx4 v[2:3], off offset:2048
	global_load_lds_dwordx4 v[2:3], off offset:3072
	s_mov_b64 s[10:11], 0x10040
	s_mov_b64 s[10:11], 0x18040
	v_bfe_u32 v6, v189, 2, 2
	v_bfe_u32 v196, v189, 5, 1
	s_lshl_b32 s100, s100, 1
	v_lshl_add_u64 v[194:195], v[194:195], 0, s[100:101]
	s_lshl_b32 vcc_lo, vcc_lo, 1
	v_lshl_add_u64 v[192:193], v[192:193], 0, vcc
	s_waitcnt vmcnt(6)
	s_barrier
	v_bitop3_b32 v2, v5, v6, 1 bitop3:0x6c
	v_lshlrev_b32_e32 v219, 4, v2
	v_bitop3_b32 v2, v196, v6, 2 bitop3:0x36
	v_mov_b32_e32 v66, 0
	v_lshlrev_b32_e32 v218, 6, v197
	v_lshlrev_b32_e32 v0, 6, v4
	v_lshlrev_b32_e32 v220, 4, v2
	s_mov_b32 s23, 0xc000
	s_mov_b32 s28, 0
	s_mov_b32 s21, 0
	v_readfirstlane_b32 vcc_lo, v192
	v_readfirstlane_b32 vcc_hi, v193
	v_readfirstlane_b32 s100, v194
	v_readfirstlane_b32 s101, v195
	s_sub_u32 vcc_lo, vcc_lo, 0x100000
	s_subb_u32 vcc_hi, vcc_hi, 0
	s_sub_u32 s100, s100, 0x100000
	s_subb_u32 s101, s101, 0
	v_subrev_u32_e32 v238, vcc_lo, v192
	v_subrev_u32_e32 v239, s100, v194
	v_add3_u32 v226, v218, v219, 16
	v_add3_u32 v227, v0, v219, 16
	v_add3_u32 v228, v218, v220, 16
	v_add3_u32 v229, v0, v220, 16
	ds_read_b128 v[154:157], v226 offset:0
	ds_read_b128 v[182:185], v227 offset:8192
	ds_read_b128 v[178:181], v227 offset:10240
	ds_read_b128 v[158:161], v226 offset:2048
	ds_read_b128 v[174:177], v227 offset:12288
	ds_read_b128 v[170:173], v227 offset:14336
	s_setprio 1
	ds_read_b128 v[138:141], v228 offset:0
	ds_read_b128 v[162:165], v229 offset:8192
	ds_read_b128 v[166:169], v229 offset:10240
	ds_read_b128 v[142:145], v228 offset:2048
	ds_read_b128 v[146:149], v229 offset:12288
	ds_read_b128 v[150:153], v229 offset:14336
	s_add_i32 m0, s20, 0xc000
	s_waitcnt lgkmcnt(6)
	v_mfma_f32_32x32x16_bf16 v[66:81], v[182:185], v[154:157], 0
	global_load_lds_dwordx4 v238, vcc
	v_mfma_f32_32x32x16_bf16 v[82:97], v[178:181], v[154:157], 0
	global_load_lds_dwordx4 v238, vcc offset:1024
	s_add_i32 m0, s19, 0xe000
	s_add_u32 vcc_lo, vcc_lo, 0x480000
	s_addc_u32 vcc_hi, vcc_hi, 0
	v_mfma_f32_32x32x16_bf16 v[18:33], v[182:185], v[158:161], 0
	global_load_lds_dwordx4 v239, s[100:101]
	v_mfma_f32_32x32x16_bf16 v[2:17], v[178:181], v[158:161], 0
	global_load_lds_dwordx4 v239, s[100:101] offset:1024
	v_mfma_f32_32x32x16_bf16 v[114:129], v[174:177], v[154:157], 0
	global_load_lds_dwordx4 v239, s[100:101] offset:2048
	v_mfma_f32_32x32x16_bf16 v[98:113], v[170:173], v[154:157], 0
	global_load_lds_dwordx4 v239, s[100:101] offset:3072
	s_add_u32 s100, s100, 0x58000
	s_addc_u32 s101, s101, 0
	v_mfma_f32_32x32x16_bf16 v[50:65], v[174:177], v[158:161], 0
	v_mfma_f32_32x32x16_bf16 v[34:49], v[170:173], v[158:161], 0
	s_waitcnt vmcnt(6) lgkmcnt(0)
	s_barrier
; #define LAS __attribute__((address_space(3)))
; DI f32x16 mfma32(bf16x8 a, bf16x8 b, f32x16 c) { return __builtin_amdgcn_mfma_f32_32x32x16_bf16(a, b, c, 0, 0, 0); }
;     ...
;   for (int kt = 0; kt < nk; ++kt) {
;     const int kn = (kt + 2 < nk) ? (kt + 2) : (nk - 1);
;     const LAS char* cur = lds + s0;
;     bf16x8 af[2][2], bfr[2][4];
; #pragma unroll
;     for (int kk = 0; kk < 2; ++kk) {
;       const int xo = kk ? x1 : x0;
;       af[kk][0] = *(const LAS bf16x8*)(cur + a_rd + xo);
;       bfr[kk][0] = *(const LAS bf16x8*)(cur + b_rd + xo);
;       bfr[kk][1] = *(const LAS bf16x8*)(cur + b_rd + 2048 + xo);
;       af[kk][1] = *(const LAS bf16x8*)(cur + a_rd + 2048 + xo);
;       bfr[kk][2] = *(const LAS bf16x8*)(cur + b_rd + 4096 + xo);
;       bfr[kk][3] = *(const LAS bf16x8*)(cur + b_rd + 6144 + xo);
;     }
;     DMA_STEP_(kn, s2);
; #pragma unroll
;     for (int kk = 0; kk < 2; ++kk) {
;       acc[0][0] = mfma32(bfr[kk][0], af[kk][0], acc[0][0]); acc[0][1] = mfma32(bfr[kk][1], af[kk][0], acc[0][1]);
;       acc[1][0] = mfma32(bfr[kk][0], af[kk][1], acc[1][0]); acc[1][1] = mfma32(bfr[kk][1], af[kk][1], acc[1][1]);
;       acc[0][2] = mfma32(bfr[kk][2], af[kk][0], acc[0][2]); acc[0][3] = mfma32(bfr[kk][3], af[kk][0], acc[0][3]);
;       acc[1][2] = mfma32(bfr[kk][2], af[kk][1], acc[1][2]); acc[1][3] = mfma32(bfr[kk][3], af[kk][1], acc[1][3]);
;     }
;     __builtin_amdgcn_sched_group_barrier(0x100, 12, 0);
;     __builtin_amdgcn_sched_group_barrier(0x010, 6, 0);
;     __builtin_amdgcn_sched_group_barrier(0x008, 16, 0);
;     asm volatile("s_waitcnt vmcnt(6) lgkmcnt(0)" ::: "memory");
;     __builtin_amdgcn_s_barrier();
;     asm volatile("" ::: "memory");
;     s0 = (s0 == 2 * STG) ? 0 : s0 + STG;
;     s2 = (s2 == 2 * STG) ? 0 : s2 + STG;
;   }
	ds_read_b128 v[154:157], v226 offset:24576
	ds_read_b128 v[182:185], v227 offset:32768
	ds_read_b128 v[178:181], v227 offset:34816
	ds_read_b128 v[158:161], v226 offset:26624
	ds_read_b128 v[174:177], v227 offset:36864
	ds_read_b128 v[170:173], v227 offset:38912
	v_mfma_f32_32x32x16_bf16 v[66:81], v[162:165], v[138:141], v[66:81]
	v_mfma_f32_32x32x16_bf16 v[82:97], v[166:169], v[138:141], v[82:97]
	v_mfma_f32_32x32x16_bf16 v[18:33], v[162:165], v[142:145], v[18:33]
	v_mfma_f32_32x32x16_bf16 v[2:17], v[166:169], v[142:145], v[2:17]
	v_mfma_f32_32x32x16_bf16 v[114:129], v[146:149], v[138:141], v[114:129]
	v_mfma_f32_32x32x16_bf16 v[98:113], v[150:153], v[138:141], v[98:113]
	v_mfma_f32_32x32x16_bf16 v[50:65], v[146:149], v[142:145], v[50:65]
	v_mfma_f32_32x32x16_bf16 v[34:49], v[150:153], v[142:145], v[34:49]
	ds_read_b128 v[138:141], v228 offset:24576
	ds_read_b128 v[162:165], v229 offset:32768
	ds_read_b128 v[166:169], v229 offset:34816
	ds_read_b128 v[142:145], v228 offset:26624
	ds_read_b128 v[146:149], v229 offset:36864
	ds_read_b128 v[150:153], v229 offset:38912
	s_add_i32 m0, s20, 0x0
	s_waitcnt lgkmcnt(6)
	v_mfma_f32_32x32x16_bf16 v[66:81], v[182:185], v[154:157], v[66:81]
	global_load_lds_dwordx4 v238, vcc
	v_mfma_f32_32x32x16_bf16 v[82:97], v[178:181], v[154:157], v[82:97]
	global_load_lds_dwordx4 v238, vcc offset:1024
	s_add_i32 m0, s19, 0x2000
	s_add_u32 vcc_lo, vcc_lo, 0x480000
	s_addc_u32 vcc_hi, vcc_hi, 0
	v_mfma_f32_32x32x16_bf16 v[18:33], v[182:185], v[158:161], v[18:33]
	global_load_lds_dwordx4 v239, s[100:101]
	v_mfma_f32_32x32x16_bf16 v[2:17], v[178:181], v[158:161], v[2:17]
	global_load_lds_dwordx4 v239, s[100:101] offset:1024
	v_mfma_f32_32x32x16_bf16 v[114:129], v[174:177], v[154:157], v[114:129]
	global_load_lds_dwordx4 v239, s[100:101] offset:2048
	v_mfma_f32_32x32x16_bf16 v[98:113], v[170:173], v[154:157], v[98:113]
	global_load_lds_dwordx4 v239, s[100:101] offset:3072
	s_add_u32 s100, s100, 0x58000
	s_addc_u32 s101, s101, 0
	v_mfma_f32_32x32x16_bf16 v[50:65], v[174:177], v[158:161], v[50:65]
	v_mfma_f32_32x32x16_bf16 v[34:49], v[170:173], v[158:161], v[34:49]
	s_waitcnt vmcnt(6) lgkmcnt(0)
	s_barrier
	ds_read_b128 v[154:157], v226 offset:49152
	ds_read_b128 v[182:185], v227 offset:57344
	ds_read_b128 v[178:181], v227 offset:59392
	ds_read_b128 v[158:161], v226 offset:51200
	ds_read_b128 v[174:177], v227 offset:61440
	ds_read_b128 v[170:173], v227 offset:63488
	v_mfma_f32_32x32x16_bf16 v[66:81], v[162:165], v[138:141], v[66:81]
	v_mfma_f32_32x32x16_bf16 v[82:97], v[166:169], v[138:141], v[82:97]
	v_mfma_f32_32x32x16_bf16 v[18:33], v[162:165], v[142:145], v[18:33]
	v_mfma_f32_32x32x16_bf16 v[2:17], v[166:169], v[142:145], v[2:17]
	v_mfma_f32_32x32x16_bf16 v[114:129], v[146:149], v[138:141], v[114:129]
	v_mfma_f32_32x32x16_bf16 v[98:113], v[150:153], v[138:141], v[98:113]
	v_mfma_f32_32x32x16_bf16 v[50:65], v[146:149], v[142:145], v[50:65]
	v_mfma_f32_32x32x16_bf16 v[34:49], v[150:153], v[142:145], v[34:49]
	ds_read_b128 v[138:141], v228 offset:49152
	ds_read_b128 v[162:165], v229 offset:57344
	ds_read_b128 v[166:169], v229 offset:59392
	ds_read_b128 v[142:145], v228 offset:51200
	ds_read_b128 v[146:149], v229 offset:61440
	ds_read_b128 v[150:153], v229 offset:63488
	s_add_i32 m0, s20, 0x6000
	s_waitcnt lgkmcnt(6)
	v_mfma_f32_32x32x16_bf16 v[66:81], v[182:185], v[154:157], v[66:81]
	global_load_lds_dwordx4 v238, vcc
	v_mfma_f32_32x32x16_bf16 v[82:97], v[178:181], v[154:157], v[82:97]
	global_load_lds_dwordx4 v238, vcc offset:1024
	s_add_i32 m0, s19, 0x8000
	s_add_u32 vcc_lo, vcc_lo, 0x480000
	s_addc_u32 vcc_hi, vcc_hi, 0
	v_mfma_f32_32x32x16_bf16 v[18:33], v[182:185], v[158:161], v[18:33]
	global_load_lds_dwordx4 v239, s[100:101]
	v_mfma_f32_32x32x16_bf16 v[2:17], v[178:181], v[158:161], v[2:17]
	global_load_lds_dwordx4 v239, s[100:101] offset:1024
	v_mfma_f32_32x32x16_bf16 v[114:129], v[174:177], v[154:157], v[114:129]
	global_load_lds_dwordx4 v239, s[100:101] offset:2048
	v_mfma_f32_32x32x16_bf16 v[98:113], v[170:173], v[154:157], v[98:113]
	global_load_lds_dwordx4 v239, s[100:101] offset:3072
	s_add_u32 s100, s100, 0x58000
	s_addc_u32 s101, s101, 0
	v_mfma_f32_32x32x16_bf16 v[50:65], v[174:177], v[158:161], v[50:65]
	v_mfma_f32_32x32x16_bf16 v[34:49], v[170:173], v[158:161], v[34:49]
	s_waitcnt vmcnt(6) lgkmcnt(0)
	s_barrier
	ds_read_b128 v[154:157], v226 offset:0
	ds_read_b128 v[182:185], v227 offset:8192
	ds_read_b128 v[178:181], v227 offset:10240
	ds_read_b128 v[158:161], v226 offset:2048
	ds_read_b128 v[174:177], v227 offset:12288
	ds_read_b128 v[170:173], v227 offset:14336
	v_mfma_f32_32x32x16_bf16 v[66:81], v[162:165], v[138:141], v[66:81]
	v_mfma_f32_32x32x16_bf16 v[82:97], v[166:169], v[138:141], v[82:97]
	v_mfma_f32_32x32x16_bf16 v[18:33], v[162:165], v[142:145], v[18:33]
	v_mfma_f32_32x32x16_bf16 v[2:17], v[166:169], v[142:145], v[2:17]
	v_mfma_f32_32x32x16_bf16 v[114:129], v[146:149], v[138:141], v[114:129]
	v_mfma_f32_32x32x16_bf16 v[98:113], v[150:153], v[138:141], v[98:113]
	v_mfma_f32_32x32x16_bf16 v[50:65], v[146:149], v[142:145], v[50:65]
	v_mfma_f32_32x32x16_bf16 v[34:49], v[150:153], v[142:145], v[34:49]
	ds_read_b128 v[138:141], v228 offset:0
	ds_read_b128 v[162:165], v229 offset:8192
	ds_read_b128 v[166:169], v229 offset:10240
	ds_read_b128 v[142:145], v228 offset:2048
	ds_read_b128 v[146:149], v229 offset:12288
	ds_read_b128 v[150:153], v229 offset:14336
	s_add_i32 m0, s20, 0xc000
	s_waitcnt lgkmcnt(6)
	v_mfma_f32_32x32x16_bf16 v[66:81], v[182:185], v[154:157], v[66:81]
	global_load_lds_dwordx4 v238, vcc
	v_mfma_f32_32x32x16_bf16 v[82:97], v[178:181], v[154:157], v[82:97]
	global_load_lds_dwordx4 v238, vcc offset:1024
	s_add_i32 m0, s19, 0xe000
	s_add_u32 vcc_lo, vcc_lo, 0x480000
	s_addc_u32 vcc_hi, vcc_hi, 0
	v_mfma_f32_32x32x16_bf16 v[18:33], v[182:185], v[158:161], v[18:33]
	global_load_lds_dwordx4 v239, s[100:101]
	v_mfma_f32_32x32x16_bf16 v[2:17], v[178:181], v[158:161], v[2:17]
	global_load_lds_dwordx4 v239, s[100:101] offset:1024
	v_mfma_f32_32x32x16_bf16 v[114:129], v[174:177], v[154:157], v[114:129]
	global_load_lds_dwordx4 v239, s[100:101] offset:2048
	v_mfma_f32_32x32x16_bf16 v[98:113], v[170:173], v[154:157], v[98:113]
	global_load_lds_dwordx4 v239, s[100:101] offset:3072
	s_add_u32 s100, s100, 0x58000
	s_addc_u32 s101, s101, 0
	v_mfma_f32_32x32x16_bf16 v[50:65], v[174:177], v[158:161], v[50:65]
	v_mfma_f32_32x32x16_bf16 v[34:49], v[170:173], v[158:161], v[34:49]
	s_waitcnt vmcnt(6) lgkmcnt(0)
	s_barrier
; #define LAS __attribute__((address_space(3)))
; DI f32x16 mfma32(bf16x8 a, bf16x8 b, f32x16 c) { return __builtin_amdgcn_mfma_f32_32x32x16_bf16(a, b, c, 0, 0, 0); }
;     ...
;   for (int kt = 0; kt < nk; ++kt) {
;     const int kn = (kt + 2 < nk) ? (kt + 2) : (nk - 1);
;     const LAS char* cur = lds + s0;
;     bf16x8 af[2][2], bfr[2][4];
; #pragma unroll
;     for (int kk = 0; kk < 2; ++kk) {
;       const int xo = kk ? x1 : x0;
;       af[kk][0] = *(const LAS bf16x8*)(cur + a_rd + xo);
;       bfr[kk][0] = *(const LAS bf16x8*)(cur + b_rd + xo);
;       bfr[kk][1] = *(const LAS bf16x8*)(cur + b_rd + 2048 + xo);
;       af[kk][1] = *(const LAS bf16x8*)(cur + a_rd + 2048 + xo);
;       bfr[kk][2] = *(const LAS bf16x8*)(cur + b_rd + 4096 + xo);
;       bfr[kk][3] = *(const LAS bf16x8*)(cur + b_rd + 6144 + xo);
;     }
;     DMA_STEP_(kn, s2);
; #pragma unroll
;     for (int kk = 0; kk < 2; ++kk) {
;       acc[0][0] = mfma32(bfr[kk][0], af[kk][0], acc[0][0]); acc[0][1] = mfma32(bfr[kk][1], af[kk][0], acc[0][1]);
;       acc[1][0] = mfma32(bfr[kk][0], af[kk][1], acc[1][0]); acc[1][1] = mfma32(bfr[kk][1], af[kk][1], acc[1][1]);
;       acc[0][2] = mfma32(bfr[kk][2], af[kk][0], acc[0][2]); acc[0][3] = mfma32(bfr[kk][3], af[kk][0], acc[0][3]);
;       acc[1][2] = mfma32(bfr[kk][2], af[kk][1], acc[1][2]); acc[1][3] = mfma32(bfr[kk][3], af[kk][1], acc[1][3]);
;     }
;     __builtin_amdgcn_sched_group_barrier(0x100, 12, 0);
;     __builtin_amdgcn_sched_group_barrier(0x010, 6, 0);
;     __builtin_amdgcn_sched_group_barrier(0x008, 16, 0);
;     asm volatile("s_waitcnt vmcnt(6) lgkmcnt(0)" ::: "memory");
;     __builtin_amdgcn_s_barrier();
;     asm volatile("" ::: "memory");
;     s0 = (s0 == 2 * STG) ? 0 : s0 + STG;
;     s2 = (s2 == 2 * STG) ? 0 : s2 + STG;
;   }
	ds_read_b128 v[154:157], v226 offset:24576
	ds_read_b128 v[182:185], v227 offset:32768
	ds_read_b128 v[178:181], v227 offset:34816
	ds_read_b128 v[158:161], v226 offset:26624
	ds_read_b128 v[174:177], v227 offset:36864
	ds_read_b128 v[170:173], v227 offset:38912
	v_mfma_f32_32x32x16_bf16 v[66:81], v[162:165], v[138:141], v[66:81]
	v_mfma_f32_32x32x16_bf16 v[82:97], v[166:169], v[138:141], v[82:97]
	v_mfma_f32_32x32x16_bf16 v[18:33], v[162:165], v[142:145], v[18:33]
	v_mfma_f32_32x32x16_bf16 v[2:17], v[166:169], v[142:145], v[2:17]
	v_mfma_f32_32x32x16_bf16 v[114:129], v[146:149], v[138:141], v[114:129]
	v_mfma_f32_32x32x16_bf16 v[98:113], v[150:153], v[138:141], v[98:113]
	v_mfma_f32_32x32x16_bf16 v[50:65], v[146:149], v[142:145], v[50:65]
	v_mfma_f32_32x32x16_bf16 v[34:49], v[150:153], v[142:145], v[34:49]
	ds_read_b128 v[138:141], v228 offset:24576
	ds_read_b128 v[162:165], v229 offset:32768
	ds_read_b128 v[166:169], v229 offset:34816
	ds_read_b128 v[142:145], v228 offset:26624
	ds_read_b128 v[146:149], v229 offset:36864
	ds_read_b128 v[150:153], v229 offset:38912
	s_add_i32 m0, s20, 0x0
	s_waitcnt lgkmcnt(6)
	v_mfma_f32_32x32x16_bf16 v[66:81], v[182:185], v[154:157], v[66:81]
	global_load_lds_dwordx4 v238, vcc
	v_mfma_f32_32x32x16_bf16 v[82:97], v[178:181], v[154:157], v[82:97]
	global_load_lds_dwordx4 v238, vcc offset:1024
	s_add_i32 m0, s19, 0x2000
	s_add_u32 vcc_lo, vcc_lo, 0x480000
	s_addc_u32 vcc_hi, vcc_hi, 0
	v_mfma_f32_32x32x16_bf16 v[18:33], v[182:185], v[158:161], v[18:33]
	global_load_lds_dwordx4 v239, s[100:101]
	v_mfma_f32_32x32x16_bf16 v[2:17], v[178:181], v[158:161], v[2:17]
	global_load_lds_dwordx4 v239, s[100:101] offset:1024
	v_mfma_f32_32x32x16_bf16 v[114:129], v[174:177], v[154:157], v[114:129]
	global_load_lds_dwordx4 v239, s[100:101] offset:2048
	v_mfma_f32_32x32x16_bf16 v[98:113], v[170:173], v[154:157], v[98:113]
	global_load_lds_dwordx4 v239, s[100:101] offset:3072
	s_add_u32 s100, s100, 0x58000
	s_addc_u32 s101, s101, 0
	v_mfma_f32_32x32x16_bf16 v[50:65], v[174:177], v[158:161], v[50:65]
	v_mfma_f32_32x32x16_bf16 v[34:49], v[170:173], v[158:161], v[34:49]
	s_waitcnt vmcnt(6) lgkmcnt(0)
	s_barrier
	ds_read_b128 v[154:157], v226 offset:49152
	ds_read_b128 v[182:185], v227 offset:57344
	ds_read_b128 v[178:181], v227 offset:59392
	ds_read_b128 v[158:161], v226 offset:51200
	ds_read_b128 v[174:177], v227 offset:61440
	ds_read_b128 v[170:173], v227 offset:63488
	v_mfma_f32_32x32x16_bf16 v[66:81], v[162:165], v[138:141], v[66:81]
	v_mfma_f32_32x32x16_bf16 v[82:97], v[166:169], v[138:141], v[82:97]
	v_mfma_f32_32x32x16_bf16 v[18:33], v[162:165], v[142:145], v[18:33]
	v_mfma_f32_32x32x16_bf16 v[2:17], v[166:169], v[142:145], v[2:17]
	v_mfma_f32_32x32x16_bf16 v[114:129], v[146:149], v[138:141], v[114:129]
	v_mfma_f32_32x32x16_bf16 v[98:113], v[150:153], v[138:141], v[98:113]
	v_mfma_f32_32x32x16_bf16 v[50:65], v[146:149], v[142:145], v[50:65]
	v_mfma_f32_32x32x16_bf16 v[34:49], v[150:153], v[142:145], v[34:49]
	ds_read_b128 v[138:141], v228 offset:49152
	ds_read_b128 v[162:165], v229 offset:57344
	ds_read_b128 v[166:169], v229 offset:59392
	ds_read_b128 v[142:145], v228 offset:51200
	ds_read_b128 v[146:149], v229 offset:61440
	ds_read_b128 v[150:153], v229 offset:63488
	s_add_i32 m0, s20, 0x6000
	s_waitcnt lgkmcnt(6)
	v_mfma_f32_32x32x16_bf16 v[66:81], v[182:185], v[154:157], v[66:81]
	global_load_lds_dwordx4 v238, vcc
	v_mfma_f32_32x32x16_bf16 v[82:97], v[178:181], v[154:157], v[82:97]
	global_load_lds_dwordx4 v238, vcc offset:1024
	s_add_i32 m0, s19, 0x8000
	s_add_u32 vcc_lo, vcc_lo, 0x480000
	s_addc_u32 vcc_hi, vcc_hi, 0
	v_mfma_f32_32x32x16_bf16 v[18:33], v[182:185], v[158:161], v[18:33]
	global_load_lds_dwordx4 v239, s[100:101]
	v_mfma_f32_32x32x16_bf16 v[2:17], v[178:181], v[158:161], v[2:17]
	global_load_lds_dwordx4 v239, s[100:101] offset:1024
	v_mfma_f32_32x32x16_bf16 v[114:129], v[174:177], v[154:157], v[114:129]
	global_load_lds_dwordx4 v239, s[100:101] offset:2048
	v_mfma_f32_32x32x16_bf16 v[98:113], v[170:173], v[154:157], v[98:113]
	global_load_lds_dwordx4 v239, s[100:101] offset:3072
	s_add_u32 s100, s100, 0x58000
	s_addc_u32 s101, s101, 0
	v_mfma_f32_32x32x16_bf16 v[50:65], v[174:177], v[158:161], v[50:65]
	v_mfma_f32_32x32x16_bf16 v[34:49], v[170:173], v[158:161], v[34:49]
	s_waitcnt vmcnt(6) lgkmcnt(0)
	s_barrier
	ds_read_b128 v[154:157], v226 offset:0
	ds_read_b128 v[182:185], v227 offset:8192
	ds_read_b128 v[178:181], v227 offset:10240
	ds_read_b128 v[158:161], v226 offset:2048
	ds_read_b128 v[174:177], v227 offset:12288
	ds_read_b128 v[170:173], v227 offset:14336
	v_mfma_f32_32x32x16_bf16 v[66:81], v[162:165], v[138:141], v[66:81]
	v_mfma_f32_32x32x16_bf16 v[82:97], v[166:169], v[138:141], v[82:97]
	v_mfma_f32_32x32x16_bf16 v[18:33], v[162:165], v[142:145], v[18:33]
	v_mfma_f32_32x32x16_bf16 v[2:17], v[166:169], v[142:145], v[2:17]
	v_mfma_f32_32x32x16_bf16 v[114:129], v[146:149], v[138:141], v[114:129]
	v_mfma_f32_32x32x16_bf16 v[98:113], v[150:153], v[138:141], v[98:113]
	v_mfma_f32_32x32x16_bf16 v[50:65], v[146:149], v[142:145], v[50:65]
	v_mfma_f32_32x32x16_bf16 v[34:49], v[150:153], v[142:145], v[34:49]
	s_add_i32 s21, s21, 6
